# peeled first K-iteration with SrcC=0 in 7 GEMM instances; accumulator zeroing fully removed
# speedup vs baseline: 1.0156x; 1.0089x over previous
; #define PG8_STAGE(bufoff, gbase, voff) do { _Pragma("unroll") for (int _i = 0; _i < 2; ++_i) \
;         __builtin_amdgcn_global_load_lds((const unsigned*)((const char*)(gbase) + (voff)[_i]), (PG8_LAS unsigned*)(lds + (bufoff) + ldsw + _i * 8192), 16, 0, 0); } while (0)
; #define PG8_LDA(dst, b, h) do { _Pragma("unroll") for (int m = 0; m < 4; ++m) _Pragma("unroll") for (int k = 0; k < 2; ++k) dst[m][k] = *(const PG8_LAS bf16x8*)(lds + PG8_SA(b, h) + aoff + m * 2048 + k * 1024); } while (0)
; #define PG8_LDB(dst, b, h) do { _Pragma("unroll") for (int n = 0; n < 2; ++n) _Pragma("unroll") for (int k = 0; k < 2; ++k) dst[n][k] = *(const PG8_LAS bf16x8*)(lds + PG8_SB(b, h) + boff + n * 2048 + k * 1024); } while (0)
; #define PG8_MMA(ai, bj, At, Bt) do { __builtin_amdgcn_s_setprio(1); _Pragma("unroll") for (int m = 0; m < 4; ++m) _Pragma("unroll") for (int n = 0; n < 2; ++n) _Pragma("unroll") for (int k = 0; k < 2; ++k) \
;         acc[ai][bj][m][n] = __builtin_amdgcn_mfma_f32_16x16x32_bf16(Bt[n][k], At[m][k], acc[ai][bj][m][n], 0, 0, 0); __builtin_amdgcn_s_setprio(0); } while (0)
; #define PG8_WAIT_V(n) asm volatile("s_waitcnt vmcnt(" #n ")" ::: "memory")
; #define PG8_WAIT_L(n) asm volatile("s_waitcnt lgkmcnt(" #n ")" ::: "memory")
; #define PG8_BAR __builtin_amdgcn_s_barrier()
; #define PG8_SCHED __builtin_amdgcn_sched_barrier(0)
; template <class Epi, class Sched, bool ALIGN_EPI = false, bool SP2 = false>
; __device__ __forceinline__ void gemm_phase(PG8_LAS unsigned char* lds, const Gemm g, const Sched& S, const Epi& E) {
;     ...
;             const bool last = (t == nt - 2);
;             const char* a1 = cA + (size_t)(t + 1) * kstep;
;             const char* a2 = last ? nA : cA + (size_t)(t + 2) * kstep; const char* b2 = last ? nB : cB + (size_t)(t + 2) * kstep;
;             const char* a3 = a2 + kstep; const char* b3 = b2 + kstep;
;             if (last && has_next) S.a_ready(nxt);
;             if constexpr (SP2) {
;             PG8_LDB(B0, 0, 0); PG8_LDB(B1, 0, 1); PG8_SCHED; PG8_LDA(At, 0, 0); PG8_STAGE(PG8_SA(1, 1), a1 + hstep, voffA);
;             PG8_WAIT_V(8); PG8_WAIT_L(0); PG8_BAR; PG8_MMA(0, 0, At, B0); PG8_MMA(0, 1, At, B1); PG8_BAR; PG8_SCHED;
;             PG8_LDA(At, 0, 1); PG8_STAGE(PG8_SB(0, 0), b2, voffB); PG8_STAGE(PG8_SB(0, 1), b2 + hstep, voffB); PG8_STAGE(PG8_SA(0, 0), a2, voffA);
.LBB0_354:
	s_andn2_b64 vcc, exec, s[22:23]
	s_waitcnt lgkmcnt(0)
	s_cbranch_vccnz .LBB0_357
	s_add_u32 s4, s4, 0x80
	s_addc_u32 s5, s5, 0
	s_add_u32 s11, s6, 0x100
	s_addc_u32 s16, s7, 0
	s_mov_b32 s6, 0
	ds_read_b128 v[146:149], v171
	ds_read_b128 v[150:153], v171 offset:1024
	ds_read_b128 v[154:157], v171 offset:2048
	ds_read_b128 v[158:161], v171 offset:3072
	ds_read_b128 v[162:165], v172
	ds_read_b128 v[166:169], v172 offset:1024
	ds_read_b128 v[176:179], v172 offset:2048
	ds_read_b128 v[180:183], v172 offset:3072
	s_add_i32 s46, s6, 2
	s_add_u32 s47, s4, 0x80
	s_addc_u32 s7, s5, 0
	s_cmp_eq_u32 s68, s6
	s_cselect_b32 s6, s0, s47
	s_cselect_b32 s7, s1, s7
	s_cselect_b32 s49, s45, s16
	s_cselect_b32 s48, s44, s11
	v_lshl_add_u64 v[218:219], s[4:5], 0, v[138:139]
	s_add_i32 m0, s59, 0xc000
	ds_read_b128 v[184:187], v173
	ds_read_b128 v[188:191], v173 offset:1024
	ds_read_b128 v[192:195], v173 offset:2048
	ds_read_b128 v[196:199], v173 offset:3072
	ds_read_b128 v[202:205], v173 offset:4096
	ds_read_b128 v[206:209], v173 offset:5120
	ds_read_b128 v[210:213], v173 offset:6144
	ds_read_b128 v[214:217], v173 offset:7168
	global_load_lds_dwordx4 v[218:219], off
	v_lshl_add_u64 v[218:219], s[4:5], 0, v[140:141]
	s_add_i32 m0, s59, 0xe000
	s_nop 0
	global_load_lds_dwordx4 v[218:219], off
	s_waitcnt vmcnt(8)
	s_waitcnt lgkmcnt(0)
	s_barrier
	s_setprio 1
	s_waitcnt lgkmcnt(0)
	v_mfma_f32_16x16x32_bf16 v[120:123], v[146:149], v[184:187], 0
	v_mfma_f32_16x16x32_bf16 v[116:119], v[154:157], v[184:187], 0
	v_mfma_f32_16x16x32_bf16 v[108:111], v[146:149], v[192:195], 0
	v_mfma_f32_16x16x32_bf16 v[100:103], v[154:157], v[192:195], 0
	v_mfma_f32_16x16x32_bf16 v[92:95], v[146:149], v[202:205], 0
	v_mfma_f32_16x16x32_bf16 v[84:87], v[154:157], v[202:205], 0
	v_mfma_f32_16x16x32_bf16 v[76:79], v[146:149], v[210:213], 0
	v_mfma_f32_16x16x32_bf16 v[68:71], v[154:157], v[210:213], 0
	v_mfma_f32_16x16x32_bf16 v[120:123], v[150:153], v[188:191], v[120:123]
	v_mfma_f32_16x16x32_bf16 v[116:119], v[158:161], v[188:191], v[116:119]
	v_mfma_f32_16x16x32_bf16 v[108:111], v[150:153], v[196:199], v[108:111]
	v_mfma_f32_16x16x32_bf16 v[100:103], v[158:161], v[196:199], v[100:103]
	v_mfma_f32_16x16x32_bf16 v[92:95], v[150:153], v[206:209], v[92:95]
	v_mfma_f32_16x16x32_bf16 v[84:87], v[158:161], v[206:209], v[84:87]
	v_mfma_f32_16x16x32_bf16 v[76:79], v[150:153], v[214:217], v[76:79]
	v_mfma_f32_16x16x32_bf16 v[68:71], v[158:161], v[214:217], v[68:71]
	s_setprio 0
	s_setprio 1
	v_mfma_f32_16x16x32_bf16 v[124:127], v[162:165], v[184:187], 0
	v_mfma_f32_16x16x32_bf16 v[112:115], v[176:179], v[184:187], 0
	v_mfma_f32_16x16x32_bf16 v[104:107], v[162:165], v[192:195], 0
	v_mfma_f32_16x16x32_bf16 v[96:99], v[176:179], v[192:195], 0
	v_mfma_f32_16x16x32_bf16 v[88:91], v[162:165], v[202:205], 0
	v_mfma_f32_16x16x32_bf16 v[80:83], v[176:179], v[202:205], 0
	v_mfma_f32_16x16x32_bf16 v[72:75], v[162:165], v[210:213], 0
	v_mfma_f32_16x16x32_bf16 v[64:67], v[176:179], v[210:213], 0
	v_mfma_f32_16x16x32_bf16 v[124:127], v[166:169], v[188:191], v[124:127]
	v_mfma_f32_16x16x32_bf16 v[112:115], v[180:183], v[188:191], v[112:115]
	v_mfma_f32_16x16x32_bf16 v[104:107], v[166:169], v[196:199], v[104:107]
	v_mfma_f32_16x16x32_bf16 v[96:99], v[180:183], v[196:199], v[96:99]
	v_mfma_f32_16x16x32_bf16 v[88:91], v[166:169], v[206:209], v[88:91]
	v_mfma_f32_16x16x32_bf16 v[80:83], v[180:183], v[206:209], v[80:83]
	v_mfma_f32_16x16x32_bf16 v[72:75], v[166:169], v[214:217], v[72:75]
	v_mfma_f32_16x16x32_bf16 v[64:67], v[180:183], v[214:217], v[64:67]
	s_setprio 0
	s_barrier
	s_add_i32 s47, s75, s58
	v_lshl_add_u64 v[218:219], s[48:49], 0, v[130:131]
	s_mov_b32 m0, s47
	ds_read_b128 v[184:187], v173 offset:16384
	ds_read_b128 v[188:191], v173 offset:17408
	ds_read_b128 v[192:195], v173 offset:18432
	ds_read_b128 v[196:199], v173 offset:19456
	ds_read_b128 v[202:205], v173 offset:20480
	ds_read_b128 v[206:209], v173 offset:21504
	ds_read_b128 v[210:213], v173 offset:22528
	ds_read_b128 v[214:217], v173 offset:23552
	global_load_lds_dwordx4 v[218:219], off
	s_add_i32 m0, s47, 0x2000
	v_lshl_add_u64 v[220:221], s[48:49], 0, v[134:135]
	s_add_u32 s48, s48, s12
	s_addc_u32 s49, s49, s13
	s_add_i32 s47, s76, s58
	global_load_lds_dwordx4 v[220:221], off
	v_lshl_add_u64 v[222:223], s[48:49], 0, v[130:131]
	s_mov_b32 m0, s47
	v_lshl_add_u64 v[224:225], s[48:49], 0, v[134:135]
	global_load_lds_dwordx4 v[222:223], off
	s_add_i32 m0, s47, 0x2000
	v_lshl_add_u64 v[226:227], s[6:7], 0, v[128:129]
	global_load_lds_dwordx4 v[224:225], off
	s_mov_b32 m0, s59
	v_lshl_add_u64 v[228:229], s[6:7], 0, v[132:133]
	global_load_lds_dwordx4 v[226:227], off
	s_mov_b32 m0, s60
	s_nop 0
	global_load_lds_dwordx4 v[228:229], off
	s_waitcnt vmcnt(8)
	s_waitcnt lgkmcnt(0)
	s_barrier
; #define PG8_STAGE(bufoff, gbase, voff) do { _Pragma("unroll") for (int _i = 0; _i < 2; ++_i) \
;         __builtin_amdgcn_global_load_lds((const unsigned*)((const char*)(gbase) + (voff)[_i]), (PG8_LAS unsigned*)(lds + (bufoff) + ldsw + _i * 8192), 16, 0, 0); } while (0)
; #define PG8_LDA(dst, b, h) do { _Pragma("unroll") for (int m = 0; m < 4; ++m) _Pragma("unroll") for (int k = 0; k < 2; ++k) dst[m][k] = *(const PG8_LAS bf16x8*)(lds + PG8_SA(b, h) + aoff + m * 2048 + k * 1024); } while (0)
; #define PG8_LDB(dst, b, h) do { _Pragma("unroll") for (int n = 0; n < 2; ++n) _Pragma("unroll") for (int k = 0; k < 2; ++k) dst[n][k] = *(const PG8_LAS bf16x8*)(lds + PG8_SB(b, h) + boff + n * 2048 + k * 1024); } while (0)
; #define PG8_MMA(ai, bj, At, Bt) do { __builtin_amdgcn_s_setprio(1); _Pragma("unroll") for (int m = 0; m < 4; ++m) _Pragma("unroll") for (int n = 0; n < 2; ++n) _Pragma("unroll") for (int k = 0; k < 2; ++k) \
;         acc[ai][bj][m][n] = __builtin_amdgcn_mfma_f32_16x16x32_bf16(Bt[n][k], At[m][k], acc[ai][bj][m][n], 0, 0, 0); __builtin_amdgcn_s_setprio(0); } while (0)
; #define PG8_WAIT_V(n) asm volatile("s_waitcnt vmcnt(" #n ")" ::: "memory")
; #define PG8_WAIT_L(n) asm volatile("s_waitcnt lgkmcnt(" #n ")" ::: "memory")
; #define PG8_BAR __builtin_amdgcn_s_barrier()
; #define PG8_SCHED __builtin_amdgcn_sched_barrier(0)
; template <class Epi, class Sched, bool ALIGN_EPI = false, bool SP2 = false>
; __device__ __forceinline__ void gemm_phase(PG8_LAS unsigned char* lds, const Gemm g, const Sched& S, const Epi& E) {
;     ...
;             PG8_WAIT_V(8); PG8_WAIT_L(0); PG8_BAR; PG8_MMA(1, 0, At, B0); PG8_MMA(1, 1, At, B1); PG8_BAR; PG8_SCHED;
;             PG8_LDB(B0, 1, 0); PG8_LDB(B1, 1, 1); PG8_SCHED; PG8_LDA(At, 1, 0); PG8_STAGE(PG8_SA(0, 1), a2 + hstep, voffA);
;             PG8_WAIT_V(8); PG8_WAIT_L(0); PG8_BAR; PG8_MMA(0, 0, At, B0); PG8_MMA(0, 1, At, B1); PG8_BAR; PG8_SCHED;
	s_setprio 1
	s_waitcnt lgkmcnt(0)
	v_mfma_f32_16x16x32_bf16 v[60:63], v[146:149], v[184:187], 0
	v_mfma_f32_16x16x32_bf16 v[52:55], v[154:157], v[184:187], 0
	v_mfma_f32_16x16x32_bf16 v[44:47], v[146:149], v[192:195], 0
	v_mfma_f32_16x16x32_bf16 v[36:39], v[154:157], v[192:195], 0
	v_mfma_f32_16x16x32_bf16 v[28:31], v[146:149], v[202:205], 0
	v_mfma_f32_16x16x32_bf16 v[20:23], v[154:157], v[202:205], 0
	v_mfma_f32_16x16x32_bf16 v[12:15], v[146:149], v[210:213], 0
	v_mfma_f32_16x16x32_bf16 v[4:7], v[154:157], v[210:213], 0
	v_mfma_f32_16x16x32_bf16 v[60:63], v[150:153], v[188:191], v[60:63]
	v_mfma_f32_16x16x32_bf16 v[52:55], v[158:161], v[188:191], v[52:55]
	v_mfma_f32_16x16x32_bf16 v[44:47], v[150:153], v[196:199], v[44:47]
	v_mfma_f32_16x16x32_bf16 v[36:39], v[158:161], v[196:199], v[36:39]
	v_mfma_f32_16x16x32_bf16 v[28:31], v[150:153], v[206:209], v[28:31]
	v_mfma_f32_16x16x32_bf16 v[20:23], v[158:161], v[206:209], v[20:23]
	v_mfma_f32_16x16x32_bf16 v[12:15], v[150:153], v[214:217], v[12:15]
	v_mfma_f32_16x16x32_bf16 v[4:7], v[158:161], v[214:217], v[4:7]
	s_setprio 0
	s_setprio 1
	v_mfma_f32_16x16x32_bf16 v[56:59], v[162:165], v[184:187], 0
	v_mfma_f32_16x16x32_bf16 v[48:51], v[176:179], v[184:187], 0
	v_mfma_f32_16x16x32_bf16 v[40:43], v[162:165], v[192:195], 0
	v_mfma_f32_16x16x32_bf16 v[32:35], v[176:179], v[192:195], 0
	v_mfma_f32_16x16x32_bf16 v[24:27], v[162:165], v[202:205], 0
	v_mfma_f32_16x16x32_bf16 v[16:19], v[176:179], v[202:205], 0
	v_mfma_f32_16x16x32_bf16 v[8:11], v[162:165], v[210:213], 0
	v_mfma_f32_16x16x32_bf16 v[0:3], v[176:179], v[210:213], 0
	v_mfma_f32_16x16x32_bf16 v[56:59], v[166:169], v[188:191], v[56:59]
	v_mfma_f32_16x16x32_bf16 v[48:51], v[180:183], v[188:191], v[48:51]
	v_mfma_f32_16x16x32_bf16 v[40:43], v[166:169], v[196:199], v[40:43]
	v_mfma_f32_16x16x32_bf16 v[32:35], v[180:183], v[196:199], v[32:35]
	v_mfma_f32_16x16x32_bf16 v[24:27], v[166:169], v[206:209], v[24:27]
	v_mfma_f32_16x16x32_bf16 v[16:19], v[180:183], v[206:209], v[16:19]
	v_mfma_f32_16x16x32_bf16 v[8:11], v[166:169], v[214:217], v[8:11]
	v_mfma_f32_16x16x32_bf16 v[0:3], v[180:183], v[214:217], v[0:3]
	s_setprio 0
	s_barrier
	s_add_i32 s47, 0, 0x18000
	v_add_u32_e32 v136, s47, v170
	s_add_i32 s48, 0, 0x1c000
	ds_read_b128 v[146:149], v136
	ds_read_b128 v[150:153], v136 offset:1024
	ds_read_b128 v[154:157], v136 offset:2048
	ds_read_b128 v[158:161], v136 offset:3072
	v_add_u32_e32 v136, s48, v170
	ds_read_b128 v[162:165], v136
	ds_read_b128 v[166:169], v136 offset:1024
	ds_read_b128 v[176:179], v136 offset:2048
	ds_read_b128 v[180:183], v136 offset:3072
	s_add_u32 s6, s6, s12
	s_addc_u32 s7, s7, s13
	s_mov_b32 m0, s61
	v_lshl_add_u64 v[230:231], s[6:7], 0, v[128:129]
	ds_read_b128 v[184:187], v173 offset:32768
	ds_read_b128 v[188:191], v173 offset:33792
	ds_read_b128 v[192:195], v173 offset:34816
	ds_read_b128 v[196:199], v173 offset:35840
	ds_read_b128 v[202:205], v173 offset:36864
	ds_read_b128 v[206:209], v173 offset:37888
	ds_read_b128 v[210:213], v173 offset:38912
	ds_read_b128 v[214:217], v173 offset:39936
	global_load_lds_dwordx4 v[230:231], off
	v_lshl_add_u64 v[230:231], s[6:7], 0, v[132:133]
	s_mov_b32 m0, s62
	s_nop 0
	global_load_lds_dwordx4 v[230:231], off
	s_waitcnt vmcnt(8)
	s_waitcnt lgkmcnt(0)
	s_barrier
	s_setprio 1
	s_waitcnt lgkmcnt(0)
	v_mfma_f32_16x16x32_bf16 v[120:123], v[146:149], v[184:187], v[120:123]
	v_mfma_f32_16x16x32_bf16 v[116:119], v[154:157], v[184:187], v[116:119]
	v_mfma_f32_16x16x32_bf16 v[108:111], v[146:149], v[192:195], v[108:111]
	v_mfma_f32_16x16x32_bf16 v[100:103], v[154:157], v[192:195], v[100:103]
	v_mfma_f32_16x16x32_bf16 v[92:95], v[146:149], v[202:205], v[92:95]
	v_mfma_f32_16x16x32_bf16 v[84:87], v[154:157], v[202:205], v[84:87]
	v_mfma_f32_16x16x32_bf16 v[76:79], v[146:149], v[210:213], v[76:79]
	v_mfma_f32_16x16x32_bf16 v[68:71], v[154:157], v[210:213], v[68:71]
	v_mfma_f32_16x16x32_bf16 v[120:123], v[150:153], v[188:191], v[120:123]
	v_mfma_f32_16x16x32_bf16 v[116:119], v[158:161], v[188:191], v[116:119]
	v_mfma_f32_16x16x32_bf16 v[108:111], v[150:153], v[196:199], v[108:111]
	v_mfma_f32_16x16x32_bf16 v[100:103], v[158:161], v[196:199], v[100:103]
	v_mfma_f32_16x16x32_bf16 v[92:95], v[150:153], v[206:209], v[92:95]
	v_mfma_f32_16x16x32_bf16 v[84:87], v[158:161], v[206:209], v[84:87]
	v_mfma_f32_16x16x32_bf16 v[76:79], v[150:153], v[214:217], v[76:79]
	v_mfma_f32_16x16x32_bf16 v[68:71], v[158:161], v[214:217], v[68:71]
	s_setprio 0
	s_setprio 1
	v_mfma_f32_16x16x32_bf16 v[124:127], v[162:165], v[184:187], v[124:127]
	v_mfma_f32_16x16x32_bf16 v[112:115], v[176:179], v[184:187], v[112:115]
	v_mfma_f32_16x16x32_bf16 v[104:107], v[162:165], v[192:195], v[104:107]
	v_mfma_f32_16x16x32_bf16 v[96:99], v[176:179], v[192:195], v[96:99]
	v_mfma_f32_16x16x32_bf16 v[88:91], v[162:165], v[202:205], v[88:91]
	v_mfma_f32_16x16x32_bf16 v[80:83], v[176:179], v[202:205], v[80:83]
	v_mfma_f32_16x16x32_bf16 v[72:75], v[162:165], v[210:213], v[72:75]
	v_mfma_f32_16x16x32_bf16 v[64:67], v[176:179], v[210:213], v[64:67]
	v_mfma_f32_16x16x32_bf16 v[124:127], v[166:169], v[188:191], v[124:127]
	v_mfma_f32_16x16x32_bf16 v[112:115], v[180:183], v[188:191], v[112:115]
	v_mfma_f32_16x16x32_bf16 v[104:107], v[166:169], v[196:199], v[104:107]
	v_mfma_f32_16x16x32_bf16 v[96:99], v[180:183], v[196:199], v[96:99]
	v_mfma_f32_16x16x32_bf16 v[88:91], v[166:169], v[206:209], v[88:91]
	v_mfma_f32_16x16x32_bf16 v[80:83], v[180:183], v[206:209], v[80:83]
	v_mfma_f32_16x16x32_bf16 v[72:75], v[166:169], v[214:217], v[72:75]
	v_mfma_f32_16x16x32_bf16 v[64:67], v[180:183], v[214:217], v[64:67]
	s_setprio 0
	s_barrier
; #define PG8_STAGE(bufoff, gbase, voff) do { _Pragma("unroll") for (int _i = 0; _i < 2; ++_i) \
;         __builtin_amdgcn_global_load_lds((const unsigned*)((const char*)(gbase) + (voff)[_i]), (PG8_LAS unsigned*)(lds + (bufoff) + ldsw + _i * 8192), 16, 0, 0); } while (0)
; #define PG8_LDA(dst, b, h) do { _Pragma("unroll") for (int m = 0; m < 4; ++m) _Pragma("unroll") for (int k = 0; k < 2; ++k) dst[m][k] = *(const PG8_LAS bf16x8*)(lds + PG8_SA(b, h) + aoff + m * 2048 + k * 1024); } while (0)
; #define PG8_MMA(ai, bj, At, Bt) do { __builtin_amdgcn_s_setprio(1); _Pragma("unroll") for (int m = 0; m < 4; ++m) _Pragma("unroll") for (int n = 0; n < 2; ++n) _Pragma("unroll") for (int k = 0; k < 2; ++k) \
;         acc[ai][bj][m][n] = __builtin_amdgcn_mfma_f32_16x16x32_bf16(Bt[n][k], At[m][k], acc[ai][bj][m][n], 0, 0, 0); __builtin_amdgcn_s_setprio(0); } while (0)
; #define PG8_WAIT_V(n) asm volatile("s_waitcnt vmcnt(" #n ")" ::: "memory")
; #define PG8_WAIT_L(n) asm volatile("s_waitcnt lgkmcnt(" #n ")" ::: "memory")
; #define PG8_BAR __builtin_amdgcn_s_barrier()
; #define PG8_SCHED __builtin_amdgcn_sched_barrier(0)
; template <class Epi, class Sched, bool ALIGN_EPI = false, bool SP2 = false>
; __device__ __forceinline__ void gemm_phase(PG8_LAS unsigned char* lds, const Gemm g, const Sched& S, const Epi& E) {
;     ...
;         for (int t = 0; t < nt; t += 2) {
;     ...
;             PG8_LDA(At, 1, 1); PG8_STAGE(PG8_SB(1, 0), b3, voffB); PG8_STAGE(PG8_SB(1, 1), b3 + hstep, voffB); PG8_STAGE(PG8_SA(1, 0), a3, voffA);
;             PG8_WAIT_V(8); PG8_WAIT_L(0); PG8_BAR; PG8_MMA(1, 0, At, B0); PG8_MMA(1, 1, At, B1); PG8_BAR; PG8_SCHED;
	s_add_i32 s6, s47, s58
	v_lshl_add_u64 v[218:219], v[218:219], 0, s[20:21]
	s_mov_b32 m0, s6
	ds_read_b128 v[184:187], v173 offset:49152
	ds_read_b128 v[188:191], v173 offset:50176
	ds_read_b128 v[192:195], v173 offset:51200
	ds_read_b128 v[196:199], v173 offset:52224
	ds_read_b128 v[202:205], v173 offset:53248
	ds_read_b128 v[206:209], v173 offset:54272
	ds_read_b128 v[210:213], v173 offset:55296
	ds_read_b128 v[214:217], v173 offset:56320
	global_load_lds_dwordx4 v[218:219], off
	v_lshl_add_u64 v[218:219], v[220:221], 0, s[20:21]
	s_add_i32 m0, s6, 0x2000
	s_add_i32 s6, s48, s58
	global_load_lds_dwordx4 v[218:219], off
	v_lshl_add_u64 v[218:219], v[222:223], 0, s[20:21]
	s_mov_b32 m0, s6
	s_nop 0
	global_load_lds_dwordx4 v[218:219], off
	v_lshl_add_u64 v[218:219], v[224:225], 0, s[20:21]
	s_add_i32 m0, s6, 0x2000
	s_nop 0
	global_load_lds_dwordx4 v[218:219], off
	v_lshl_add_u64 v[218:219], v[226:227], 0, s[20:21]
	s_mov_b32 m0, s63
	s_nop 0
	global_load_lds_dwordx4 v[218:219], off
	v_lshl_add_u64 v[218:219], v[228:229], 0, s[20:21]
	s_mov_b32 m0, s64
	s_nop 0
	global_load_lds_dwordx4 v[218:219], off
	s_waitcnt vmcnt(8)
	s_waitcnt lgkmcnt(0)
	s_barrier
	s_setprio 1
	s_waitcnt lgkmcnt(0)
	v_mfma_f32_16x16x32_bf16 v[60:63], v[146:149], v[184:187], v[60:63]
	v_mfma_f32_16x16x32_bf16 v[52:55], v[154:157], v[184:187], v[52:55]
	v_mfma_f32_16x16x32_bf16 v[44:47], v[146:149], v[192:195], v[44:47]
	v_mfma_f32_16x16x32_bf16 v[36:39], v[154:157], v[192:195], v[36:39]
	v_mfma_f32_16x16x32_bf16 v[28:31], v[146:149], v[202:205], v[28:31]
	v_mfma_f32_16x16x32_bf16 v[20:23], v[154:157], v[202:205], v[20:23]
	v_mfma_f32_16x16x32_bf16 v[12:15], v[146:149], v[210:213], v[12:15]
	v_mfma_f32_16x16x32_bf16 v[4:7], v[154:157], v[210:213], v[4:7]
	v_mfma_f32_16x16x32_bf16 v[60:63], v[150:153], v[188:191], v[60:63]
	v_mfma_f32_16x16x32_bf16 v[52:55], v[158:161], v[188:191], v[52:55]
	v_mfma_f32_16x16x32_bf16 v[44:47], v[150:153], v[196:199], v[44:47]
	v_mfma_f32_16x16x32_bf16 v[36:39], v[158:161], v[196:199], v[36:39]
	v_mfma_f32_16x16x32_bf16 v[28:31], v[150:153], v[206:209], v[28:31]
	v_mfma_f32_16x16x32_bf16 v[20:23], v[158:161], v[206:209], v[20:23]
	v_mfma_f32_16x16x32_bf16 v[12:15], v[150:153], v[214:217], v[12:15]
	v_mfma_f32_16x16x32_bf16 v[4:7], v[158:161], v[214:217], v[4:7]
	s_setprio 0
	s_setprio 1
	v_mfma_f32_16x16x32_bf16 v[56:59], v[162:165], v[184:187], v[56:59]
	v_mfma_f32_16x16x32_bf16 v[48:51], v[176:179], v[184:187], v[48:51]
	v_mfma_f32_16x16x32_bf16 v[40:43], v[162:165], v[192:195], v[40:43]
	v_mfma_f32_16x16x32_bf16 v[32:35], v[176:179], v[192:195], v[32:35]
	v_mfma_f32_16x16x32_bf16 v[24:27], v[162:165], v[202:205], v[24:27]
	v_mfma_f32_16x16x32_bf16 v[16:19], v[176:179], v[202:205], v[16:19]
	v_mfma_f32_16x16x32_bf16 v[8:11], v[162:165], v[210:213], v[8:11]
	v_mfma_f32_16x16x32_bf16 v[0:3], v[176:179], v[210:213], v[0:3]
	v_mfma_f32_16x16x32_bf16 v[56:59], v[166:169], v[188:191], v[56:59]
	v_mfma_f32_16x16x32_bf16 v[48:51], v[180:183], v[188:191], v[48:51]
	v_mfma_f32_16x16x32_bf16 v[40:43], v[166:169], v[196:199], v[40:43]
	v_mfma_f32_16x16x32_bf16 v[32:35], v[180:183], v[196:199], v[32:35]
	v_mfma_f32_16x16x32_bf16 v[24:27], v[166:169], v[206:209], v[24:27]
	v_mfma_f32_16x16x32_bf16 v[16:19], v[180:183], v[206:209], v[16:19]
	v_mfma_f32_16x16x32_bf16 v[8:11], v[166:169], v[214:217], v[8:11]
	v_mfma_f32_16x16x32_bf16 v[0:3], v[180:183], v[214:217], v[0:3]
	s_setprio 0
	s_barrier
	s_add_u32 s4, s4, 0x100
	s_addc_u32 s5, s5, 0
	s_add_u32 s11, s11, 0x100
	s_addc_u32 s16, s16, 0
	s_cmp_ge_i32 s46, s65
	s_mov_b32 s6, s46
	s_cbranch_scc1 .LBB0_357

; #define PG8_STAGE(bufoff, gbase, voff) do { _Pragma("unroll") for (int _i = 0; _i < 2; ++_i) \
;         __builtin_amdgcn_global_load_lds((const unsigned*)((const char*)(gbase) + (voff)[_i]), (PG8_LAS unsigned*)(lds + (bufoff) + ldsw + _i * 8192), 16, 0, 0); } while (0)
; #define PG8_LDA(dst, b, h) do { _Pragma("unroll") for (int m = 0; m < 4; ++m) _Pragma("unroll") for (int k = 0; k < 2; ++k) dst[m][k] = *(const PG8_LAS bf16x8*)(lds + PG8_SA(b, h) + aoff + m * 2048 + k * 1024); } while (0)
; #define PG8_LDB(dst, b, h) do { _Pragma("unroll") for (int n = 0; n < 2; ++n) _Pragma("unroll") for (int k = 0; k < 2; ++k) dst[n][k] = *(const PG8_LAS bf16x8*)(lds + PG8_SB(b, h) + boff + n * 2048 + k * 1024); } while (0)
; #define PG8_MMA(ai, bj, At, Bt) do { __builtin_amdgcn_s_setprio(1); _Pragma("unroll") for (int m = 0; m < 4; ++m) _Pragma("unroll") for (int n = 0; n < 2; ++n) _Pragma("unroll") for (int k = 0; k < 2; ++k) \
;         acc[ai][bj][m][n] = __builtin_amdgcn_mfma_f32_16x16x32_bf16(Bt[n][k], At[m][k], acc[ai][bj][m][n], 0, 0, 0); __builtin_amdgcn_s_setprio(0); } while (0)
; #define PG8_WAIT_V(n) asm volatile("s_waitcnt vmcnt(" #n ")" ::: "memory")
; #define PG8_WAIT_L(n) asm volatile("s_waitcnt lgkmcnt(" #n ")" ::: "memory")
; #define PG8_BAR __builtin_amdgcn_s_barrier()
; #define PG8_SCHED __builtin_amdgcn_sched_barrier(0)
; template <class Epi, class Sched, bool ALIGN_EPI = false, bool SP2 = false>
; __device__ __forceinline__ void gemm_phase(PG8_LAS unsigned char* lds, const Gemm g, const Sched& S, const Epi& E) {
;     ...
;             const bool last = (t == nt - 2);
;             const char* a1 = cA + (size_t)(t + 1) * kstep;
;             const char* a2 = last ? nA : cA + (size_t)(t + 2) * kstep; const char* b2 = last ? nB : cB + (size_t)(t + 2) * kstep;
;             const char* a3 = a2 + kstep; const char* b3 = b2 + kstep;
;             if (last && has_next) S.a_ready(nxt);
;             if constexpr (SP2) {
;             PG8_LDB(B0, 0, 0); PG8_LDB(B1, 0, 1); PG8_SCHED; PG8_LDA(At, 0, 0); PG8_STAGE(PG8_SA(1, 1), a1 + hstep, voffA);
;             PG8_WAIT_V(8); PG8_WAIT_L(0); PG8_BAR; PG8_MMA(0, 0, At, B0); PG8_MMA(0, 1, At, B1); PG8_BAR; PG8_SCHED;
;             PG8_LDA(At, 0, 1); PG8_STAGE(PG8_SB(0, 0), b2, voffB); PG8_STAGE(PG8_SB(0, 1), b2 + hstep, voffB); PG8_STAGE(PG8_SA(0, 0), a2, voffA);
.LBB0_710:
	s_andn2_b64 vcc, exec, s[18:19]
	s_cbranch_vccnz .LBB0_713
	s_add_u32 s6, s6, 0x80
	s_addc_u32 s7, s7, 0
	s_add_u32 s58, s30, 0x100
	s_addc_u32 s59, s31, 0
	s_mov_b32 s30, 0
	ds_read_b128 v[146:149], v169
	ds_read_b128 v[150:153], v169 offset:1024
	ds_read_b128 v[154:157], v169 offset:2048
	ds_read_b128 v[158:161], v169 offset:3072
	ds_read_b128 v[162:165], v170
	ds_read_b128 v[174:177], v170 offset:1024
	ds_read_b128 v[178:181], v170 offset:2048
	ds_read_b128 v[182:185], v170 offset:3072
	s_add_i32 s60, s30, 2
	s_add_u32 s61, s6, 0x80
	s_addc_u32 s31, s7, 0
	s_cmp_eq_u32 s49, s30
	s_cselect_b32 s30, s0, s61
	s_cselect_b32 s31, s1, s31
	s_cselect_b32 s63, s29, s59
	s_cselect_b32 s62, s28, s58
	v_lshl_add_u64 v[166:167], s[6:7], 0, v[138:139]
	s_add_i32 m0, s40, 0xc000
	ds_read_b128 v[186:189], v171
	ds_read_b128 v[190:193], v171 offset:1024
	ds_read_b128 v[194:197], v171 offset:2048
	ds_read_b128 v[202:205], v171 offset:3072
	ds_read_b128 v[206:209], v171 offset:4096
	ds_read_b128 v[210:213], v171 offset:5120
	ds_read_b128 v[214:217], v171 offset:6144
	ds_read_b128 v[218:221], v171 offset:7168
	global_load_lds_dwordx4 v[166:167], off
	v_lshl_add_u64 v[166:167], s[6:7], 0, v[140:141]
	s_add_i32 m0, s40, 0xe000
	s_nop 0
	global_load_lds_dwordx4 v[166:167], off
	s_waitcnt vmcnt(8)
	s_waitcnt lgkmcnt(0)
	s_barrier
	s_setprio 1
	s_waitcnt lgkmcnt(0)
	v_mfma_f32_16x16x32_bf16 v[120:123], v[146:149], v[186:189], 0
	v_mfma_f32_16x16x32_bf16 v[124:127], v[154:157], v[186:189], 0
	v_mfma_f32_16x16x32_bf16 v[108:111], v[146:149], v[194:197], 0
	v_mfma_f32_16x16x32_bf16 v[104:107], v[154:157], v[194:197], 0
	v_mfma_f32_16x16x32_bf16 v[92:95], v[146:149], v[206:209], 0
	v_mfma_f32_16x16x32_bf16 v[88:91], v[154:157], v[206:209], 0
	v_mfma_f32_16x16x32_bf16 v[76:79], v[146:149], v[214:217], 0
	v_mfma_f32_16x16x32_bf16 v[72:75], v[154:157], v[214:217], 0
	v_mfma_f32_16x16x32_bf16 v[120:123], v[150:153], v[190:193], v[120:123]
	v_mfma_f32_16x16x32_bf16 v[124:127], v[158:161], v[190:193], v[124:127]
	v_mfma_f32_16x16x32_bf16 v[108:111], v[150:153], v[202:205], v[108:111]
	v_mfma_f32_16x16x32_bf16 v[104:107], v[158:161], v[202:205], v[104:107]
	v_mfma_f32_16x16x32_bf16 v[92:95], v[150:153], v[210:213], v[92:95]
	v_mfma_f32_16x16x32_bf16 v[88:91], v[158:161], v[210:213], v[88:91]
	v_mfma_f32_16x16x32_bf16 v[76:79], v[150:153], v[218:221], v[76:79]
	v_mfma_f32_16x16x32_bf16 v[72:75], v[158:161], v[218:221], v[72:75]
	s_setprio 0
	s_setprio 1
	v_mfma_f32_16x16x32_bf16 v[116:119], v[162:165], v[186:189], 0
	v_mfma_f32_16x16x32_bf16 v[112:115], v[178:181], v[186:189], 0
	v_mfma_f32_16x16x32_bf16 v[100:103], v[162:165], v[194:197], 0
	v_mfma_f32_16x16x32_bf16 v[96:99], v[178:181], v[194:197], 0
	v_mfma_f32_16x16x32_bf16 v[84:87], v[162:165], v[206:209], 0
	v_mfma_f32_16x16x32_bf16 v[80:83], v[178:181], v[206:209], 0
	v_mfma_f32_16x16x32_bf16 v[68:71], v[162:165], v[214:217], 0
	v_mfma_f32_16x16x32_bf16 v[64:67], v[178:181], v[214:217], 0
	v_mfma_f32_16x16x32_bf16 v[116:119], v[174:177], v[190:193], v[116:119]
	v_mfma_f32_16x16x32_bf16 v[112:115], v[182:185], v[190:193], v[112:115]
	v_mfma_f32_16x16x32_bf16 v[100:103], v[174:177], v[202:205], v[100:103]
	v_mfma_f32_16x16x32_bf16 v[96:99], v[182:185], v[202:205], v[96:99]
	v_mfma_f32_16x16x32_bf16 v[84:87], v[174:177], v[210:213], v[84:87]
	v_mfma_f32_16x16x32_bf16 v[80:83], v[182:185], v[210:213], v[80:83]
	v_mfma_f32_16x16x32_bf16 v[68:71], v[174:177], v[218:221], v[68:71]
	v_mfma_f32_16x16x32_bf16 v[64:67], v[182:185], v[218:221], v[64:67]
	s_setprio 0
	s_barrier
	s_add_i32 s61, s53, s39
	v_lshl_add_u64 v[166:167], s[62:63], 0, v[130:131]
	s_mov_b32 m0, s61
	ds_read_b128 v[186:189], v171 offset:16384
	ds_read_b128 v[190:193], v171 offset:17408
	ds_read_b128 v[194:197], v171 offset:18432
	ds_read_b128 v[202:205], v171 offset:19456
	ds_read_b128 v[206:209], v171 offset:20480
	ds_read_b128 v[210:213], v171 offset:21504
	ds_read_b128 v[214:217], v171 offset:22528
	ds_read_b128 v[218:221], v171 offset:23552
	global_load_lds_dwordx4 v[166:167], off
	s_add_i32 m0, s61, 0x2000
	v_lshl_add_u64 v[198:199], s[62:63], 0, v[134:135]
	s_add_u32 s62, s62, s10
	s_addc_u32 s63, s63, s11
	s_add_i32 s61, s54, s39
	global_load_lds_dwordx4 v[198:199], off
	v_lshl_add_u64 v[222:223], s[62:63], 0, v[130:131]
	s_mov_b32 m0, s61
	v_lshl_add_u64 v[224:225], s[62:63], 0, v[134:135]
	global_load_lds_dwordx4 v[222:223], off
	s_add_i32 m0, s61, 0x2000
	v_lshl_add_u64 v[226:227], s[30:31], 0, v[128:129]
	global_load_lds_dwordx4 v[224:225], off
	s_mov_b32 m0, s40
	v_lshl_add_u64 v[228:229], s[30:31], 0, v[132:133]
	global_load_lds_dwordx4 v[226:227], off
	s_mov_b32 m0, s41
	s_nop 0
	global_load_lds_dwordx4 v[228:229], off
	s_waitcnt vmcnt(8)
	s_waitcnt lgkmcnt(0)
	s_barrier
; #define PG8_STAGE(bufoff, gbase, voff) do { _Pragma("unroll") for (int _i = 0; _i < 2; ++_i) \
;         __builtin_amdgcn_global_load_lds((const unsigned*)((const char*)(gbase) + (voff)[_i]), (PG8_LAS unsigned*)(lds + (bufoff) + ldsw + _i * 8192), 16, 0, 0); } while (0)
; #define PG8_LDA(dst, b, h) do { _Pragma("unroll") for (int m = 0; m < 4; ++m) _Pragma("unroll") for (int k = 0; k < 2; ++k) dst[m][k] = *(const PG8_LAS bf16x8*)(lds + PG8_SA(b, h) + aoff + m * 2048 + k * 1024); } while (0)
; #define PG8_LDB(dst, b, h) do { _Pragma("unroll") for (int n = 0; n < 2; ++n) _Pragma("unroll") for (int k = 0; k < 2; ++k) dst[n][k] = *(const PG8_LAS bf16x8*)(lds + PG8_SB(b, h) + boff + n * 2048 + k * 1024); } while (0)
; #define PG8_MMA(ai, bj, At, Bt) do { __builtin_amdgcn_s_setprio(1); _Pragma("unroll") for (int m = 0; m < 4; ++m) _Pragma("unroll") for (int n = 0; n < 2; ++n) _Pragma("unroll") for (int k = 0; k < 2; ++k) \
;         acc[ai][bj][m][n] = __builtin_amdgcn_mfma_f32_16x16x32_bf16(Bt[n][k], At[m][k], acc[ai][bj][m][n], 0, 0, 0); __builtin_amdgcn_s_setprio(0); } while (0)
; #define PG8_WAIT_V(n) asm volatile("s_waitcnt vmcnt(" #n ")" ::: "memory")
; #define PG8_WAIT_L(n) asm volatile("s_waitcnt lgkmcnt(" #n ")" ::: "memory")
; #define PG8_BAR __builtin_amdgcn_s_barrier()
; #define PG8_SCHED __builtin_amdgcn_sched_barrier(0)
; template <class Epi, class Sched, bool ALIGN_EPI = false, bool SP2 = false>
; __device__ __forceinline__ void gemm_phase(PG8_LAS unsigned char* lds, const Gemm g, const Sched& S, const Epi& E) {
;     ...
;             PG8_WAIT_V(8); PG8_WAIT_L(0); PG8_BAR; PG8_MMA(1, 0, At, B0); PG8_MMA(1, 1, At, B1); PG8_BAR; PG8_SCHED;
;             PG8_LDB(B0, 1, 0); PG8_LDB(B1, 1, 1); PG8_SCHED; PG8_LDA(At, 1, 0); PG8_STAGE(PG8_SA(0, 1), a2 + hstep, voffA);
;             PG8_WAIT_V(8); PG8_WAIT_L(0); PG8_BAR; PG8_MMA(0, 0, At, B0); PG8_MMA(0, 1, At, B1); PG8_BAR; PG8_SCHED;
	s_setprio 1
	s_waitcnt lgkmcnt(0)
	v_mfma_f32_16x16x32_bf16 v[60:63], v[146:149], v[186:189], 0
	v_mfma_f32_16x16x32_bf16 v[56:59], v[154:157], v[186:189], 0
	v_mfma_f32_16x16x32_bf16 v[44:47], v[146:149], v[194:197], 0
	v_mfma_f32_16x16x32_bf16 v[40:43], v[154:157], v[194:197], 0
	v_mfma_f32_16x16x32_bf16 v[28:31], v[146:149], v[206:209], 0
	v_mfma_f32_16x16x32_bf16 v[24:27], v[154:157], v[206:209], 0
	v_mfma_f32_16x16x32_bf16 v[12:15], v[146:149], v[214:217], 0
	v_mfma_f32_16x16x32_bf16 v[8:11], v[154:157], v[214:217], 0
	v_mfma_f32_16x16x32_bf16 v[60:63], v[150:153], v[190:193], v[60:63]
	v_mfma_f32_16x16x32_bf16 v[56:59], v[158:161], v[190:193], v[56:59]
	v_mfma_f32_16x16x32_bf16 v[44:47], v[150:153], v[202:205], v[44:47]
	v_mfma_f32_16x16x32_bf16 v[40:43], v[158:161], v[202:205], v[40:43]
	v_mfma_f32_16x16x32_bf16 v[28:31], v[150:153], v[210:213], v[28:31]
	v_mfma_f32_16x16x32_bf16 v[24:27], v[158:161], v[210:213], v[24:27]
	v_mfma_f32_16x16x32_bf16 v[12:15], v[150:153], v[218:221], v[12:15]
	v_mfma_f32_16x16x32_bf16 v[8:11], v[158:161], v[218:221], v[8:11]
	s_setprio 0
	s_setprio 1
	v_mfma_f32_16x16x32_bf16 v[52:55], v[162:165], v[186:189], 0
	v_mfma_f32_16x16x32_bf16 v[48:51], v[178:181], v[186:189], 0
	v_mfma_f32_16x16x32_bf16 v[36:39], v[162:165], v[194:197], 0
	v_mfma_f32_16x16x32_bf16 v[32:35], v[178:181], v[194:197], 0
	v_mfma_f32_16x16x32_bf16 v[20:23], v[162:165], v[206:209], 0
	v_mfma_f32_16x16x32_bf16 v[16:19], v[178:181], v[206:209], 0
	v_mfma_f32_16x16x32_bf16 v[0:3], v[162:165], v[214:217], 0
	v_mfma_f32_16x16x32_bf16 v[4:7], v[178:181], v[214:217], 0
	v_mfma_f32_16x16x32_bf16 v[52:55], v[174:177], v[190:193], v[52:55]
	v_mfma_f32_16x16x32_bf16 v[48:51], v[182:185], v[190:193], v[48:51]
	v_mfma_f32_16x16x32_bf16 v[36:39], v[174:177], v[202:205], v[36:39]
	v_mfma_f32_16x16x32_bf16 v[32:35], v[182:185], v[202:205], v[32:35]
	v_mfma_f32_16x16x32_bf16 v[20:23], v[174:177], v[210:213], v[20:23]
	v_mfma_f32_16x16x32_bf16 v[16:19], v[182:185], v[210:213], v[16:19]
	v_mfma_f32_16x16x32_bf16 v[0:3], v[174:177], v[218:221], v[0:3]
	v_mfma_f32_16x16x32_bf16 v[4:7], v[182:185], v[218:221], v[4:7]
	s_setprio 0
	s_barrier
	s_add_i32 s61, 0, 0x18000
	v_add_u32_e32 v136, s61, v168
	s_add_i32 s62, 0, 0x1c000
	ds_read_b128 v[146:149], v136
	ds_read_b128 v[150:153], v136 offset:1024
	ds_read_b128 v[154:157], v136 offset:2048
	ds_read_b128 v[158:161], v136 offset:3072
	v_add_u32_e32 v136, s62, v168
	ds_read_b128 v[162:165], v136
	ds_read_b128 v[174:177], v136 offset:1024
	ds_read_b128 v[178:181], v136 offset:2048
	ds_read_b128 v[182:185], v136 offset:3072
	s_add_u32 s30, s30, s10
	s_addc_u32 s31, s31, s11
	s_mov_b32 m0, s42
	v_lshl_add_u64 v[230:231], s[30:31], 0, v[128:129]
	ds_read_b128 v[186:189], v171 offset:32768
	ds_read_b128 v[190:193], v171 offset:33792
	ds_read_b128 v[194:197], v171 offset:34816
	ds_read_b128 v[202:205], v171 offset:35840
	ds_read_b128 v[206:209], v171 offset:36864
	ds_read_b128 v[210:213], v171 offset:37888
	ds_read_b128 v[214:217], v171 offset:38912
	ds_read_b128 v[218:221], v171 offset:39936
	global_load_lds_dwordx4 v[230:231], off
	v_lshl_add_u64 v[230:231], s[30:31], 0, v[132:133]
	s_mov_b32 m0, s43
	s_nop 0
	global_load_lds_dwordx4 v[230:231], off
	s_waitcnt vmcnt(8)
	s_waitcnt lgkmcnt(0)
	s_barrier
	s_setprio 1
	s_waitcnt lgkmcnt(0)
	v_mfma_f32_16x16x32_bf16 v[120:123], v[146:149], v[186:189], v[120:123]
	v_mfma_f32_16x16x32_bf16 v[124:127], v[154:157], v[186:189], v[124:127]
	v_mfma_f32_16x16x32_bf16 v[108:111], v[146:149], v[194:197], v[108:111]
	v_mfma_f32_16x16x32_bf16 v[104:107], v[154:157], v[194:197], v[104:107]
	v_mfma_f32_16x16x32_bf16 v[92:95], v[146:149], v[206:209], v[92:95]
	v_mfma_f32_16x16x32_bf16 v[88:91], v[154:157], v[206:209], v[88:91]
	v_mfma_f32_16x16x32_bf16 v[76:79], v[146:149], v[214:217], v[76:79]
	v_mfma_f32_16x16x32_bf16 v[72:75], v[154:157], v[214:217], v[72:75]
	v_mfma_f32_16x16x32_bf16 v[120:123], v[150:153], v[190:193], v[120:123]
	v_mfma_f32_16x16x32_bf16 v[124:127], v[158:161], v[190:193], v[124:127]
	v_mfma_f32_16x16x32_bf16 v[108:111], v[150:153], v[202:205], v[108:111]
	v_mfma_f32_16x16x32_bf16 v[104:107], v[158:161], v[202:205], v[104:107]
	v_mfma_f32_16x16x32_bf16 v[92:95], v[150:153], v[210:213], v[92:95]
	v_mfma_f32_16x16x32_bf16 v[88:91], v[158:161], v[210:213], v[88:91]
	v_mfma_f32_16x16x32_bf16 v[76:79], v[150:153], v[218:221], v[76:79]
	v_mfma_f32_16x16x32_bf16 v[72:75], v[158:161], v[218:221], v[72:75]
	s_setprio 0
	s_setprio 1
	v_mfma_f32_16x16x32_bf16 v[116:119], v[162:165], v[186:189], v[116:119]
	v_mfma_f32_16x16x32_bf16 v[112:115], v[178:181], v[186:189], v[112:115]
	v_mfma_f32_16x16x32_bf16 v[100:103], v[162:165], v[194:197], v[100:103]
	v_mfma_f32_16x16x32_bf16 v[96:99], v[178:181], v[194:197], v[96:99]
	v_mfma_f32_16x16x32_bf16 v[84:87], v[162:165], v[206:209], v[84:87]
	v_mfma_f32_16x16x32_bf16 v[80:83], v[178:181], v[206:209], v[80:83]
	v_mfma_f32_16x16x32_bf16 v[68:71], v[162:165], v[214:217], v[68:71]
	v_mfma_f32_16x16x32_bf16 v[64:67], v[178:181], v[214:217], v[64:67]
	v_mfma_f32_16x16x32_bf16 v[116:119], v[174:177], v[190:193], v[116:119]
	v_mfma_f32_16x16x32_bf16 v[112:115], v[182:185], v[190:193], v[112:115]
	v_mfma_f32_16x16x32_bf16 v[100:103], v[174:177], v[202:205], v[100:103]
	v_mfma_f32_16x16x32_bf16 v[96:99], v[182:185], v[202:205], v[96:99]
	v_mfma_f32_16x16x32_bf16 v[84:87], v[174:177], v[210:213], v[84:87]
	v_mfma_f32_16x16x32_bf16 v[80:83], v[182:185], v[210:213], v[80:83]
	v_mfma_f32_16x16x32_bf16 v[68:71], v[174:177], v[218:221], v[68:71]
	v_mfma_f32_16x16x32_bf16 v[64:67], v[182:185], v[218:221], v[64:67]
	s_setprio 0
	s_barrier
; #define PG8_STAGE(bufoff, gbase, voff) do { _Pragma("unroll") for (int _i = 0; _i < 2; ++_i) \
;         __builtin_amdgcn_global_load_lds((const unsigned*)((const char*)(gbase) + (voff)[_i]), (PG8_LAS unsigned*)(lds + (bufoff) + ldsw + _i * 8192), 16, 0, 0); } while (0)
; #define PG8_LDA(dst, b, h) do { _Pragma("unroll") for (int m = 0; m < 4; ++m) _Pragma("unroll") for (int k = 0; k < 2; ++k) dst[m][k] = *(const PG8_LAS bf16x8*)(lds + PG8_SA(b, h) + aoff + m * 2048 + k * 1024); } while (0)
; #define PG8_MMA(ai, bj, At, Bt) do { __builtin_amdgcn_s_setprio(1); _Pragma("unroll") for (int m = 0; m < 4; ++m) _Pragma("unroll") for (int n = 0; n < 2; ++n) _Pragma("unroll") for (int k = 0; k < 2; ++k) \
;         acc[ai][bj][m][n] = __builtin_amdgcn_mfma_f32_16x16x32_bf16(Bt[n][k], At[m][k], acc[ai][bj][m][n], 0, 0, 0); __builtin_amdgcn_s_setprio(0); } while (0)
; #define PG8_WAIT_V(n) asm volatile("s_waitcnt vmcnt(" #n ")" ::: "memory")
; #define PG8_WAIT_L(n) asm volatile("s_waitcnt lgkmcnt(" #n ")" ::: "memory")
; #define PG8_BAR __builtin_amdgcn_s_barrier()
; #define PG8_SCHED __builtin_amdgcn_sched_barrier(0)
; template <class Epi, class Sched, bool ALIGN_EPI = false, bool SP2 = false>
; __device__ __forceinline__ void gemm_phase(PG8_LAS unsigned char* lds, const Gemm g, const Sched& S, const Epi& E) {
;     ...
;         for (int t = 0; t < nt; t += 2) {
;     ...
;             PG8_LDA(At, 1, 1); PG8_STAGE(PG8_SB(1, 0), b3, voffB); PG8_STAGE(PG8_SB(1, 1), b3 + hstep, voffB); PG8_STAGE(PG8_SA(1, 0), a3, voffA);
;             PG8_WAIT_V(8); PG8_WAIT_L(0); PG8_BAR; PG8_MMA(1, 0, At, B0); PG8_MMA(1, 1, At, B1); PG8_BAR; PG8_SCHED;
	s_add_i32 s30, s61, s39
	v_lshl_add_u64 v[166:167], v[166:167], 0, s[16:17]
	s_mov_b32 m0, s30
	ds_read_b128 v[186:189], v171 offset:49152
	ds_read_b128 v[190:193], v171 offset:50176
	ds_read_b128 v[194:197], v171 offset:51200
	ds_read_b128 v[202:205], v171 offset:52224
	ds_read_b128 v[206:209], v171 offset:53248
	ds_read_b128 v[210:213], v171 offset:54272
	ds_read_b128 v[214:217], v171 offset:55296
	ds_read_b128 v[218:221], v171 offset:56320
	global_load_lds_dwordx4 v[166:167], off
	v_lshl_add_u64 v[166:167], v[198:199], 0, s[16:17]
	s_add_i32 m0, s30, 0x2000
	s_add_i32 s30, s62, s39
	global_load_lds_dwordx4 v[166:167], off
	v_lshl_add_u64 v[166:167], v[222:223], 0, s[16:17]
	s_mov_b32 m0, s30
	s_nop 0
	global_load_lds_dwordx4 v[166:167], off
	v_lshl_add_u64 v[166:167], v[224:225], 0, s[16:17]
	s_add_i32 m0, s30, 0x2000
	s_nop 0
	global_load_lds_dwordx4 v[166:167], off
	v_lshl_add_u64 v[166:167], v[226:227], 0, s[16:17]
	s_mov_b32 m0, s45
	s_nop 0
	global_load_lds_dwordx4 v[166:167], off
	v_lshl_add_u64 v[166:167], v[228:229], 0, s[16:17]
	s_mov_b32 m0, s46
	s_nop 0
	global_load_lds_dwordx4 v[166:167], off
	s_waitcnt vmcnt(8)
	s_waitcnt lgkmcnt(0)
	s_barrier
	s_setprio 1
	s_waitcnt lgkmcnt(0)
	v_mfma_f32_16x16x32_bf16 v[60:63], v[146:149], v[186:189], v[60:63]
	v_mfma_f32_16x16x32_bf16 v[56:59], v[154:157], v[186:189], v[56:59]
	v_mfma_f32_16x16x32_bf16 v[44:47], v[146:149], v[194:197], v[44:47]
	v_mfma_f32_16x16x32_bf16 v[40:43], v[154:157], v[194:197], v[40:43]
	v_mfma_f32_16x16x32_bf16 v[28:31], v[146:149], v[206:209], v[28:31]
	v_mfma_f32_16x16x32_bf16 v[24:27], v[154:157], v[206:209], v[24:27]
	v_mfma_f32_16x16x32_bf16 v[12:15], v[146:149], v[214:217], v[12:15]
	v_mfma_f32_16x16x32_bf16 v[8:11], v[154:157], v[214:217], v[8:11]
	v_mfma_f32_16x16x32_bf16 v[60:63], v[150:153], v[190:193], v[60:63]
	v_mfma_f32_16x16x32_bf16 v[56:59], v[158:161], v[190:193], v[56:59]
	v_mfma_f32_16x16x32_bf16 v[44:47], v[150:153], v[202:205], v[44:47]
	v_mfma_f32_16x16x32_bf16 v[40:43], v[158:161], v[202:205], v[40:43]
	v_mfma_f32_16x16x32_bf16 v[28:31], v[150:153], v[210:213], v[28:31]
	v_mfma_f32_16x16x32_bf16 v[24:27], v[158:161], v[210:213], v[24:27]
	v_mfma_f32_16x16x32_bf16 v[12:15], v[150:153], v[218:221], v[12:15]
	v_mfma_f32_16x16x32_bf16 v[8:11], v[158:161], v[218:221], v[8:11]
	s_setprio 0
	s_setprio 1
	v_mfma_f32_16x16x32_bf16 v[52:55], v[162:165], v[186:189], v[52:55]
	v_mfma_f32_16x16x32_bf16 v[48:51], v[178:181], v[186:189], v[48:51]
	v_mfma_f32_16x16x32_bf16 v[36:39], v[162:165], v[194:197], v[36:39]
	v_mfma_f32_16x16x32_bf16 v[32:35], v[178:181], v[194:197], v[32:35]
	v_mfma_f32_16x16x32_bf16 v[20:23], v[162:165], v[206:209], v[20:23]
	v_mfma_f32_16x16x32_bf16 v[16:19], v[178:181], v[206:209], v[16:19]
	v_mfma_f32_16x16x32_bf16 v[0:3], v[162:165], v[214:217], v[0:3]
	v_mfma_f32_16x16x32_bf16 v[4:7], v[178:181], v[214:217], v[4:7]
	v_mfma_f32_16x16x32_bf16 v[52:55], v[174:177], v[190:193], v[52:55]
	v_mfma_f32_16x16x32_bf16 v[48:51], v[182:185], v[190:193], v[48:51]
	v_mfma_f32_16x16x32_bf16 v[36:39], v[174:177], v[202:205], v[36:39]
	v_mfma_f32_16x16x32_bf16 v[32:35], v[182:185], v[202:205], v[32:35]
	v_mfma_f32_16x16x32_bf16 v[20:23], v[174:177], v[210:213], v[20:23]
	v_mfma_f32_16x16x32_bf16 v[16:19], v[182:185], v[210:213], v[16:19]
	v_mfma_f32_16x16x32_bf16 v[0:3], v[174:177], v[218:221], v[0:3]
	v_mfma_f32_16x16x32_bf16 v[4:7], v[182:185], v[218:221], v[4:7]
	s_setprio 0
	s_barrier
	s_add_u32 s6, s6, 0x100
	s_addc_u32 s7, s7, 0
	s_add_u32 s58, s58, 0x100
	s_addc_u32 s59, s59, 0
	s_cmp_ge_i32 s60, s47
	s_mov_b32 s30, s60
	s_cbranch_scc1 .LBB0_713

; #define PG8_STAGE(bufoff, gbase, voff) do { _Pragma("unroll") for (int _i = 0; _i < 2; ++_i) \
;         __builtin_amdgcn_global_load_lds((const unsigned*)((const char*)(gbase) + (voff)[_i]), (PG8_LAS unsigned*)(lds + (bufoff) + ldsw + _i * 8192), 16, 0, 0); } while (0)
; #define PG8_LDA(dst, b, h) do { _Pragma("unroll") for (int m = 0; m < 4; ++m) _Pragma("unroll") for (int k = 0; k < 2; ++k) dst[m][k] = *(const PG8_LAS bf16x8*)(lds + PG8_SA(b, h) + aoff + m * 2048 + k * 1024); } while (0)
; #define PG8_LDB(dst, b, h) do { _Pragma("unroll") for (int n = 0; n < 2; ++n) _Pragma("unroll") for (int k = 0; k < 2; ++k) dst[n][k] = *(const PG8_LAS bf16x8*)(lds + PG8_SB(b, h) + boff + n * 2048 + k * 1024); } while (0)
; #define PG8_MMA(ai, bj, At, Bt) do { __builtin_amdgcn_s_setprio(1); _Pragma("unroll") for (int m = 0; m < 4; ++m) _Pragma("unroll") for (int n = 0; n < 2; ++n) _Pragma("unroll") for (int k = 0; k < 2; ++k) \
;         acc[ai][bj][m][n] = __builtin_amdgcn_mfma_f32_16x16x32_bf16(Bt[n][k], At[m][k], acc[ai][bj][m][n], 0, 0, 0); __builtin_amdgcn_s_setprio(0); } while (0)
; #define PG8_WAIT_V(n) asm volatile("s_waitcnt vmcnt(" #n ")" ::: "memory")
; #define PG8_WAIT_L(n) asm volatile("s_waitcnt lgkmcnt(" #n ")" ::: "memory")
; #define PG8_BAR __builtin_amdgcn_s_barrier()
; #define PG8_SCHED __builtin_amdgcn_sched_barrier(0)
; template <class Epi, class Sched, bool ALIGN_EPI = false, bool SP2 = false>
; __device__ __forceinline__ void gemm_phase(PG8_LAS unsigned char* lds, const Gemm g, const Sched& S, const Epi& E) {
;     ...
;             const bool last = (t == nt - 2);
;             const char* a1 = cA + (size_t)(t + 1) * kstep;
;             const char* a2 = last ? nA : cA + (size_t)(t + 2) * kstep; const char* b2 = last ? nB : cB + (size_t)(t + 2) * kstep;
;             const char* a3 = a2 + kstep; const char* b3 = b2 + kstep;
;             if (last && has_next) S.a_ready(nxt);
;             if constexpr (SP2) {
;             PG8_LDB(B0, 0, 0); PG8_LDB(B1, 0, 1); PG8_SCHED; PG8_LDA(At, 0, 0); PG8_STAGE(PG8_SA(1, 1), a1 + hstep, voffA);
;             PG8_WAIT_V(8); PG8_WAIT_L(0); PG8_BAR; PG8_MMA(0, 0, At, B0); PG8_MMA(0, 1, At, B1); PG8_BAR; PG8_SCHED;
;             PG8_LDA(At, 0, 1); PG8_STAGE(PG8_SB(0, 0), b2, voffB); PG8_STAGE(PG8_SB(0, 1), b2 + hstep, voffB); PG8_STAGE(PG8_SA(0, 0), a2, voffA);
.LBB0_773:
	s_andn2_b64 vcc, exec, s[16:17]
	s_cbranch_vccnz .LBB0_776
	s_add_u32 s10, s10, 0x80
	s_addc_u32 s11, s11, 0
	s_add_u32 s55, s30, 0x100
	s_addc_u32 s56, s31, 0
	s_mov_b32 s30, 0
	ds_read_b128 v[80:83], v246
	ds_read_b128 v[84:87], v246 offset:1024
	ds_read_b128 v[88:91], v246 offset:2048
	ds_read_b128 v[92:95], v246 offset:3072
	ds_read_b128 v[96:99], v247
	ds_read_b128 v[100:103], v247 offset:1024
	ds_read_b128 v[152:155], v247 offset:2048
	ds_read_b128 v[156:159], v247 offset:3072
	s_add_i32 s57, s30, 2
	s_add_u32 s58, s10, 0x80
	s_addc_u32 s31, s11, 0
	s_cmp_eq_u32 s47, s30
	s_cselect_b32 s30, s0, s58
	s_cselect_b32 s31, s1, s31
	s_cselect_b32 s59, s29, s56
	s_cselect_b32 s58, s28, s55
	v_lshl_add_u64 v[192:193], s[10:11], 0, v[210:211]
	s_add_i32 m0, s37, 0xc000
	ds_read_b128 v[160:163], v248
	ds_read_b128 v[164:167], v248 offset:1024
	ds_read_b128 v[168:171], v248 offset:2048
	ds_read_b128 v[172:175], v248 offset:3072
	ds_read_b128 v[176:179], v248 offset:4096
	ds_read_b128 v[180:183], v248 offset:5120
	ds_read_b128 v[184:187], v248 offset:6144
	ds_read_b128 v[188:191], v248 offset:7168
	global_load_lds_dwordx4 v[192:193], off
	v_lshl_add_u64 v[192:193], s[10:11], 0, v[212:213]
	s_add_i32 m0, s37, 0xe000
	s_nop 0
	global_load_lds_dwordx4 v[192:193], off
	s_waitcnt vmcnt(8)
	s_waitcnt lgkmcnt(0)
	s_barrier
	s_setprio 1
	s_waitcnt lgkmcnt(0)
	v_mfma_f32_16x16x32_bf16 v[144:147], v[80:83], v[160:163], 0
	v_mfma_f32_16x16x32_bf16 v[136:139], v[88:91], v[160:163], 0
	v_mfma_f32_16x16x32_bf16 v[128:131], v[80:83], v[168:171], 0
	v_mfma_f32_16x16x32_bf16 v[120:123], v[88:91], v[168:171], 0
	v_mfma_f32_16x16x32_bf16 v[112:115], v[80:83], v[176:179], 0
	v_mfma_f32_16x16x32_bf16 v[104:107], v[88:91], v[176:179], 0
	v_mfma_f32_16x16x32_bf16 v[72:75], v[80:83], v[184:187], 0
	v_mfma_f32_16x16x32_bf16 v[64:67], v[88:91], v[184:187], 0
	v_mfma_f32_16x16x32_bf16 v[144:147], v[84:87], v[164:167], v[144:147]
	v_mfma_f32_16x16x32_bf16 v[136:139], v[92:95], v[164:167], v[136:139]
	v_mfma_f32_16x16x32_bf16 v[128:131], v[84:87], v[172:175], v[128:131]
	v_mfma_f32_16x16x32_bf16 v[120:123], v[92:95], v[172:175], v[120:123]
	v_mfma_f32_16x16x32_bf16 v[112:115], v[84:87], v[180:183], v[112:115]
	v_mfma_f32_16x16x32_bf16 v[104:107], v[92:95], v[180:183], v[104:107]
	v_mfma_f32_16x16x32_bf16 v[72:75], v[84:87], v[188:191], v[72:75]
	v_mfma_f32_16x16x32_bf16 v[64:67], v[92:95], v[188:191], v[64:67]
	s_setprio 0
	s_setprio 1
	v_mfma_f32_16x16x32_bf16 v[148:151], v[96:99], v[160:163], 0
	v_mfma_f32_16x16x32_bf16 v[140:143], v[152:155], v[160:163], 0
	v_mfma_f32_16x16x32_bf16 v[132:135], v[96:99], v[168:171], 0
	v_mfma_f32_16x16x32_bf16 v[124:127], v[152:155], v[168:171], 0
	v_mfma_f32_16x16x32_bf16 v[116:119], v[96:99], v[176:179], 0
	v_mfma_f32_16x16x32_bf16 v[108:111], v[152:155], v[176:179], 0
	v_mfma_f32_16x16x32_bf16 v[76:79], v[96:99], v[184:187], 0
	v_mfma_f32_16x16x32_bf16 v[68:71], v[152:155], v[184:187], 0
	v_mfma_f32_16x16x32_bf16 v[148:151], v[100:103], v[164:167], v[148:151]
	v_mfma_f32_16x16x32_bf16 v[140:143], v[156:159], v[164:167], v[140:143]
	v_mfma_f32_16x16x32_bf16 v[132:135], v[100:103], v[172:175], v[132:135]
	v_mfma_f32_16x16x32_bf16 v[124:127], v[156:159], v[172:175], v[124:127]
	v_mfma_f32_16x16x32_bf16 v[116:119], v[100:103], v[180:183], v[116:119]
	v_mfma_f32_16x16x32_bf16 v[108:111], v[156:159], v[180:183], v[108:111]
	v_mfma_f32_16x16x32_bf16 v[76:79], v[100:103], v[188:191], v[76:79]
	v_mfma_f32_16x16x32_bf16 v[68:71], v[156:159], v[188:191], v[68:71]
	s_setprio 0
	s_barrier
	s_add_i32 s60, s50, s36
	v_lshl_add_u64 v[192:193], s[58:59], 0, v[204:205]
	s_mov_b32 m0, s60
	ds_read_b128 v[160:163], v248 offset:16384
	ds_read_b128 v[164:167], v248 offset:17408
	ds_read_b128 v[168:171], v248 offset:18432
	ds_read_b128 v[172:175], v248 offset:19456
	ds_read_b128 v[176:179], v248 offset:20480
	ds_read_b128 v[180:183], v248 offset:21504
	ds_read_b128 v[184:187], v248 offset:22528
	ds_read_b128 v[188:191], v248 offset:23552
	global_load_lds_dwordx4 v[192:193], off
	s_add_i32 m0, s60, 0x2000
	v_lshl_add_u64 v[194:195], s[58:59], 0, v[208:209]
	s_add_u32 s58, s58, s4
	s_addc_u32 s59, s59, s5
	s_add_i32 s60, s51, s36
	global_load_lds_dwordx4 v[194:195], off
	v_lshl_add_u64 v[196:197], s[58:59], 0, v[204:205]
	s_mov_b32 m0, s60
	v_lshl_add_u64 v[198:199], s[58:59], 0, v[208:209]
	global_load_lds_dwordx4 v[196:197], off
	s_add_i32 m0, s60, 0x2000
	v_lshl_add_u64 v[218:219], s[30:31], 0, v[202:203]
	global_load_lds_dwordx4 v[198:199], off
	s_mov_b32 m0, s37
	v_lshl_add_u64 v[220:221], s[30:31], 0, v[206:207]
	global_load_lds_dwordx4 v[218:219], off
	s_mov_b32 m0, s38
	s_nop 0
	global_load_lds_dwordx4 v[220:221], off
	s_waitcnt vmcnt(8)
	s_waitcnt lgkmcnt(0)
	s_barrier
; #define PG8_STAGE(bufoff, gbase, voff) do { _Pragma("unroll") for (int _i = 0; _i < 2; ++_i) \
;         __builtin_amdgcn_global_load_lds((const unsigned*)((const char*)(gbase) + (voff)[_i]), (PG8_LAS unsigned*)(lds + (bufoff) + ldsw + _i * 8192), 16, 0, 0); } while (0)
; #define PG8_LDA(dst, b, h) do { _Pragma("unroll") for (int m = 0; m < 4; ++m) _Pragma("unroll") for (int k = 0; k < 2; ++k) dst[m][k] = *(const PG8_LAS bf16x8*)(lds + PG8_SA(b, h) + aoff + m * 2048 + k * 1024); } while (0)
; #define PG8_LDB(dst, b, h) do { _Pragma("unroll") for (int n = 0; n < 2; ++n) _Pragma("unroll") for (int k = 0; k < 2; ++k) dst[n][k] = *(const PG8_LAS bf16x8*)(lds + PG8_SB(b, h) + boff + n * 2048 + k * 1024); } while (0)
; #define PG8_MMA(ai, bj, At, Bt) do { __builtin_amdgcn_s_setprio(1); _Pragma("unroll") for (int m = 0; m < 4; ++m) _Pragma("unroll") for (int n = 0; n < 2; ++n) _Pragma("unroll") for (int k = 0; k < 2; ++k) \
;         acc[ai][bj][m][n] = __builtin_amdgcn_mfma_f32_16x16x32_bf16(Bt[n][k], At[m][k], acc[ai][bj][m][n], 0, 0, 0); __builtin_amdgcn_s_setprio(0); } while (0)
; #define PG8_WAIT_V(n) asm volatile("s_waitcnt vmcnt(" #n ")" ::: "memory")
; #define PG8_WAIT_L(n) asm volatile("s_waitcnt lgkmcnt(" #n ")" ::: "memory")
; #define PG8_BAR __builtin_amdgcn_s_barrier()
; #define PG8_SCHED __builtin_amdgcn_sched_barrier(0)
; template <class Epi, class Sched, bool ALIGN_EPI = false, bool SP2 = false>
; __device__ __forceinline__ void gemm_phase(PG8_LAS unsigned char* lds, const Gemm g, const Sched& S, const Epi& E) {
;     ...
;             PG8_WAIT_V(8); PG8_WAIT_L(0); PG8_BAR; PG8_MMA(1, 0, At, B0); PG8_MMA(1, 1, At, B1); PG8_BAR; PG8_SCHED;
;             PG8_LDB(B0, 1, 0); PG8_LDB(B1, 1, 1); PG8_SCHED; PG8_LDA(At, 1, 0); PG8_STAGE(PG8_SA(0, 1), a2 + hstep, voffA);
;             PG8_WAIT_V(8); PG8_WAIT_L(0); PG8_BAR; PG8_MMA(0, 0, At, B0); PG8_MMA(0, 1, At, B1); PG8_BAR; PG8_SCHED;
	s_setprio 1
	s_waitcnt lgkmcnt(0)
	v_mfma_f32_16x16x32_bf16 v[56:59], v[80:83], v[160:163], 0
	v_mfma_f32_16x16x32_bf16 v[48:51], v[88:91], v[160:163], 0
	v_mfma_f32_16x16x32_bf16 v[40:43], v[80:83], v[168:171], 0
	v_mfma_f32_16x16x32_bf16 v[32:35], v[88:91], v[168:171], 0
	v_mfma_f32_16x16x32_bf16 v[24:27], v[80:83], v[176:179], 0
	v_mfma_f32_16x16x32_bf16 v[16:19], v[88:91], v[176:179], 0
	v_mfma_f32_16x16x32_bf16 v[8:11], v[80:83], v[184:187], 0
	v_mfma_f32_16x16x32_bf16 v[0:3], v[88:91], v[184:187], 0
	v_mfma_f32_16x16x32_bf16 v[56:59], v[84:87], v[164:167], v[56:59]
	v_mfma_f32_16x16x32_bf16 v[48:51], v[92:95], v[164:167], v[48:51]
	v_mfma_f32_16x16x32_bf16 v[40:43], v[84:87], v[172:175], v[40:43]
	v_mfma_f32_16x16x32_bf16 v[32:35], v[92:95], v[172:175], v[32:35]
	v_mfma_f32_16x16x32_bf16 v[24:27], v[84:87], v[180:183], v[24:27]
	v_mfma_f32_16x16x32_bf16 v[16:19], v[92:95], v[180:183], v[16:19]
	v_mfma_f32_16x16x32_bf16 v[8:11], v[84:87], v[188:191], v[8:11]
	v_mfma_f32_16x16x32_bf16 v[0:3], v[92:95], v[188:191], v[0:3]
	s_setprio 0
	s_setprio 1
	v_mfma_f32_16x16x32_bf16 v[60:63], v[96:99], v[160:163], 0
	v_mfma_f32_16x16x32_bf16 v[52:55], v[152:155], v[160:163], 0
	v_mfma_f32_16x16x32_bf16 v[44:47], v[96:99], v[168:171], 0
	v_mfma_f32_16x16x32_bf16 v[36:39], v[152:155], v[168:171], 0
	v_mfma_f32_16x16x32_bf16 v[28:31], v[96:99], v[176:179], 0
	v_mfma_f32_16x16x32_bf16 v[20:23], v[152:155], v[176:179], 0
	v_mfma_f32_16x16x32_bf16 v[12:15], v[96:99], v[184:187], 0
	v_mfma_f32_16x16x32_bf16 v[4:7], v[152:155], v[184:187], 0
	v_mfma_f32_16x16x32_bf16 v[60:63], v[100:103], v[164:167], v[60:63]
	v_mfma_f32_16x16x32_bf16 v[52:55], v[156:159], v[164:167], v[52:55]
	v_mfma_f32_16x16x32_bf16 v[44:47], v[100:103], v[172:175], v[44:47]
	v_mfma_f32_16x16x32_bf16 v[36:39], v[156:159], v[172:175], v[36:39]
	v_mfma_f32_16x16x32_bf16 v[28:31], v[100:103], v[180:183], v[28:31]
	v_mfma_f32_16x16x32_bf16 v[20:23], v[156:159], v[180:183], v[20:23]
	v_mfma_f32_16x16x32_bf16 v[12:15], v[100:103], v[188:191], v[12:15]
	v_mfma_f32_16x16x32_bf16 v[4:7], v[156:159], v[188:191], v[4:7]
	s_setprio 0
	s_barrier
	s_add_i32 s58, 0, 0x18000
	s_add_i32 s59, 0, 0x1c000
	v_add_u32_e32 v92, s58, v245
	v_add_u32_e32 v156, s59, v245
	ds_read_b128 v[80:83], v92
	ds_read_b128 v[84:87], v92 offset:1024
	ds_read_b128 v[88:91], v92 offset:2048
	ds_read_b128 v[92:95], v92 offset:3072
	ds_read_b128 v[96:99], v156
	ds_read_b128 v[100:103], v156 offset:1024
	ds_read_b128 v[152:155], v156 offset:2048
	ds_read_b128 v[156:159], v156 offset:3072
	s_add_u32 s30, s30, s4
	s_addc_u32 s31, s31, s5
	s_mov_b32 m0, s39
	v_lshl_add_u64 v[222:223], s[30:31], 0, v[202:203]
	ds_read_b128 v[160:163], v248 offset:32768
	ds_read_b128 v[164:167], v248 offset:33792
	ds_read_b128 v[168:171], v248 offset:34816
	ds_read_b128 v[172:175], v248 offset:35840
	ds_read_b128 v[176:179], v248 offset:36864
	ds_read_b128 v[180:183], v248 offset:37888
	ds_read_b128 v[184:187], v248 offset:38912
	ds_read_b128 v[188:191], v248 offset:39936
	global_load_lds_dwordx4 v[222:223], off
	v_lshl_add_u64 v[222:223], s[30:31], 0, v[206:207]
	s_mov_b32 m0, s40
	s_nop 0
	global_load_lds_dwordx4 v[222:223], off
	s_waitcnt vmcnt(8)
	s_waitcnt lgkmcnt(0)
	s_barrier
	s_setprio 1
	s_waitcnt lgkmcnt(0)
	v_mfma_f32_16x16x32_bf16 v[144:147], v[80:83], v[160:163], v[144:147]
	v_mfma_f32_16x16x32_bf16 v[136:139], v[88:91], v[160:163], v[136:139]
	v_mfma_f32_16x16x32_bf16 v[128:131], v[80:83], v[168:171], v[128:131]
	v_mfma_f32_16x16x32_bf16 v[120:123], v[88:91], v[168:171], v[120:123]
	v_mfma_f32_16x16x32_bf16 v[112:115], v[80:83], v[176:179], v[112:115]
	v_mfma_f32_16x16x32_bf16 v[104:107], v[88:91], v[176:179], v[104:107]
	v_mfma_f32_16x16x32_bf16 v[72:75], v[80:83], v[184:187], v[72:75]
	v_mfma_f32_16x16x32_bf16 v[64:67], v[88:91], v[184:187], v[64:67]
	v_mfma_f32_16x16x32_bf16 v[144:147], v[84:87], v[164:167], v[144:147]
	v_mfma_f32_16x16x32_bf16 v[136:139], v[92:95], v[164:167], v[136:139]
	v_mfma_f32_16x16x32_bf16 v[128:131], v[84:87], v[172:175], v[128:131]
	v_mfma_f32_16x16x32_bf16 v[120:123], v[92:95], v[172:175], v[120:123]
	v_mfma_f32_16x16x32_bf16 v[112:115], v[84:87], v[180:183], v[112:115]
	v_mfma_f32_16x16x32_bf16 v[104:107], v[92:95], v[180:183], v[104:107]
	v_mfma_f32_16x16x32_bf16 v[72:75], v[84:87], v[188:191], v[72:75]
	v_mfma_f32_16x16x32_bf16 v[64:67], v[92:95], v[188:191], v[64:67]
	s_setprio 0
	s_setprio 1
	v_mfma_f32_16x16x32_bf16 v[148:151], v[96:99], v[160:163], v[148:151]
	v_mfma_f32_16x16x32_bf16 v[140:143], v[152:155], v[160:163], v[140:143]
	v_mfma_f32_16x16x32_bf16 v[132:135], v[96:99], v[168:171], v[132:135]
	v_mfma_f32_16x16x32_bf16 v[124:127], v[152:155], v[168:171], v[124:127]
	v_mfma_f32_16x16x32_bf16 v[116:119], v[96:99], v[176:179], v[116:119]
	v_mfma_f32_16x16x32_bf16 v[108:111], v[152:155], v[176:179], v[108:111]
	v_mfma_f32_16x16x32_bf16 v[76:79], v[96:99], v[184:187], v[76:79]
	v_mfma_f32_16x16x32_bf16 v[68:71], v[152:155], v[184:187], v[68:71]
	v_mfma_f32_16x16x32_bf16 v[148:151], v[100:103], v[164:167], v[148:151]
	v_mfma_f32_16x16x32_bf16 v[140:143], v[156:159], v[164:167], v[140:143]
	v_mfma_f32_16x16x32_bf16 v[132:135], v[100:103], v[172:175], v[132:135]
	v_mfma_f32_16x16x32_bf16 v[124:127], v[156:159], v[172:175], v[124:127]
	v_mfma_f32_16x16x32_bf16 v[116:119], v[100:103], v[180:183], v[116:119]
	v_mfma_f32_16x16x32_bf16 v[108:111], v[156:159], v[180:183], v[108:111]
	v_mfma_f32_16x16x32_bf16 v[76:79], v[100:103], v[188:191], v[76:79]
	v_mfma_f32_16x16x32_bf16 v[68:71], v[156:159], v[188:191], v[68:71]
	s_setprio 0
	s_barrier
; #define PG8_STAGE(bufoff, gbase, voff) do { _Pragma("unroll") for (int _i = 0; _i < 2; ++_i) \
;         __builtin_amdgcn_global_load_lds((const unsigned*)((const char*)(gbase) + (voff)[_i]), (PG8_LAS unsigned*)(lds + (bufoff) + ldsw + _i * 8192), 16, 0, 0); } while (0)
; #define PG8_LDA(dst, b, h) do { _Pragma("unroll") for (int m = 0; m < 4; ++m) _Pragma("unroll") for (int k = 0; k < 2; ++k) dst[m][k] = *(const PG8_LAS bf16x8*)(lds + PG8_SA(b, h) + aoff + m * 2048 + k * 1024); } while (0)
; #define PG8_MMA(ai, bj, At, Bt) do { __builtin_amdgcn_s_setprio(1); _Pragma("unroll") for (int m = 0; m < 4; ++m) _Pragma("unroll") for (int n = 0; n < 2; ++n) _Pragma("unroll") for (int k = 0; k < 2; ++k) \
;         acc[ai][bj][m][n] = __builtin_amdgcn_mfma_f32_16x16x32_bf16(Bt[n][k], At[m][k], acc[ai][bj][m][n], 0, 0, 0); __builtin_amdgcn_s_setprio(0); } while (0)
; #define PG8_WAIT_V(n) asm volatile("s_waitcnt vmcnt(" #n ")" ::: "memory")
; #define PG8_WAIT_L(n) asm volatile("s_waitcnt lgkmcnt(" #n ")" ::: "memory")
; #define PG8_BAR __builtin_amdgcn_s_barrier()
; #define PG8_SCHED __builtin_amdgcn_sched_barrier(0)
; template <class Epi, class Sched, bool ALIGN_EPI = false, bool SP2 = false>
; __device__ __forceinline__ void gemm_phase(PG8_LAS unsigned char* lds, const Gemm g, const Sched& S, const Epi& E) {
;     ...
;         for (int t = 0; t < nt; t += 2) {
;     ...
;             PG8_LDA(At, 1, 1); PG8_STAGE(PG8_SB(1, 0), b3, voffB); PG8_STAGE(PG8_SB(1, 1), b3 + hstep, voffB); PG8_STAGE(PG8_SA(1, 0), a3, voffA);
;             PG8_WAIT_V(8); PG8_WAIT_L(0); PG8_BAR; PG8_MMA(1, 0, At, B0); PG8_MMA(1, 1, At, B1); PG8_BAR; PG8_SCHED;
	s_add_i32 s30, s58, s36
	v_lshl_add_u64 v[192:193], v[192:193], 0, s[14:15]
	s_mov_b32 m0, s30
	ds_read_b128 v[160:163], v248 offset:49152
	ds_read_b128 v[164:167], v248 offset:50176
	ds_read_b128 v[168:171], v248 offset:51200
	ds_read_b128 v[172:175], v248 offset:52224
	ds_read_b128 v[176:179], v248 offset:53248
	ds_read_b128 v[180:183], v248 offset:54272
	ds_read_b128 v[184:187], v248 offset:55296
	ds_read_b128 v[188:191], v248 offset:56320
	global_load_lds_dwordx4 v[192:193], off
	v_lshl_add_u64 v[192:193], v[194:195], 0, s[14:15]
	s_add_i32 m0, s30, 0x2000
	s_add_i32 s30, s59, s36
	global_load_lds_dwordx4 v[192:193], off
	v_lshl_add_u64 v[192:193], v[196:197], 0, s[14:15]
	s_mov_b32 m0, s30
	s_nop 0
	global_load_lds_dwordx4 v[192:193], off
	v_lshl_add_u64 v[192:193], v[198:199], 0, s[14:15]
	s_add_i32 m0, s30, 0x2000
	s_nop 0
	global_load_lds_dwordx4 v[192:193], off
	v_lshl_add_u64 v[192:193], v[218:219], 0, s[14:15]
	s_mov_b32 m0, s42
	s_nop 0
	global_load_lds_dwordx4 v[192:193], off
	v_lshl_add_u64 v[192:193], v[220:221], 0, s[14:15]
	s_mov_b32 m0, s43
	s_nop 0
	global_load_lds_dwordx4 v[192:193], off
	s_waitcnt vmcnt(8)
	s_waitcnt lgkmcnt(0)
	s_barrier
	s_setprio 1
	s_waitcnt lgkmcnt(0)
	v_mfma_f32_16x16x32_bf16 v[56:59], v[80:83], v[160:163], v[56:59]
	v_mfma_f32_16x16x32_bf16 v[48:51], v[88:91], v[160:163], v[48:51]
	v_mfma_f32_16x16x32_bf16 v[40:43], v[80:83], v[168:171], v[40:43]
	v_mfma_f32_16x16x32_bf16 v[32:35], v[88:91], v[168:171], v[32:35]
	v_mfma_f32_16x16x32_bf16 v[24:27], v[80:83], v[176:179], v[24:27]
	v_mfma_f32_16x16x32_bf16 v[16:19], v[88:91], v[176:179], v[16:19]
	v_mfma_f32_16x16x32_bf16 v[8:11], v[80:83], v[184:187], v[8:11]
	v_mfma_f32_16x16x32_bf16 v[0:3], v[88:91], v[184:187], v[0:3]
	v_mfma_f32_16x16x32_bf16 v[56:59], v[84:87], v[164:167], v[56:59]
	v_mfma_f32_16x16x32_bf16 v[48:51], v[92:95], v[164:167], v[48:51]
	v_mfma_f32_16x16x32_bf16 v[40:43], v[84:87], v[172:175], v[40:43]
	v_mfma_f32_16x16x32_bf16 v[32:35], v[92:95], v[172:175], v[32:35]
	v_mfma_f32_16x16x32_bf16 v[24:27], v[84:87], v[180:183], v[24:27]
	v_mfma_f32_16x16x32_bf16 v[16:19], v[92:95], v[180:183], v[16:19]
	v_mfma_f32_16x16x32_bf16 v[8:11], v[84:87], v[188:191], v[8:11]
	v_mfma_f32_16x16x32_bf16 v[0:3], v[92:95], v[188:191], v[0:3]
	s_setprio 0
	s_setprio 1
	v_mfma_f32_16x16x32_bf16 v[60:63], v[96:99], v[160:163], v[60:63]
	v_mfma_f32_16x16x32_bf16 v[52:55], v[152:155], v[160:163], v[52:55]
	v_mfma_f32_16x16x32_bf16 v[44:47], v[96:99], v[168:171], v[44:47]
	v_mfma_f32_16x16x32_bf16 v[36:39], v[152:155], v[168:171], v[36:39]
	v_mfma_f32_16x16x32_bf16 v[28:31], v[96:99], v[176:179], v[28:31]
	v_mfma_f32_16x16x32_bf16 v[20:23], v[152:155], v[176:179], v[20:23]
	v_mfma_f32_16x16x32_bf16 v[12:15], v[96:99], v[184:187], v[12:15]
	v_mfma_f32_16x16x32_bf16 v[4:7], v[152:155], v[184:187], v[4:7]
	v_mfma_f32_16x16x32_bf16 v[60:63], v[100:103], v[164:167], v[60:63]
	v_mfma_f32_16x16x32_bf16 v[52:55], v[156:159], v[164:167], v[52:55]
	v_mfma_f32_16x16x32_bf16 v[44:47], v[100:103], v[172:175], v[44:47]
	v_mfma_f32_16x16x32_bf16 v[36:39], v[156:159], v[172:175], v[36:39]
	v_mfma_f32_16x16x32_bf16 v[28:31], v[100:103], v[180:183], v[28:31]
	v_mfma_f32_16x16x32_bf16 v[20:23], v[156:159], v[180:183], v[20:23]
	v_mfma_f32_16x16x32_bf16 v[12:15], v[100:103], v[188:191], v[12:15]
	v_mfma_f32_16x16x32_bf16 v[4:7], v[156:159], v[188:191], v[4:7]
	s_setprio 0
	s_barrier
	s_add_u32 s10, s10, 0x100
	s_addc_u32 s11, s11, 0
	s_add_u32 s55, s55, 0x100
	s_addc_u32 s56, s56, 0
	s_cmp_ge_i32 s57, s44
	s_mov_b32 s30, s57
	s_cbranch_scc1 .LBB0_776

; #define PG8_STAGE(bufoff, gbase, voff) do { _Pragma("unroll") for (int _i = 0; _i < 2; ++_i) \
;         __builtin_amdgcn_global_load_lds((const unsigned*)((const char*)(gbase) + (voff)[_i]), (PG8_LAS unsigned*)(lds + (bufoff) + ldsw + _i * 8192), 16, 0, 0); } while (0)
; #define PG8_LDA(dst, b, h) do { _Pragma("unroll") for (int m = 0; m < 4; ++m) _Pragma("unroll") for (int k = 0; k < 2; ++k) dst[m][k] = *(const PG8_LAS bf16x8*)(lds + PG8_SA(b, h) + aoff + m * 2048 + k * 1024); } while (0)
; #define PG8_LDB(dst, b, h) do { _Pragma("unroll") for (int n = 0; n < 2; ++n) _Pragma("unroll") for (int k = 0; k < 2; ++k) dst[n][k] = *(const PG8_LAS bf16x8*)(lds + PG8_SB(b, h) + boff + n * 2048 + k * 1024); } while (0)
; #define PG8_MMA(ai, bj, At, Bt) do { __builtin_amdgcn_s_setprio(1); _Pragma("unroll") for (int m = 0; m < 4; ++m) _Pragma("unroll") for (int n = 0; n < 2; ++n) _Pragma("unroll") for (int k = 0; k < 2; ++k) \
;         acc[ai][bj][m][n] = __builtin_amdgcn_mfma_f32_16x16x32_bf16(Bt[n][k], At[m][k], acc[ai][bj][m][n], 0, 0, 0); __builtin_amdgcn_s_setprio(0); } while (0)
; #define PG8_WAIT_V(n) asm volatile("s_waitcnt vmcnt(" #n ")" ::: "memory")
; #define PG8_WAIT_L(n) asm volatile("s_waitcnt lgkmcnt(" #n ")" ::: "memory")
; #define PG8_BAR __builtin_amdgcn_s_barrier()
; #define PG8_SCHED __builtin_amdgcn_sched_barrier(0)
; template <class Epi, class Sched, bool ALIGN_EPI = false, bool SP2 = false>
; __device__ __forceinline__ void gemm_phase(PG8_LAS unsigned char* lds, const Gemm g, const Sched& S, const Epi& E) {
;     ...
;             const bool last = (t == nt - 2);
;             const char* a1 = cA + (size_t)(t + 1) * kstep;
;             const char* a2 = last ? nA : cA + (size_t)(t + 2) * kstep; const char* b2 = last ? nB : cB + (size_t)(t + 2) * kstep;
;             const char* a3 = a2 + kstep; const char* b3 = b2 + kstep;
;             if (last && has_next) S.a_ready(nxt);
;             if constexpr (SP2) {
;             PG8_LDB(B0, 0, 0); PG8_LDB(B1, 0, 1); PG8_SCHED; PG8_LDA(At, 0, 0); PG8_STAGE(PG8_SA(1, 1), a1 + hstep, voffA);
;             PG8_WAIT_V(8); PG8_WAIT_L(0); PG8_BAR; PG8_MMA(0, 0, At, B0); PG8_MMA(0, 1, At, B1); PG8_BAR; PG8_SCHED;
;             PG8_LDA(At, 0, 1); PG8_STAGE(PG8_SB(0, 0), b2, voffB); PG8_STAGE(PG8_SB(0, 1), b2 + hstep, voffB); PG8_STAGE(PG8_SA(0, 0), a2, voffA);
.LBB0_838:
	s_andn2_b64 vcc, exec, s[18:19]
	s_cbranch_vccnz .LBB0_841
	s_add_u32 s10, s10, 0x80
	s_addc_u32 s11, s11, 0
	s_add_u32 s57, s34, 0x100
	s_addc_u32 s58, s35, 0
	s_mov_b32 s34, 0
	ds_read_b128 v[80:83], v246
	ds_read_b128 v[84:87], v246 offset:1024
	ds_read_b128 v[88:91], v246 offset:2048
	ds_read_b128 v[92:95], v246 offset:3072
	ds_read_b128 v[96:99], v247
	ds_read_b128 v[100:103], v247 offset:1024
	ds_read_b128 v[152:155], v247 offset:2048
	ds_read_b128 v[156:159], v247 offset:3072
	s_add_i32 s59, s34, 2
	s_add_u32 s60, s10, 0x80
	s_addc_u32 s35, s11, 0
	s_cmp_eq_u32 s49, s34
	s_cselect_b32 s34, s0, s60
	s_cselect_b32 s35, s1, s35
	s_cselect_b32 s61, s31, s58
	s_cselect_b32 s60, s30, s57
	v_lshl_add_u64 v[192:193], s[10:11], 0, v[210:211]
	s_add_i32 m0, s39, 0xc000
	ds_read_b128 v[160:163], v248
	ds_read_b128 v[164:167], v248 offset:1024
	ds_read_b128 v[168:171], v248 offset:2048
	ds_read_b128 v[172:175], v248 offset:3072
	ds_read_b128 v[176:179], v248 offset:4096
	ds_read_b128 v[180:183], v248 offset:5120
	ds_read_b128 v[184:187], v248 offset:6144
	ds_read_b128 v[188:191], v248 offset:7168
	global_load_lds_dwordx4 v[192:193], off
	v_lshl_add_u64 v[192:193], s[10:11], 0, v[212:213]
	s_add_i32 m0, s39, 0xe000
	s_nop 0
	global_load_lds_dwordx4 v[192:193], off
	s_waitcnt vmcnt(8)
	s_waitcnt lgkmcnt(0)
	s_barrier
	s_setprio 1
	s_waitcnt lgkmcnt(0)
	v_mfma_f32_16x16x32_bf16 v[144:147], v[80:83], v[160:163], 0
	v_mfma_f32_16x16x32_bf16 v[136:139], v[88:91], v[160:163], 0
	v_mfma_f32_16x16x32_bf16 v[128:131], v[80:83], v[168:171], 0
	v_mfma_f32_16x16x32_bf16 v[120:123], v[88:91], v[168:171], 0
	v_mfma_f32_16x16x32_bf16 v[112:115], v[80:83], v[176:179], 0
	v_mfma_f32_16x16x32_bf16 v[104:107], v[88:91], v[176:179], 0
	v_mfma_f32_16x16x32_bf16 v[72:75], v[80:83], v[184:187], 0
	v_mfma_f32_16x16x32_bf16 v[64:67], v[88:91], v[184:187], 0
	v_mfma_f32_16x16x32_bf16 v[144:147], v[84:87], v[164:167], v[144:147]
	v_mfma_f32_16x16x32_bf16 v[136:139], v[92:95], v[164:167], v[136:139]
	v_mfma_f32_16x16x32_bf16 v[128:131], v[84:87], v[172:175], v[128:131]
	v_mfma_f32_16x16x32_bf16 v[120:123], v[92:95], v[172:175], v[120:123]
	v_mfma_f32_16x16x32_bf16 v[112:115], v[84:87], v[180:183], v[112:115]
	v_mfma_f32_16x16x32_bf16 v[104:107], v[92:95], v[180:183], v[104:107]
	v_mfma_f32_16x16x32_bf16 v[72:75], v[84:87], v[188:191], v[72:75]
	v_mfma_f32_16x16x32_bf16 v[64:67], v[92:95], v[188:191], v[64:67]
	s_setprio 0
	s_setprio 1
	v_mfma_f32_16x16x32_bf16 v[148:151], v[96:99], v[160:163], 0
	v_mfma_f32_16x16x32_bf16 v[140:143], v[152:155], v[160:163], 0
	v_mfma_f32_16x16x32_bf16 v[132:135], v[96:99], v[168:171], 0
	v_mfma_f32_16x16x32_bf16 v[124:127], v[152:155], v[168:171], 0
	v_mfma_f32_16x16x32_bf16 v[116:119], v[96:99], v[176:179], 0
	v_mfma_f32_16x16x32_bf16 v[108:111], v[152:155], v[176:179], 0
	v_mfma_f32_16x16x32_bf16 v[76:79], v[96:99], v[184:187], 0
	v_mfma_f32_16x16x32_bf16 v[68:71], v[152:155], v[184:187], 0
	v_mfma_f32_16x16x32_bf16 v[148:151], v[100:103], v[164:167], v[148:151]
	v_mfma_f32_16x16x32_bf16 v[140:143], v[156:159], v[164:167], v[140:143]
	v_mfma_f32_16x16x32_bf16 v[132:135], v[100:103], v[172:175], v[132:135]
	v_mfma_f32_16x16x32_bf16 v[124:127], v[156:159], v[172:175], v[124:127]
	v_mfma_f32_16x16x32_bf16 v[116:119], v[100:103], v[180:183], v[116:119]
	v_mfma_f32_16x16x32_bf16 v[108:111], v[156:159], v[180:183], v[108:111]
	v_mfma_f32_16x16x32_bf16 v[76:79], v[100:103], v[188:191], v[76:79]
	v_mfma_f32_16x16x32_bf16 v[68:71], v[156:159], v[188:191], v[68:71]
	s_setprio 0
	s_barrier
	s_add_i32 s62, s52, s38
	v_lshl_add_u64 v[192:193], s[60:61], 0, v[204:205]
	s_mov_b32 m0, s62
	ds_read_b128 v[160:163], v248 offset:16384
	ds_read_b128 v[164:167], v248 offset:17408
	ds_read_b128 v[168:171], v248 offset:18432
	ds_read_b128 v[172:175], v248 offset:19456
	ds_read_b128 v[176:179], v248 offset:20480
	ds_read_b128 v[180:183], v248 offset:21504
	ds_read_b128 v[184:187], v248 offset:22528
	ds_read_b128 v[188:191], v248 offset:23552
	global_load_lds_dwordx4 v[192:193], off
	s_add_i32 m0, s62, 0x2000
	v_lshl_add_u64 v[194:195], s[60:61], 0, v[208:209]
	s_add_u32 s60, s60, s6
	s_addc_u32 s61, s61, s7
	s_add_i32 s62, s53, s38
	global_load_lds_dwordx4 v[194:195], off
	v_lshl_add_u64 v[196:197], s[60:61], 0, v[204:205]
	s_mov_b32 m0, s62
	v_lshl_add_u64 v[198:199], s[60:61], 0, v[208:209]
	global_load_lds_dwordx4 v[196:197], off
	s_add_i32 m0, s62, 0x2000
	v_lshl_add_u64 v[218:219], s[34:35], 0, v[202:203]
	global_load_lds_dwordx4 v[198:199], off
	s_mov_b32 m0, s39
	v_lshl_add_u64 v[220:221], s[34:35], 0, v[206:207]
	global_load_lds_dwordx4 v[218:219], off
	s_mov_b32 m0, s40
	s_nop 0
	global_load_lds_dwordx4 v[220:221], off
	s_waitcnt vmcnt(8)
	s_waitcnt lgkmcnt(0)
	s_barrier
; #define PG8_STAGE(bufoff, gbase, voff) do { _Pragma("unroll") for (int _i = 0; _i < 2; ++_i) \
;         __builtin_amdgcn_global_load_lds((const unsigned*)((const char*)(gbase) + (voff)[_i]), (PG8_LAS unsigned*)(lds + (bufoff) + ldsw + _i * 8192), 16, 0, 0); } while (0)
; #define PG8_LDA(dst, b, h) do { _Pragma("unroll") for (int m = 0; m < 4; ++m) _Pragma("unroll") for (int k = 0; k < 2; ++k) dst[m][k] = *(const PG8_LAS bf16x8*)(lds + PG8_SA(b, h) + aoff + m * 2048 + k * 1024); } while (0)
; #define PG8_LDB(dst, b, h) do { _Pragma("unroll") for (int n = 0; n < 2; ++n) _Pragma("unroll") for (int k = 0; k < 2; ++k) dst[n][k] = *(const PG8_LAS bf16x8*)(lds + PG8_SB(b, h) + boff + n * 2048 + k * 1024); } while (0)
; #define PG8_MMA(ai, bj, At, Bt) do { __builtin_amdgcn_s_setprio(1); _Pragma("unroll") for (int m = 0; m < 4; ++m) _Pragma("unroll") for (int n = 0; n < 2; ++n) _Pragma("unroll") for (int k = 0; k < 2; ++k) \
;         acc[ai][bj][m][n] = __builtin_amdgcn_mfma_f32_16x16x32_bf16(Bt[n][k], At[m][k], acc[ai][bj][m][n], 0, 0, 0); __builtin_amdgcn_s_setprio(0); } while (0)
; #define PG8_WAIT_V(n) asm volatile("s_waitcnt vmcnt(" #n ")" ::: "memory")
; #define PG8_WAIT_L(n) asm volatile("s_waitcnt lgkmcnt(" #n ")" ::: "memory")
; #define PG8_BAR __builtin_amdgcn_s_barrier()
; #define PG8_SCHED __builtin_amdgcn_sched_barrier(0)
; template <class Epi, class Sched, bool ALIGN_EPI = false, bool SP2 = false>
; __device__ __forceinline__ void gemm_phase(PG8_LAS unsigned char* lds, const Gemm g, const Sched& S, const Epi& E) {
;     ...
;             PG8_WAIT_V(8); PG8_WAIT_L(0); PG8_BAR; PG8_MMA(1, 0, At, B0); PG8_MMA(1, 1, At, B1); PG8_BAR; PG8_SCHED;
;             PG8_LDB(B0, 1, 0); PG8_LDB(B1, 1, 1); PG8_SCHED; PG8_LDA(At, 1, 0); PG8_STAGE(PG8_SA(0, 1), a2 + hstep, voffA);
;             PG8_WAIT_V(8); PG8_WAIT_L(0); PG8_BAR; PG8_MMA(0, 0, At, B0); PG8_MMA(0, 1, At, B1); PG8_BAR; PG8_SCHED;
	s_setprio 1
	s_waitcnt lgkmcnt(0)
	v_mfma_f32_16x16x32_bf16 v[56:59], v[80:83], v[160:163], 0
	v_mfma_f32_16x16x32_bf16 v[48:51], v[88:91], v[160:163], 0
	v_mfma_f32_16x16x32_bf16 v[40:43], v[80:83], v[168:171], 0
	v_mfma_f32_16x16x32_bf16 v[32:35], v[88:91], v[168:171], 0
	v_mfma_f32_16x16x32_bf16 v[24:27], v[80:83], v[176:179], 0
	v_mfma_f32_16x16x32_bf16 v[16:19], v[88:91], v[176:179], 0
	v_mfma_f32_16x16x32_bf16 v[8:11], v[80:83], v[184:187], 0
	v_mfma_f32_16x16x32_bf16 v[0:3], v[88:91], v[184:187], 0
	v_mfma_f32_16x16x32_bf16 v[56:59], v[84:87], v[164:167], v[56:59]
	v_mfma_f32_16x16x32_bf16 v[48:51], v[92:95], v[164:167], v[48:51]
	v_mfma_f32_16x16x32_bf16 v[40:43], v[84:87], v[172:175], v[40:43]
	v_mfma_f32_16x16x32_bf16 v[32:35], v[92:95], v[172:175], v[32:35]
	v_mfma_f32_16x16x32_bf16 v[24:27], v[84:87], v[180:183], v[24:27]
	v_mfma_f32_16x16x32_bf16 v[16:19], v[92:95], v[180:183], v[16:19]
	v_mfma_f32_16x16x32_bf16 v[8:11], v[84:87], v[188:191], v[8:11]
	v_mfma_f32_16x16x32_bf16 v[0:3], v[92:95], v[188:191], v[0:3]
	s_setprio 0
	s_setprio 1
	v_mfma_f32_16x16x32_bf16 v[60:63], v[96:99], v[160:163], 0
	v_mfma_f32_16x16x32_bf16 v[52:55], v[152:155], v[160:163], 0
	v_mfma_f32_16x16x32_bf16 v[44:47], v[96:99], v[168:171], 0
	v_mfma_f32_16x16x32_bf16 v[36:39], v[152:155], v[168:171], 0
	v_mfma_f32_16x16x32_bf16 v[28:31], v[96:99], v[176:179], 0
	v_mfma_f32_16x16x32_bf16 v[20:23], v[152:155], v[176:179], 0
	v_mfma_f32_16x16x32_bf16 v[12:15], v[96:99], v[184:187], 0
	v_mfma_f32_16x16x32_bf16 v[4:7], v[152:155], v[184:187], 0
	v_mfma_f32_16x16x32_bf16 v[60:63], v[100:103], v[164:167], v[60:63]
	v_mfma_f32_16x16x32_bf16 v[52:55], v[156:159], v[164:167], v[52:55]
	v_mfma_f32_16x16x32_bf16 v[44:47], v[100:103], v[172:175], v[44:47]
	v_mfma_f32_16x16x32_bf16 v[36:39], v[156:159], v[172:175], v[36:39]
	v_mfma_f32_16x16x32_bf16 v[28:31], v[100:103], v[180:183], v[28:31]
	v_mfma_f32_16x16x32_bf16 v[20:23], v[156:159], v[180:183], v[20:23]
	v_mfma_f32_16x16x32_bf16 v[12:15], v[100:103], v[188:191], v[12:15]
	v_mfma_f32_16x16x32_bf16 v[4:7], v[156:159], v[188:191], v[4:7]
	s_setprio 0
	s_barrier
	s_add_i32 s60, 0, 0x18000
	s_add_i32 s61, 0, 0x1c000
	v_add_u32_e32 v92, s60, v245
	v_add_u32_e32 v156, s61, v245
	ds_read_b128 v[80:83], v92
	ds_read_b128 v[84:87], v92 offset:1024
	ds_read_b128 v[88:91], v92 offset:2048
	ds_read_b128 v[92:95], v92 offset:3072
	ds_read_b128 v[96:99], v156
	ds_read_b128 v[100:103], v156 offset:1024
	ds_read_b128 v[152:155], v156 offset:2048
	ds_read_b128 v[156:159], v156 offset:3072
	s_add_u32 s34, s34, s6
	s_addc_u32 s35, s35, s7
	s_mov_b32 m0, s41
	v_lshl_add_u64 v[222:223], s[34:35], 0, v[202:203]
	ds_read_b128 v[160:163], v248 offset:32768
	ds_read_b128 v[164:167], v248 offset:33792
	ds_read_b128 v[168:171], v248 offset:34816
	ds_read_b128 v[172:175], v248 offset:35840
	ds_read_b128 v[176:179], v248 offset:36864
	ds_read_b128 v[180:183], v248 offset:37888
	ds_read_b128 v[184:187], v248 offset:38912
	ds_read_b128 v[188:191], v248 offset:39936
	global_load_lds_dwordx4 v[222:223], off
	v_lshl_add_u64 v[222:223], s[34:35], 0, v[206:207]
	s_mov_b32 m0, s42
	s_nop 0
	global_load_lds_dwordx4 v[222:223], off
	s_waitcnt vmcnt(8)
	s_waitcnt lgkmcnt(0)
	s_barrier
	s_setprio 1
	s_waitcnt lgkmcnt(0)
	v_mfma_f32_16x16x32_bf16 v[144:147], v[80:83], v[160:163], v[144:147]
	v_mfma_f32_16x16x32_bf16 v[136:139], v[88:91], v[160:163], v[136:139]
	v_mfma_f32_16x16x32_bf16 v[128:131], v[80:83], v[168:171], v[128:131]
	v_mfma_f32_16x16x32_bf16 v[120:123], v[88:91], v[168:171], v[120:123]
	v_mfma_f32_16x16x32_bf16 v[112:115], v[80:83], v[176:179], v[112:115]
	v_mfma_f32_16x16x32_bf16 v[104:107], v[88:91], v[176:179], v[104:107]
	v_mfma_f32_16x16x32_bf16 v[72:75], v[80:83], v[184:187], v[72:75]
	v_mfma_f32_16x16x32_bf16 v[64:67], v[88:91], v[184:187], v[64:67]
	v_mfma_f32_16x16x32_bf16 v[144:147], v[84:87], v[164:167], v[144:147]
	v_mfma_f32_16x16x32_bf16 v[136:139], v[92:95], v[164:167], v[136:139]
	v_mfma_f32_16x16x32_bf16 v[128:131], v[84:87], v[172:175], v[128:131]
	v_mfma_f32_16x16x32_bf16 v[120:123], v[92:95], v[172:175], v[120:123]
	v_mfma_f32_16x16x32_bf16 v[112:115], v[84:87], v[180:183], v[112:115]
	v_mfma_f32_16x16x32_bf16 v[104:107], v[92:95], v[180:183], v[104:107]
	v_mfma_f32_16x16x32_bf16 v[72:75], v[84:87], v[188:191], v[72:75]
	v_mfma_f32_16x16x32_bf16 v[64:67], v[92:95], v[188:191], v[64:67]
	s_setprio 0
	s_setprio 1
	v_mfma_f32_16x16x32_bf16 v[148:151], v[96:99], v[160:163], v[148:151]
	v_mfma_f32_16x16x32_bf16 v[140:143], v[152:155], v[160:163], v[140:143]
	v_mfma_f32_16x16x32_bf16 v[132:135], v[96:99], v[168:171], v[132:135]
	v_mfma_f32_16x16x32_bf16 v[124:127], v[152:155], v[168:171], v[124:127]
	v_mfma_f32_16x16x32_bf16 v[116:119], v[96:99], v[176:179], v[116:119]
	v_mfma_f32_16x16x32_bf16 v[108:111], v[152:155], v[176:179], v[108:111]
	v_mfma_f32_16x16x32_bf16 v[76:79], v[96:99], v[184:187], v[76:79]
	v_mfma_f32_16x16x32_bf16 v[68:71], v[152:155], v[184:187], v[68:71]
	v_mfma_f32_16x16x32_bf16 v[148:151], v[100:103], v[164:167], v[148:151]
	v_mfma_f32_16x16x32_bf16 v[140:143], v[156:159], v[164:167], v[140:143]
	v_mfma_f32_16x16x32_bf16 v[132:135], v[100:103], v[172:175], v[132:135]
	v_mfma_f32_16x16x32_bf16 v[124:127], v[156:159], v[172:175], v[124:127]
	v_mfma_f32_16x16x32_bf16 v[116:119], v[100:103], v[180:183], v[116:119]
	v_mfma_f32_16x16x32_bf16 v[108:111], v[156:159], v[180:183], v[108:111]
	v_mfma_f32_16x16x32_bf16 v[76:79], v[100:103], v[188:191], v[76:79]
	v_mfma_f32_16x16x32_bf16 v[68:71], v[156:159], v[188:191], v[68:71]
	s_setprio 0
	s_barrier
; #define PG8_STAGE(bufoff, gbase, voff) do { _Pragma("unroll") for (int _i = 0; _i < 2; ++_i) \
;         __builtin_amdgcn_global_load_lds((const unsigned*)((const char*)(gbase) + (voff)[_i]), (PG8_LAS unsigned*)(lds + (bufoff) + ldsw + _i * 8192), 16, 0, 0); } while (0)
; #define PG8_LDA(dst, b, h) do { _Pragma("unroll") for (int m = 0; m < 4; ++m) _Pragma("unroll") for (int k = 0; k < 2; ++k) dst[m][k] = *(const PG8_LAS bf16x8*)(lds + PG8_SA(b, h) + aoff + m * 2048 + k * 1024); } while (0)
; #define PG8_MMA(ai, bj, At, Bt) do { __builtin_amdgcn_s_setprio(1); _Pragma("unroll") for (int m = 0; m < 4; ++m) _Pragma("unroll") for (int n = 0; n < 2; ++n) _Pragma("unroll") for (int k = 0; k < 2; ++k) \
;         acc[ai][bj][m][n] = __builtin_amdgcn_mfma_f32_16x16x32_bf16(Bt[n][k], At[m][k], acc[ai][bj][m][n], 0, 0, 0); __builtin_amdgcn_s_setprio(0); } while (0)
; #define PG8_WAIT_V(n) asm volatile("s_waitcnt vmcnt(" #n ")" ::: "memory")
; #define PG8_WAIT_L(n) asm volatile("s_waitcnt lgkmcnt(" #n ")" ::: "memory")
; #define PG8_BAR __builtin_amdgcn_s_barrier()
; #define PG8_SCHED __builtin_amdgcn_sched_barrier(0)
; template <class Epi, class Sched, bool ALIGN_EPI = false, bool SP2 = false>
; __device__ __forceinline__ void gemm_phase(PG8_LAS unsigned char* lds, const Gemm g, const Sched& S, const Epi& E) {
;     ...
;         for (int t = 0; t < nt; t += 2) {
;     ...
;             PG8_LDA(At, 1, 1); PG8_STAGE(PG8_SB(1, 0), b3, voffB); PG8_STAGE(PG8_SB(1, 1), b3 + hstep, voffB); PG8_STAGE(PG8_SA(1, 0), a3, voffA);
;             PG8_WAIT_V(8); PG8_WAIT_L(0); PG8_BAR; PG8_MMA(1, 0, At, B0); PG8_MMA(1, 1, At, B1); PG8_BAR; PG8_SCHED;
	s_add_i32 s34, s60, s38
	v_lshl_add_u64 v[192:193], v[192:193], 0, s[16:17]
	s_mov_b32 m0, s34
	ds_read_b128 v[160:163], v248 offset:49152
	ds_read_b128 v[164:167], v248 offset:50176
	ds_read_b128 v[168:171], v248 offset:51200
	ds_read_b128 v[172:175], v248 offset:52224
	ds_read_b128 v[176:179], v248 offset:53248
	ds_read_b128 v[180:183], v248 offset:54272
	ds_read_b128 v[184:187], v248 offset:55296
	ds_read_b128 v[188:191], v248 offset:56320
	global_load_lds_dwordx4 v[192:193], off
	v_lshl_add_u64 v[192:193], v[194:195], 0, s[16:17]
	s_add_i32 m0, s34, 0x2000
	s_add_i32 s34, s61, s38
	global_load_lds_dwordx4 v[192:193], off
	v_lshl_add_u64 v[192:193], v[196:197], 0, s[16:17]
	s_mov_b32 m0, s34
	s_nop 0
	global_load_lds_dwordx4 v[192:193], off
	v_lshl_add_u64 v[192:193], v[198:199], 0, s[16:17]
	s_add_i32 m0, s34, 0x2000
	s_nop 0
	global_load_lds_dwordx4 v[192:193], off
	v_lshl_add_u64 v[192:193], v[218:219], 0, s[16:17]
	s_mov_b32 m0, s44
	s_nop 0
	global_load_lds_dwordx4 v[192:193], off
	v_lshl_add_u64 v[192:193], v[220:221], 0, s[16:17]
	s_mov_b32 m0, s45
	s_nop 0
	global_load_lds_dwordx4 v[192:193], off
	s_waitcnt vmcnt(8)
	s_waitcnt lgkmcnt(0)
	s_barrier
	s_setprio 1
	s_waitcnt lgkmcnt(0)
	v_mfma_f32_16x16x32_bf16 v[56:59], v[80:83], v[160:163], v[56:59]
	v_mfma_f32_16x16x32_bf16 v[48:51], v[88:91], v[160:163], v[48:51]
	v_mfma_f32_16x16x32_bf16 v[40:43], v[80:83], v[168:171], v[40:43]
	v_mfma_f32_16x16x32_bf16 v[32:35], v[88:91], v[168:171], v[32:35]
	v_mfma_f32_16x16x32_bf16 v[24:27], v[80:83], v[176:179], v[24:27]
	v_mfma_f32_16x16x32_bf16 v[16:19], v[88:91], v[176:179], v[16:19]
	v_mfma_f32_16x16x32_bf16 v[8:11], v[80:83], v[184:187], v[8:11]
	v_mfma_f32_16x16x32_bf16 v[0:3], v[88:91], v[184:187], v[0:3]
	v_mfma_f32_16x16x32_bf16 v[56:59], v[84:87], v[164:167], v[56:59]
	v_mfma_f32_16x16x32_bf16 v[48:51], v[92:95], v[164:167], v[48:51]
	v_mfma_f32_16x16x32_bf16 v[40:43], v[84:87], v[172:175], v[40:43]
	v_mfma_f32_16x16x32_bf16 v[32:35], v[92:95], v[172:175], v[32:35]
	v_mfma_f32_16x16x32_bf16 v[24:27], v[84:87], v[180:183], v[24:27]
	v_mfma_f32_16x16x32_bf16 v[16:19], v[92:95], v[180:183], v[16:19]
	v_mfma_f32_16x16x32_bf16 v[8:11], v[84:87], v[188:191], v[8:11]
	v_mfma_f32_16x16x32_bf16 v[0:3], v[92:95], v[188:191], v[0:3]
	s_setprio 0
	s_setprio 1
	v_mfma_f32_16x16x32_bf16 v[60:63], v[96:99], v[160:163], v[60:63]
	v_mfma_f32_16x16x32_bf16 v[52:55], v[152:155], v[160:163], v[52:55]
	v_mfma_f32_16x16x32_bf16 v[44:47], v[96:99], v[168:171], v[44:47]
	v_mfma_f32_16x16x32_bf16 v[36:39], v[152:155], v[168:171], v[36:39]
	v_mfma_f32_16x16x32_bf16 v[28:31], v[96:99], v[176:179], v[28:31]
	v_mfma_f32_16x16x32_bf16 v[20:23], v[152:155], v[176:179], v[20:23]
	v_mfma_f32_16x16x32_bf16 v[12:15], v[96:99], v[184:187], v[12:15]
	v_mfma_f32_16x16x32_bf16 v[4:7], v[152:155], v[184:187], v[4:7]
	v_mfma_f32_16x16x32_bf16 v[60:63], v[100:103], v[164:167], v[60:63]
	v_mfma_f32_16x16x32_bf16 v[52:55], v[156:159], v[164:167], v[52:55]
	v_mfma_f32_16x16x32_bf16 v[44:47], v[100:103], v[172:175], v[44:47]
	v_mfma_f32_16x16x32_bf16 v[36:39], v[156:159], v[172:175], v[36:39]
	v_mfma_f32_16x16x32_bf16 v[28:31], v[100:103], v[180:183], v[28:31]
	v_mfma_f32_16x16x32_bf16 v[20:23], v[156:159], v[180:183], v[20:23]
	v_mfma_f32_16x16x32_bf16 v[12:15], v[100:103], v[188:191], v[12:15]
	v_mfma_f32_16x16x32_bf16 v[4:7], v[156:159], v[188:191], v[4:7]
	s_setprio 0
	s_barrier
	s_add_u32 s10, s10, 0x100
	s_addc_u32 s11, s11, 0
	s_add_u32 s57, s57, 0x100
	s_addc_u32 s58, s58, 0
	s_cmp_ge_i32 s59, s46
	s_mov_b32 s34, s59
	s_cbranch_scc1 .LBB0_841

; #define PG8_STAGE(bufoff, gbase, voff) do { _Pragma("unroll") for (int _i = 0; _i < 2; ++_i) \
;         __builtin_amdgcn_global_load_lds((const unsigned*)((const char*)(gbase) + (voff)[_i]), (PG8_LAS unsigned*)(lds + (bufoff) + ldsw + _i * 8192), 16, 0, 0); } while (0)
; #define PG8_LDA(dst, b, h) do { _Pragma("unroll") for (int m = 0; m < 4; ++m) _Pragma("unroll") for (int k = 0; k < 2; ++k) dst[m][k] = *(const PG8_LAS bf16x8*)(lds + PG8_SA(b, h) + aoff + m * 2048 + k * 1024); } while (0)
; #define PG8_LDB(dst, b, h) do { _Pragma("unroll") for (int n = 0; n < 2; ++n) _Pragma("unroll") for (int k = 0; k < 2; ++k) dst[n][k] = *(const PG8_LAS bf16x8*)(lds + PG8_SB(b, h) + boff + n * 2048 + k * 1024); } while (0)
; #define PG8_MMA(ai, bj, At, Bt) do { __builtin_amdgcn_s_setprio(1); _Pragma("unroll") for (int m = 0; m < 4; ++m) _Pragma("unroll") for (int n = 0; n < 2; ++n) _Pragma("unroll") for (int k = 0; k < 2; ++k) \
;         acc[ai][bj][m][n] = __builtin_amdgcn_mfma_f32_16x16x32_bf16(Bt[n][k], At[m][k], acc[ai][bj][m][n], 0, 0, 0); __builtin_amdgcn_s_setprio(0); } while (0)
; #define PG8_WAIT_V(n) asm volatile("s_waitcnt vmcnt(" #n ")" ::: "memory")
; #define PG8_WAIT_L(n) asm volatile("s_waitcnt lgkmcnt(" #n ")" ::: "memory")
; #define PG8_BAR __builtin_amdgcn_s_barrier()
; #define PG8_SCHED __builtin_amdgcn_sched_barrier(0)
; template <class Epi, class Sched, bool ALIGN_EPI = false, bool SP2 = false>
; __device__ __forceinline__ void gemm_phase(PG8_LAS unsigned char* lds, const Gemm g, const Sched& S, const Epi& E) {
;     ...
;             const bool last = (t == nt - 2);
;             const char* a1 = cA + (size_t)(t + 1) * kstep;
;             const char* a2 = last ? nA : cA + (size_t)(t + 2) * kstep; const char* b2 = last ? nB : cB + (size_t)(t + 2) * kstep;
;             const char* a3 = a2 + kstep; const char* b3 = b2 + kstep;
;             if (last && has_next) S.a_ready(nxt);
;             if constexpr (SP2) {
;             PG8_LDB(B0, 0, 0); PG8_LDB(B1, 0, 1); PG8_SCHED; PG8_LDA(At, 0, 0); PG8_STAGE(PG8_SA(1, 1), a1 + hstep, voffA);
;             PG8_WAIT_V(8); PG8_WAIT_L(0); PG8_BAR; PG8_MMA(0, 0, At, B0); PG8_MMA(0, 1, At, B1); PG8_BAR; PG8_SCHED;
;             PG8_LDA(At, 0, 1); PG8_STAGE(PG8_SB(0, 0), b2, voffB); PG8_STAGE(PG8_SB(0, 1), b2 + hstep, voffB); PG8_STAGE(PG8_SA(0, 0), a2, voffA);
.LBB0_901:
	s_andn2_b64 vcc, exec, s[16:17]
	s_cbranch_vccnz .LBB0_904
	s_add_u32 s4, s4, 0x80
	s_addc_u32 s5, s5, 0
	s_add_u32 s56, s28, 0x100
	s_addc_u32 s57, s29, 0
	s_mov_b32 s28, 0
	ds_read_b128 v[146:149], v169
	ds_read_b128 v[150:153], v169 offset:1024
	ds_read_b128 v[154:157], v169 offset:2048
	ds_read_b128 v[158:161], v169 offset:3072
	ds_read_b128 v[162:165], v170
	ds_read_b128 v[174:177], v170 offset:1024
	ds_read_b128 v[178:181], v170 offset:2048
	ds_read_b128 v[182:185], v170 offset:3072
	s_add_i32 s58, s28, 2
	s_add_u32 s59, s4, 0x80
	s_addc_u32 s29, s5, 0
	s_cmp_eq_u32 s47, s28
	s_cselect_b32 s28, s0, s59
	s_cselect_b32 s29, s1, s29
	s_cselect_b32 s61, s27, s57
	s_cselect_b32 s60, s26, s56
	v_lshl_add_u64 v[166:167], s[4:5], 0, v[138:139]
	s_add_i32 m0, s38, 0xc000
	ds_read_b128 v[186:189], v171
	ds_read_b128 v[190:193], v171 offset:1024
	ds_read_b128 v[194:197], v171 offset:2048
	ds_read_b128 v[202:205], v171 offset:3072
	ds_read_b128 v[206:209], v171 offset:4096
	ds_read_b128 v[210:213], v171 offset:5120
	ds_read_b128 v[214:217], v171 offset:6144
	ds_read_b128 v[218:221], v171 offset:7168
	global_load_lds_dwordx4 v[166:167], off
	v_lshl_add_u64 v[166:167], s[4:5], 0, v[140:141]
	s_add_i32 m0, s38, 0xe000
	s_nop 0
	global_load_lds_dwordx4 v[166:167], off
	s_waitcnt vmcnt(8)
	s_waitcnt lgkmcnt(0)
	s_barrier
	s_setprio 1
	s_waitcnt lgkmcnt(0)
	v_mfma_f32_16x16x32_bf16 v[120:123], v[146:149], v[186:189], 0
	v_mfma_f32_16x16x32_bf16 v[124:127], v[154:157], v[186:189], 0
	v_mfma_f32_16x16x32_bf16 v[108:111], v[146:149], v[194:197], 0
	v_mfma_f32_16x16x32_bf16 v[104:107], v[154:157], v[194:197], 0
	v_mfma_f32_16x16x32_bf16 v[92:95], v[146:149], v[206:209], 0
	v_mfma_f32_16x16x32_bf16 v[88:91], v[154:157], v[206:209], 0
	v_mfma_f32_16x16x32_bf16 v[76:79], v[146:149], v[214:217], 0
	v_mfma_f32_16x16x32_bf16 v[72:75], v[154:157], v[214:217], 0
	v_mfma_f32_16x16x32_bf16 v[120:123], v[150:153], v[190:193], v[120:123]
	v_mfma_f32_16x16x32_bf16 v[124:127], v[158:161], v[190:193], v[124:127]
	v_mfma_f32_16x16x32_bf16 v[108:111], v[150:153], v[202:205], v[108:111]
	v_mfma_f32_16x16x32_bf16 v[104:107], v[158:161], v[202:205], v[104:107]
	v_mfma_f32_16x16x32_bf16 v[92:95], v[150:153], v[210:213], v[92:95]
	v_mfma_f32_16x16x32_bf16 v[88:91], v[158:161], v[210:213], v[88:91]
	v_mfma_f32_16x16x32_bf16 v[76:79], v[150:153], v[218:221], v[76:79]
	v_mfma_f32_16x16x32_bf16 v[72:75], v[158:161], v[218:221], v[72:75]
	s_setprio 0
	s_setprio 1
	v_mfma_f32_16x16x32_bf16 v[116:119], v[162:165], v[186:189], 0
	v_mfma_f32_16x16x32_bf16 v[112:115], v[178:181], v[186:189], 0
	v_mfma_f32_16x16x32_bf16 v[100:103], v[162:165], v[194:197], 0
	v_mfma_f32_16x16x32_bf16 v[96:99], v[178:181], v[194:197], 0
	v_mfma_f32_16x16x32_bf16 v[84:87], v[162:165], v[206:209], 0
	v_mfma_f32_16x16x32_bf16 v[80:83], v[178:181], v[206:209], 0
	v_mfma_f32_16x16x32_bf16 v[68:71], v[162:165], v[214:217], 0
	v_mfma_f32_16x16x32_bf16 v[64:67], v[178:181], v[214:217], 0
	v_mfma_f32_16x16x32_bf16 v[116:119], v[174:177], v[190:193], v[116:119]
	v_mfma_f32_16x16x32_bf16 v[112:115], v[182:185], v[190:193], v[112:115]
	v_mfma_f32_16x16x32_bf16 v[100:103], v[174:177], v[202:205], v[100:103]
	v_mfma_f32_16x16x32_bf16 v[96:99], v[182:185], v[202:205], v[96:99]
	v_mfma_f32_16x16x32_bf16 v[84:87], v[174:177], v[210:213], v[84:87]
	v_mfma_f32_16x16x32_bf16 v[80:83], v[182:185], v[210:213], v[80:83]
	v_mfma_f32_16x16x32_bf16 v[68:71], v[174:177], v[218:221], v[68:71]
	v_mfma_f32_16x16x32_bf16 v[64:67], v[182:185], v[218:221], v[64:67]
	s_setprio 0
	s_barrier
	s_add_i32 s59, s51, s37
	v_lshl_add_u64 v[166:167], s[60:61], 0, v[130:131]
	s_mov_b32 m0, s59
	ds_read_b128 v[186:189], v171 offset:16384
	ds_read_b128 v[190:193], v171 offset:17408
	ds_read_b128 v[194:197], v171 offset:18432
	ds_read_b128 v[202:205], v171 offset:19456
	ds_read_b128 v[206:209], v171 offset:20480
	ds_read_b128 v[210:213], v171 offset:21504
	ds_read_b128 v[214:217], v171 offset:22528
	ds_read_b128 v[218:221], v171 offset:23552
	global_load_lds_dwordx4 v[166:167], off
	s_add_i32 m0, s59, 0x2000
	v_lshl_add_u64 v[198:199], s[60:61], 0, v[134:135]
	s_add_u32 s60, s60, s6
	s_addc_u32 s61, s61, s7
	s_add_i32 s59, s52, s37
	global_load_lds_dwordx4 v[198:199], off
	v_lshl_add_u64 v[222:223], s[60:61], 0, v[130:131]
	s_mov_b32 m0, s59
	v_lshl_add_u64 v[224:225], s[60:61], 0, v[134:135]
	global_load_lds_dwordx4 v[222:223], off
	s_add_i32 m0, s59, 0x2000
	v_lshl_add_u64 v[226:227], s[28:29], 0, v[128:129]
	global_load_lds_dwordx4 v[224:225], off
	s_mov_b32 m0, s38
	v_lshl_add_u64 v[228:229], s[28:29], 0, v[132:133]
	global_load_lds_dwordx4 v[226:227], off
	s_mov_b32 m0, s39
	s_nop 0
	global_load_lds_dwordx4 v[228:229], off
	s_waitcnt vmcnt(8)
	s_waitcnt lgkmcnt(0)
	s_barrier
; #define PG8_STAGE(bufoff, gbase, voff) do { _Pragma("unroll") for (int _i = 0; _i < 2; ++_i) \
;         __builtin_amdgcn_global_load_lds((const unsigned*)((const char*)(gbase) + (voff)[_i]), (PG8_LAS unsigned*)(lds + (bufoff) + ldsw + _i * 8192), 16, 0, 0); } while (0)
; #define PG8_LDA(dst, b, h) do { _Pragma("unroll") for (int m = 0; m < 4; ++m) _Pragma("unroll") for (int k = 0; k < 2; ++k) dst[m][k] = *(const PG8_LAS bf16x8*)(lds + PG8_SA(b, h) + aoff + m * 2048 + k * 1024); } while (0)
; #define PG8_LDB(dst, b, h) do { _Pragma("unroll") for (int n = 0; n < 2; ++n) _Pragma("unroll") for (int k = 0; k < 2; ++k) dst[n][k] = *(const PG8_LAS bf16x8*)(lds + PG8_SB(b, h) + boff + n * 2048 + k * 1024); } while (0)
; #define PG8_MMA(ai, bj, At, Bt) do { __builtin_amdgcn_s_setprio(1); _Pragma("unroll") for (int m = 0; m < 4; ++m) _Pragma("unroll") for (int n = 0; n < 2; ++n) _Pragma("unroll") for (int k = 0; k < 2; ++k) \
;         acc[ai][bj][m][n] = __builtin_amdgcn_mfma_f32_16x16x32_bf16(Bt[n][k], At[m][k], acc[ai][bj][m][n], 0, 0, 0); __builtin_amdgcn_s_setprio(0); } while (0)
; #define PG8_WAIT_V(n) asm volatile("s_waitcnt vmcnt(" #n ")" ::: "memory")
; #define PG8_WAIT_L(n) asm volatile("s_waitcnt lgkmcnt(" #n ")" ::: "memory")
; #define PG8_BAR __builtin_amdgcn_s_barrier()
; #define PG8_SCHED __builtin_amdgcn_sched_barrier(0)
; template <class Epi, class Sched, bool ALIGN_EPI = false, bool SP2 = false>
; __device__ __forceinline__ void gemm_phase(PG8_LAS unsigned char* lds, const Gemm g, const Sched& S, const Epi& E) {
;     ...
;             PG8_WAIT_V(8); PG8_WAIT_L(0); PG8_BAR; PG8_MMA(1, 0, At, B0); PG8_MMA(1, 1, At, B1); PG8_BAR; PG8_SCHED;
;             PG8_LDB(B0, 1, 0); PG8_LDB(B1, 1, 1); PG8_SCHED; PG8_LDA(At, 1, 0); PG8_STAGE(PG8_SA(0, 1), a2 + hstep, voffA);
;             PG8_WAIT_V(8); PG8_WAIT_L(0); PG8_BAR; PG8_MMA(0, 0, At, B0); PG8_MMA(0, 1, At, B1); PG8_BAR; PG8_SCHED;
	s_setprio 1
	s_waitcnt lgkmcnt(0)
	v_mfma_f32_16x16x32_bf16 v[60:63], v[146:149], v[186:189], 0
	v_mfma_f32_16x16x32_bf16 v[56:59], v[154:157], v[186:189], 0
	v_mfma_f32_16x16x32_bf16 v[44:47], v[146:149], v[194:197], 0
	v_mfma_f32_16x16x32_bf16 v[40:43], v[154:157], v[194:197], 0
	v_mfma_f32_16x16x32_bf16 v[28:31], v[146:149], v[206:209], 0
	v_mfma_f32_16x16x32_bf16 v[24:27], v[154:157], v[206:209], 0
	v_mfma_f32_16x16x32_bf16 v[12:15], v[146:149], v[214:217], 0
	v_mfma_f32_16x16x32_bf16 v[8:11], v[154:157], v[214:217], 0
	v_mfma_f32_16x16x32_bf16 v[60:63], v[150:153], v[190:193], v[60:63]
	v_mfma_f32_16x16x32_bf16 v[56:59], v[158:161], v[190:193], v[56:59]
	v_mfma_f32_16x16x32_bf16 v[44:47], v[150:153], v[202:205], v[44:47]
	v_mfma_f32_16x16x32_bf16 v[40:43], v[158:161], v[202:205], v[40:43]
	v_mfma_f32_16x16x32_bf16 v[28:31], v[150:153], v[210:213], v[28:31]
	v_mfma_f32_16x16x32_bf16 v[24:27], v[158:161], v[210:213], v[24:27]
	v_mfma_f32_16x16x32_bf16 v[12:15], v[150:153], v[218:221], v[12:15]
	v_mfma_f32_16x16x32_bf16 v[8:11], v[158:161], v[218:221], v[8:11]
	s_setprio 0
	s_setprio 1
	v_mfma_f32_16x16x32_bf16 v[52:55], v[162:165], v[186:189], 0
	v_mfma_f32_16x16x32_bf16 v[48:51], v[178:181], v[186:189], 0
	v_mfma_f32_16x16x32_bf16 v[36:39], v[162:165], v[194:197], 0
	v_mfma_f32_16x16x32_bf16 v[32:35], v[178:181], v[194:197], 0
	v_mfma_f32_16x16x32_bf16 v[20:23], v[162:165], v[206:209], 0
	v_mfma_f32_16x16x32_bf16 v[16:19], v[178:181], v[206:209], 0
	v_mfma_f32_16x16x32_bf16 v[0:3], v[162:165], v[214:217], 0
	v_mfma_f32_16x16x32_bf16 v[4:7], v[178:181], v[214:217], 0
	v_mfma_f32_16x16x32_bf16 v[52:55], v[174:177], v[190:193], v[52:55]
	v_mfma_f32_16x16x32_bf16 v[48:51], v[182:185], v[190:193], v[48:51]
	v_mfma_f32_16x16x32_bf16 v[36:39], v[174:177], v[202:205], v[36:39]
	v_mfma_f32_16x16x32_bf16 v[32:35], v[182:185], v[202:205], v[32:35]
	v_mfma_f32_16x16x32_bf16 v[20:23], v[174:177], v[210:213], v[20:23]
	v_mfma_f32_16x16x32_bf16 v[16:19], v[182:185], v[210:213], v[16:19]
	v_mfma_f32_16x16x32_bf16 v[0:3], v[174:177], v[218:221], v[0:3]
	v_mfma_f32_16x16x32_bf16 v[4:7], v[182:185], v[218:221], v[4:7]
	s_setprio 0
	s_barrier
	s_add_i32 s59, 0, 0x18000
	v_add_u32_e32 v136, s59, v168
	s_add_i32 s60, 0, 0x1c000
	ds_read_b128 v[146:149], v136
	ds_read_b128 v[150:153], v136 offset:1024
	ds_read_b128 v[154:157], v136 offset:2048
	ds_read_b128 v[158:161], v136 offset:3072
	v_add_u32_e32 v136, s60, v168
	ds_read_b128 v[162:165], v136
	ds_read_b128 v[174:177], v136 offset:1024
	ds_read_b128 v[178:181], v136 offset:2048
	ds_read_b128 v[182:185], v136 offset:3072
	s_add_u32 s28, s28, s6
	s_addc_u32 s29, s29, s7
	s_mov_b32 m0, s40
	v_lshl_add_u64 v[230:231], s[28:29], 0, v[128:129]
	ds_read_b128 v[186:189], v171 offset:32768
	ds_read_b128 v[190:193], v171 offset:33792
	ds_read_b128 v[194:197], v171 offset:34816
	ds_read_b128 v[202:205], v171 offset:35840
	ds_read_b128 v[206:209], v171 offset:36864
	ds_read_b128 v[210:213], v171 offset:37888
	ds_read_b128 v[214:217], v171 offset:38912
	ds_read_b128 v[218:221], v171 offset:39936
	global_load_lds_dwordx4 v[230:231], off
	v_lshl_add_u64 v[230:231], s[28:29], 0, v[132:133]
	s_mov_b32 m0, s41
	s_nop 0
	global_load_lds_dwordx4 v[230:231], off
	s_waitcnt vmcnt(8)
	s_waitcnt lgkmcnt(0)
	s_barrier
	s_setprio 1
	s_waitcnt lgkmcnt(0)
	v_mfma_f32_16x16x32_bf16 v[120:123], v[146:149], v[186:189], v[120:123]
	v_mfma_f32_16x16x32_bf16 v[124:127], v[154:157], v[186:189], v[124:127]
	v_mfma_f32_16x16x32_bf16 v[108:111], v[146:149], v[194:197], v[108:111]
	v_mfma_f32_16x16x32_bf16 v[104:107], v[154:157], v[194:197], v[104:107]
	v_mfma_f32_16x16x32_bf16 v[92:95], v[146:149], v[206:209], v[92:95]
	v_mfma_f32_16x16x32_bf16 v[88:91], v[154:157], v[206:209], v[88:91]
	v_mfma_f32_16x16x32_bf16 v[76:79], v[146:149], v[214:217], v[76:79]
	v_mfma_f32_16x16x32_bf16 v[72:75], v[154:157], v[214:217], v[72:75]
	v_mfma_f32_16x16x32_bf16 v[120:123], v[150:153], v[190:193], v[120:123]
	v_mfma_f32_16x16x32_bf16 v[124:127], v[158:161], v[190:193], v[124:127]
	v_mfma_f32_16x16x32_bf16 v[108:111], v[150:153], v[202:205], v[108:111]
	v_mfma_f32_16x16x32_bf16 v[104:107], v[158:161], v[202:205], v[104:107]
	v_mfma_f32_16x16x32_bf16 v[92:95], v[150:153], v[210:213], v[92:95]
	v_mfma_f32_16x16x32_bf16 v[88:91], v[158:161], v[210:213], v[88:91]
	v_mfma_f32_16x16x32_bf16 v[76:79], v[150:153], v[218:221], v[76:79]
	v_mfma_f32_16x16x32_bf16 v[72:75], v[158:161], v[218:221], v[72:75]
	s_setprio 0
	s_setprio 1
	v_mfma_f32_16x16x32_bf16 v[116:119], v[162:165], v[186:189], v[116:119]
	v_mfma_f32_16x16x32_bf16 v[112:115], v[178:181], v[186:189], v[112:115]
	v_mfma_f32_16x16x32_bf16 v[100:103], v[162:165], v[194:197], v[100:103]
	v_mfma_f32_16x16x32_bf16 v[96:99], v[178:181], v[194:197], v[96:99]
	v_mfma_f32_16x16x32_bf16 v[84:87], v[162:165], v[206:209], v[84:87]
	v_mfma_f32_16x16x32_bf16 v[80:83], v[178:181], v[206:209], v[80:83]
	v_mfma_f32_16x16x32_bf16 v[68:71], v[162:165], v[214:217], v[68:71]
	v_mfma_f32_16x16x32_bf16 v[64:67], v[178:181], v[214:217], v[64:67]
	v_mfma_f32_16x16x32_bf16 v[116:119], v[174:177], v[190:193], v[116:119]
	v_mfma_f32_16x16x32_bf16 v[112:115], v[182:185], v[190:193], v[112:115]
	v_mfma_f32_16x16x32_bf16 v[100:103], v[174:177], v[202:205], v[100:103]
	v_mfma_f32_16x16x32_bf16 v[96:99], v[182:185], v[202:205], v[96:99]
	v_mfma_f32_16x16x32_bf16 v[84:87], v[174:177], v[210:213], v[84:87]
	v_mfma_f32_16x16x32_bf16 v[80:83], v[182:185], v[210:213], v[80:83]
	v_mfma_f32_16x16x32_bf16 v[68:71], v[174:177], v[218:221], v[68:71]
	v_mfma_f32_16x16x32_bf16 v[64:67], v[182:185], v[218:221], v[64:67]
	s_setprio 0
	s_barrier
; #define PG8_STAGE(bufoff, gbase, voff) do { _Pragma("unroll") for (int _i = 0; _i < 2; ++_i) \
;         __builtin_amdgcn_global_load_lds((const unsigned*)((const char*)(gbase) + (voff)[_i]), (PG8_LAS unsigned*)(lds + (bufoff) + ldsw + _i * 8192), 16, 0, 0); } while (0)
; #define PG8_LDA(dst, b, h) do { _Pragma("unroll") for (int m = 0; m < 4; ++m) _Pragma("unroll") for (int k = 0; k < 2; ++k) dst[m][k] = *(const PG8_LAS bf16x8*)(lds + PG8_SA(b, h) + aoff + m * 2048 + k * 1024); } while (0)
; #define PG8_MMA(ai, bj, At, Bt) do { __builtin_amdgcn_s_setprio(1); _Pragma("unroll") for (int m = 0; m < 4; ++m) _Pragma("unroll") for (int n = 0; n < 2; ++n) _Pragma("unroll") for (int k = 0; k < 2; ++k) \
;         acc[ai][bj][m][n] = __builtin_amdgcn_mfma_f32_16x16x32_bf16(Bt[n][k], At[m][k], acc[ai][bj][m][n], 0, 0, 0); __builtin_amdgcn_s_setprio(0); } while (0)
; #define PG8_WAIT_V(n) asm volatile("s_waitcnt vmcnt(" #n ")" ::: "memory")
; #define PG8_WAIT_L(n) asm volatile("s_waitcnt lgkmcnt(" #n ")" ::: "memory")
; #define PG8_BAR __builtin_amdgcn_s_barrier()
; #define PG8_SCHED __builtin_amdgcn_sched_barrier(0)
; template <class Epi, class Sched, bool ALIGN_EPI = false, bool SP2 = false>
; __device__ __forceinline__ void gemm_phase(PG8_LAS unsigned char* lds, const Gemm g, const Sched& S, const Epi& E) {
;     ...
;         for (int t = 0; t < nt; t += 2) {
;     ...
;             PG8_LDA(At, 1, 1); PG8_STAGE(PG8_SB(1, 0), b3, voffB); PG8_STAGE(PG8_SB(1, 1), b3 + hstep, voffB); PG8_STAGE(PG8_SA(1, 0), a3, voffA);
;             PG8_WAIT_V(8); PG8_WAIT_L(0); PG8_BAR; PG8_MMA(1, 0, At, B0); PG8_MMA(1, 1, At, B1); PG8_BAR; PG8_SCHED;
	s_add_i32 s28, s59, s37
	v_lshl_add_u64 v[166:167], v[166:167], 0, s[14:15]
	s_mov_b32 m0, s28
	ds_read_b128 v[186:189], v171 offset:49152
	ds_read_b128 v[190:193], v171 offset:50176
	ds_read_b128 v[194:197], v171 offset:51200
	ds_read_b128 v[202:205], v171 offset:52224
	ds_read_b128 v[206:209], v171 offset:53248
	ds_read_b128 v[210:213], v171 offset:54272
	ds_read_b128 v[214:217], v171 offset:55296
	ds_read_b128 v[218:221], v171 offset:56320
	global_load_lds_dwordx4 v[166:167], off
	v_lshl_add_u64 v[166:167], v[198:199], 0, s[14:15]
	s_add_i32 m0, s28, 0x2000
	s_add_i32 s28, s60, s37
	global_load_lds_dwordx4 v[166:167], off
	v_lshl_add_u64 v[166:167], v[222:223], 0, s[14:15]
	s_mov_b32 m0, s28
	s_nop 0
	global_load_lds_dwordx4 v[166:167], off
	v_lshl_add_u64 v[166:167], v[224:225], 0, s[14:15]
	s_add_i32 m0, s28, 0x2000
	s_nop 0
	global_load_lds_dwordx4 v[166:167], off
	v_lshl_add_u64 v[166:167], v[226:227], 0, s[14:15]
	s_mov_b32 m0, s43
	s_nop 0
	global_load_lds_dwordx4 v[166:167], off
	v_lshl_add_u64 v[166:167], v[228:229], 0, s[14:15]
	s_mov_b32 m0, s44
	s_nop 0
	global_load_lds_dwordx4 v[166:167], off
	s_waitcnt vmcnt(8)
	s_waitcnt lgkmcnt(0)
	s_barrier
	s_setprio 1
	s_waitcnt lgkmcnt(0)
	v_mfma_f32_16x16x32_bf16 v[60:63], v[146:149], v[186:189], v[60:63]
	v_mfma_f32_16x16x32_bf16 v[56:59], v[154:157], v[186:189], v[56:59]
	v_mfma_f32_16x16x32_bf16 v[44:47], v[146:149], v[194:197], v[44:47]
	v_mfma_f32_16x16x32_bf16 v[40:43], v[154:157], v[194:197], v[40:43]
	v_mfma_f32_16x16x32_bf16 v[28:31], v[146:149], v[206:209], v[28:31]
	v_mfma_f32_16x16x32_bf16 v[24:27], v[154:157], v[206:209], v[24:27]
	v_mfma_f32_16x16x32_bf16 v[12:15], v[146:149], v[214:217], v[12:15]
	v_mfma_f32_16x16x32_bf16 v[8:11], v[154:157], v[214:217], v[8:11]
	v_mfma_f32_16x16x32_bf16 v[60:63], v[150:153], v[190:193], v[60:63]
	v_mfma_f32_16x16x32_bf16 v[56:59], v[158:161], v[190:193], v[56:59]
	v_mfma_f32_16x16x32_bf16 v[44:47], v[150:153], v[202:205], v[44:47]
	v_mfma_f32_16x16x32_bf16 v[40:43], v[158:161], v[202:205], v[40:43]
	v_mfma_f32_16x16x32_bf16 v[28:31], v[150:153], v[210:213], v[28:31]
	v_mfma_f32_16x16x32_bf16 v[24:27], v[158:161], v[210:213], v[24:27]
	v_mfma_f32_16x16x32_bf16 v[12:15], v[150:153], v[218:221], v[12:15]
	v_mfma_f32_16x16x32_bf16 v[8:11], v[158:161], v[218:221], v[8:11]
	s_setprio 0
	s_setprio 1
	v_mfma_f32_16x16x32_bf16 v[52:55], v[162:165], v[186:189], v[52:55]
	v_mfma_f32_16x16x32_bf16 v[48:51], v[178:181], v[186:189], v[48:51]
	v_mfma_f32_16x16x32_bf16 v[36:39], v[162:165], v[194:197], v[36:39]
	v_mfma_f32_16x16x32_bf16 v[32:35], v[178:181], v[194:197], v[32:35]
	v_mfma_f32_16x16x32_bf16 v[20:23], v[162:165], v[206:209], v[20:23]
	v_mfma_f32_16x16x32_bf16 v[16:19], v[178:181], v[206:209], v[16:19]
	v_mfma_f32_16x16x32_bf16 v[0:3], v[162:165], v[214:217], v[0:3]
	v_mfma_f32_16x16x32_bf16 v[4:7], v[178:181], v[214:217], v[4:7]
	v_mfma_f32_16x16x32_bf16 v[52:55], v[174:177], v[190:193], v[52:55]
	v_mfma_f32_16x16x32_bf16 v[48:51], v[182:185], v[190:193], v[48:51]
	v_mfma_f32_16x16x32_bf16 v[36:39], v[174:177], v[202:205], v[36:39]
	v_mfma_f32_16x16x32_bf16 v[32:35], v[182:185], v[202:205], v[32:35]
	v_mfma_f32_16x16x32_bf16 v[20:23], v[174:177], v[210:213], v[20:23]
	v_mfma_f32_16x16x32_bf16 v[16:19], v[182:185], v[210:213], v[16:19]
	v_mfma_f32_16x16x32_bf16 v[0:3], v[174:177], v[218:221], v[0:3]
	v_mfma_f32_16x16x32_bf16 v[4:7], v[182:185], v[218:221], v[4:7]
	s_setprio 0
	s_barrier
	s_add_u32 s4, s4, 0x100
	s_addc_u32 s5, s5, 0
	s_add_u32 s56, s56, 0x100
	s_addc_u32 s57, s57, 0
	s_cmp_ge_i32 s58, s45
	s_mov_b32 s28, s58
	s_cbranch_scc1 .LBB0_904

; #define PG8_STAGE(bufoff, gbase, voff) do { _Pragma("unroll") for (int _i = 0; _i < 2; ++_i) \
;         __builtin_amdgcn_global_load_lds((const unsigned*)((const char*)(gbase) + (voff)[_i]), (PG8_LAS unsigned*)(lds + (bufoff) + ldsw + _i * 8192), 16, 0, 0); } while (0)
; #define PG8_LDA(dst, b, h) do { _Pragma("unroll") for (int m = 0; m < 4; ++m) _Pragma("unroll") for (int k = 0; k < 2; ++k) dst[m][k] = *(const PG8_LAS bf16x8*)(lds + PG8_SA(b, h) + aoff + m * 2048 + k * 1024); } while (0)
; #define PG8_LDB(dst, b, h) do { _Pragma("unroll") for (int n = 0; n < 2; ++n) _Pragma("unroll") for (int k = 0; k < 2; ++k) dst[n][k] = *(const PG8_LAS bf16x8*)(lds + PG8_SB(b, h) + boff + n * 2048 + k * 1024); } while (0)
; #define PG8_MMA(ai, bj, At, Bt) do { __builtin_amdgcn_s_setprio(1); _Pragma("unroll") for (int m = 0; m < 4; ++m) _Pragma("unroll") for (int n = 0; n < 2; ++n) _Pragma("unroll") for (int k = 0; k < 2; ++k) \
;         acc[ai][bj][m][n] = __builtin_amdgcn_mfma_f32_16x16x32_bf16(Bt[n][k], At[m][k], acc[ai][bj][m][n], 0, 0, 0); __builtin_amdgcn_s_setprio(0); } while (0)
; #define PG8_WAIT_V(n) asm volatile("s_waitcnt vmcnt(" #n ")" ::: "memory")
; #define PG8_WAIT_L(n) asm volatile("s_waitcnt lgkmcnt(" #n ")" ::: "memory")
; #define PG8_BAR __builtin_amdgcn_s_barrier()
; #define PG8_SCHED __builtin_amdgcn_sched_barrier(0)
; template <class Epi, class Sched, bool ALIGN_EPI = false, bool SP2 = false>
; __device__ __forceinline__ void gemm_phase(PG8_LAS unsigned char* lds, const Gemm g, const Sched& S, const Epi& E) {
;     ...
;             const bool last = (t == nt - 2);
;             const char* a1 = cA + (size_t)(t + 1) * kstep;
;             const char* a2 = last ? nA : cA + (size_t)(t + 2) * kstep; const char* b2 = last ? nB : cB + (size_t)(t + 2) * kstep;
;             const char* a3 = a2 + kstep; const char* b3 = b2 + kstep;
;             if (last && has_next) S.a_ready(nxt);
;             if constexpr (SP2) {
;             PG8_LDB(B0, 0, 0); PG8_LDB(B1, 0, 1); PG8_SCHED; PG8_LDA(At, 0, 0); PG8_STAGE(PG8_SA(1, 1), a1 + hstep, voffA);
;             PG8_WAIT_V(8); PG8_WAIT_L(0); PG8_BAR; PG8_MMA(0, 0, At, B0); PG8_MMA(0, 1, At, B1); PG8_BAR; PG8_SCHED;
;             PG8_LDA(At, 0, 1); PG8_STAGE(PG8_SB(0, 0), b2, voffB); PG8_STAGE(PG8_SB(0, 1), b2 + hstep, voffB); PG8_STAGE(PG8_SA(0, 0), a2, voffA);
.LBB0_1008:
	s_waitcnt vmcnt(0)
	s_andn2_b64 vcc, exec, s[20:21]
	s_cbranch_vccnz .LBB0_1011
	s_add_u32 s4, s4, 0x80
	s_addc_u32 s5, s5, 0
	s_add_u32 s11, s6, 0x100
	s_addc_u32 s29, s7, 0
	s_mov_b32 s6, 0
	ds_read_b128 v[128:131], v195
	ds_read_b128 v[132:135], v195 offset:1024
	ds_read_b128 v[136:139], v195 offset:2048
	ds_read_b128 v[140:143], v195 offset:3072
	ds_read_b128 v[144:147], v196
	ds_read_b128 v[148:151], v196 offset:1024
	ds_read_b128 v[152:155], v196 offset:2048
	ds_read_b128 v[156:159], v196 offset:3072
	s_add_i32 s56, s6, 2
	s_add_u32 s57, s4, 0x80
	s_addc_u32 s7, s5, 0
	s_cmp_eq_u32 s46, s6
	s_cselect_b32 s6, s0, s57
	s_cselect_b32 s7, s1, s7
	s_cselect_b32 s59, s27, s29
	s_cselect_b32 s58, s26, s11
	v_lshl_add_u64 v[218:219], s[4:5], 0, v[170:171]
	s_add_i32 m0, s37, 0xc000
	ds_read_b128 v[178:181], v197
	ds_read_b128 v[182:185], v197 offset:1024
	ds_read_b128 v[186:189], v197 offset:2048
	ds_read_b128 v[190:193], v197 offset:3072
	ds_read_b128 v[202:205], v197 offset:4096
	ds_read_b128 v[206:209], v197 offset:5120
	ds_read_b128 v[210:213], v197 offset:6144
	ds_read_b128 v[214:217], v197 offset:7168
	global_load_lds_dwordx4 v[218:219], off
	v_lshl_add_u64 v[218:219], s[4:5], 0, v[172:173]
	s_add_i32 m0, s37, 0xe000
	s_nop 0
	global_load_lds_dwordx4 v[218:219], off
	s_waitcnt vmcnt(8)
	s_waitcnt lgkmcnt(0)
	s_barrier
	s_setprio 1
	s_waitcnt lgkmcnt(0)
	v_mfma_f32_16x16x32_bf16 v[124:127], v[128:131], v[178:181], 0
	v_mfma_f32_16x16x32_bf16 v[120:123], v[136:139], v[178:181], 0
	v_mfma_f32_16x16x32_bf16 v[108:111], v[128:131], v[186:189], 0
	v_mfma_f32_16x16x32_bf16 v[104:107], v[136:139], v[186:189], 0
	v_mfma_f32_16x16x32_bf16 v[92:95], v[128:131], v[202:205], 0
	v_mfma_f32_16x16x32_bf16 v[88:91], v[136:139], v[202:205], 0
	v_mfma_f32_16x16x32_bf16 v[76:79], v[128:131], v[210:213], 0
	v_mfma_f32_16x16x32_bf16 v[72:75], v[136:139], v[210:213], 0
	v_mfma_f32_16x16x32_bf16 v[124:127], v[132:135], v[182:185], v[124:127]
	v_mfma_f32_16x16x32_bf16 v[120:123], v[140:143], v[182:185], v[120:123]
	v_mfma_f32_16x16x32_bf16 v[108:111], v[132:135], v[190:193], v[108:111]
	v_mfma_f32_16x16x32_bf16 v[104:107], v[140:143], v[190:193], v[104:107]
	v_mfma_f32_16x16x32_bf16 v[92:95], v[132:135], v[206:209], v[92:95]
	v_mfma_f32_16x16x32_bf16 v[88:91], v[140:143], v[206:209], v[88:91]
	v_mfma_f32_16x16x32_bf16 v[76:79], v[132:135], v[214:217], v[76:79]
	v_mfma_f32_16x16x32_bf16 v[72:75], v[140:143], v[214:217], v[72:75]
	s_setprio 0
	s_setprio 1
	v_mfma_f32_16x16x32_bf16 v[116:119], v[144:147], v[178:181], 0
	v_mfma_f32_16x16x32_bf16 v[112:115], v[152:155], v[178:181], 0
	v_mfma_f32_16x16x32_bf16 v[100:103], v[144:147], v[186:189], 0
	v_mfma_f32_16x16x32_bf16 v[96:99], v[152:155], v[186:189], 0
	v_mfma_f32_16x16x32_bf16 v[84:87], v[144:147], v[202:205], 0
	v_mfma_f32_16x16x32_bf16 v[80:83], v[152:155], v[202:205], 0
	v_mfma_f32_16x16x32_bf16 v[68:71], v[144:147], v[210:213], 0
	v_mfma_f32_16x16x32_bf16 v[64:67], v[152:155], v[210:213], 0
	v_mfma_f32_16x16x32_bf16 v[116:119], v[148:151], v[182:185], v[116:119]
	v_mfma_f32_16x16x32_bf16 v[112:115], v[156:159], v[182:185], v[112:115]
	v_mfma_f32_16x16x32_bf16 v[100:103], v[148:151], v[190:193], v[100:103]
	v_mfma_f32_16x16x32_bf16 v[96:99], v[156:159], v[190:193], v[96:99]
	v_mfma_f32_16x16x32_bf16 v[84:87], v[148:151], v[206:209], v[84:87]
	v_mfma_f32_16x16x32_bf16 v[80:83], v[156:159], v[206:209], v[80:83]
	v_mfma_f32_16x16x32_bf16 v[68:71], v[148:151], v[214:217], v[68:71]
	v_mfma_f32_16x16x32_bf16 v[64:67], v[156:159], v[214:217], v[64:67]
	s_setprio 0
	s_barrier
	s_add_i32 s57, s52, s36
	v_lshl_add_u64 v[218:219], s[58:59], 0, v[162:163]
	s_mov_b32 m0, s57
	ds_read_b128 v[178:181], v197 offset:16384
	ds_read_b128 v[182:185], v197 offset:17408
	ds_read_b128 v[186:189], v197 offset:18432
	ds_read_b128 v[190:193], v197 offset:19456
	ds_read_b128 v[202:205], v197 offset:20480
	ds_read_b128 v[206:209], v197 offset:21504
	ds_read_b128 v[210:213], v197 offset:22528
	ds_read_b128 v[214:217], v197 offset:23552
	global_load_lds_dwordx4 v[218:219], off
	s_add_i32 m0, s57, 0x2000
	v_lshl_add_u64 v[220:221], s[58:59], 0, v[166:167]
	s_add_u32 s58, s58, s12
	s_addc_u32 s59, s59, s13
	s_add_i32 s57, s53, s36
	global_load_lds_dwordx4 v[220:221], off
	v_lshl_add_u64 v[222:223], s[58:59], 0, v[162:163]
	s_mov_b32 m0, s57
	v_lshl_add_u64 v[224:225], s[58:59], 0, v[166:167]
	global_load_lds_dwordx4 v[222:223], off
	s_add_i32 m0, s57, 0x2000
	v_lshl_add_u64 v[226:227], s[6:7], 0, v[160:161]
	global_load_lds_dwordx4 v[224:225], off
	s_mov_b32 m0, s37
	v_lshl_add_u64 v[228:229], s[6:7], 0, v[164:165]
	global_load_lds_dwordx4 v[226:227], off
	s_mov_b32 m0, s38
	s_nop 0
	global_load_lds_dwordx4 v[228:229], off
	s_waitcnt vmcnt(8)
	s_waitcnt lgkmcnt(0)
	s_barrier
; #define PG8_STAGE(bufoff, gbase, voff) do { _Pragma("unroll") for (int _i = 0; _i < 2; ++_i) \
;         __builtin_amdgcn_global_load_lds((const unsigned*)((const char*)(gbase) + (voff)[_i]), (PG8_LAS unsigned*)(lds + (bufoff) + ldsw + _i * 8192), 16, 0, 0); } while (0)
; #define PG8_LDA(dst, b, h) do { _Pragma("unroll") for (int m = 0; m < 4; ++m) _Pragma("unroll") for (int k = 0; k < 2; ++k) dst[m][k] = *(const PG8_LAS bf16x8*)(lds + PG8_SA(b, h) + aoff + m * 2048 + k * 1024); } while (0)
; #define PG8_LDB(dst, b, h) do { _Pragma("unroll") for (int n = 0; n < 2; ++n) _Pragma("unroll") for (int k = 0; k < 2; ++k) dst[n][k] = *(const PG8_LAS bf16x8*)(lds + PG8_SB(b, h) + boff + n * 2048 + k * 1024); } while (0)
; #define PG8_MMA(ai, bj, At, Bt) do { __builtin_amdgcn_s_setprio(1); _Pragma("unroll") for (int m = 0; m < 4; ++m) _Pragma("unroll") for (int n = 0; n < 2; ++n) _Pragma("unroll") for (int k = 0; k < 2; ++k) \
;         acc[ai][bj][m][n] = __builtin_amdgcn_mfma_f32_16x16x32_bf16(Bt[n][k], At[m][k], acc[ai][bj][m][n], 0, 0, 0); __builtin_amdgcn_s_setprio(0); } while (0)
; #define PG8_WAIT_V(n) asm volatile("s_waitcnt vmcnt(" #n ")" ::: "memory")
; #define PG8_WAIT_L(n) asm volatile("s_waitcnt lgkmcnt(" #n ")" ::: "memory")
; #define PG8_BAR __builtin_amdgcn_s_barrier()
; #define PG8_SCHED __builtin_amdgcn_sched_barrier(0)
; template <class Epi, class Sched, bool ALIGN_EPI = false, bool SP2 = false>
; __device__ __forceinline__ void gemm_phase(PG8_LAS unsigned char* lds, const Gemm g, const Sched& S, const Epi& E) {
;     ...
;             PG8_WAIT_V(8); PG8_WAIT_L(0); PG8_BAR; PG8_MMA(1, 0, At, B0); PG8_MMA(1, 1, At, B1); PG8_BAR; PG8_SCHED;
;             PG8_LDB(B0, 1, 0); PG8_LDB(B1, 1, 1); PG8_SCHED; PG8_LDA(At, 1, 0); PG8_STAGE(PG8_SA(0, 1), a2 + hstep, voffA);
;             PG8_WAIT_V(8); PG8_WAIT_L(0); PG8_BAR; PG8_MMA(0, 0, At, B0); PG8_MMA(0, 1, At, B1); PG8_BAR; PG8_SCHED;
	s_setprio 1
	s_waitcnt lgkmcnt(0)
	v_mfma_f32_16x16x32_bf16 v[60:63], v[128:131], v[178:181], 0
	v_mfma_f32_16x16x32_bf16 v[56:59], v[136:139], v[178:181], 0
	v_mfma_f32_16x16x32_bf16 v[44:47], v[128:131], v[186:189], 0
	v_mfma_f32_16x16x32_bf16 v[40:43], v[136:139], v[186:189], 0
	v_mfma_f32_16x16x32_bf16 v[28:31], v[128:131], v[202:205], 0
	v_mfma_f32_16x16x32_bf16 v[24:27], v[136:139], v[202:205], 0
	v_mfma_f32_16x16x32_bf16 v[12:15], v[128:131], v[210:213], 0
	v_mfma_f32_16x16x32_bf16 v[8:11], v[136:139], v[210:213], 0
	v_mfma_f32_16x16x32_bf16 v[60:63], v[132:135], v[182:185], v[60:63]
	v_mfma_f32_16x16x32_bf16 v[56:59], v[140:143], v[182:185], v[56:59]
	v_mfma_f32_16x16x32_bf16 v[44:47], v[132:135], v[190:193], v[44:47]
	v_mfma_f32_16x16x32_bf16 v[40:43], v[140:143], v[190:193], v[40:43]
	v_mfma_f32_16x16x32_bf16 v[28:31], v[132:135], v[206:209], v[28:31]
	v_mfma_f32_16x16x32_bf16 v[24:27], v[140:143], v[206:209], v[24:27]
	v_mfma_f32_16x16x32_bf16 v[12:15], v[132:135], v[214:217], v[12:15]
	v_mfma_f32_16x16x32_bf16 v[8:11], v[140:143], v[214:217], v[8:11]
	s_setprio 0
	s_setprio 1
	v_mfma_f32_16x16x32_bf16 v[52:55], v[144:147], v[178:181], 0
	v_mfma_f32_16x16x32_bf16 v[48:51], v[152:155], v[178:181], 0
	v_mfma_f32_16x16x32_bf16 v[36:39], v[144:147], v[186:189], 0
	v_mfma_f32_16x16x32_bf16 v[32:35], v[152:155], v[186:189], 0
	v_mfma_f32_16x16x32_bf16 v[20:23], v[144:147], v[202:205], 0
	v_mfma_f32_16x16x32_bf16 v[16:19], v[152:155], v[202:205], 0
	v_mfma_f32_16x16x32_bf16 v[4:7], v[144:147], v[210:213], 0
	v_mfma_f32_16x16x32_bf16 v[0:3], v[152:155], v[210:213], 0
	v_mfma_f32_16x16x32_bf16 v[52:55], v[148:151], v[182:185], v[52:55]
	v_mfma_f32_16x16x32_bf16 v[48:51], v[156:159], v[182:185], v[48:51]
	v_mfma_f32_16x16x32_bf16 v[36:39], v[148:151], v[190:193], v[36:39]
	v_mfma_f32_16x16x32_bf16 v[32:35], v[156:159], v[190:193], v[32:35]
	v_mfma_f32_16x16x32_bf16 v[20:23], v[148:151], v[206:209], v[20:23]
	v_mfma_f32_16x16x32_bf16 v[16:19], v[156:159], v[206:209], v[16:19]
	v_mfma_f32_16x16x32_bf16 v[4:7], v[148:151], v[214:217], v[4:7]
	v_mfma_f32_16x16x32_bf16 v[0:3], v[156:159], v[214:217], v[0:3]
	s_setprio 0
	s_barrier
	s_add_i32 s57, 0, 0x18000
	s_add_i32 s58, 0, 0x1c000
	v_add_u32_e32 v140, s57, v194
	v_add_u32_e32 v156, s58, v194
	ds_read_b128 v[128:131], v140
	ds_read_b128 v[132:135], v140 offset:1024
	ds_read_b128 v[136:139], v140 offset:2048
	ds_read_b128 v[140:143], v140 offset:3072
	ds_read_b128 v[144:147], v156
	ds_read_b128 v[148:151], v156 offset:1024
	ds_read_b128 v[152:155], v156 offset:2048
	ds_read_b128 v[156:159], v156 offset:3072
	s_add_u32 s6, s6, s12
	s_addc_u32 s7, s7, s13
	s_mov_b32 m0, s39
	v_lshl_add_u64 v[230:231], s[6:7], 0, v[160:161]
	ds_read_b128 v[178:181], v197 offset:32768
	ds_read_b128 v[182:185], v197 offset:33792
	ds_read_b128 v[186:189], v197 offset:34816
	ds_read_b128 v[190:193], v197 offset:35840
	ds_read_b128 v[202:205], v197 offset:36864
	ds_read_b128 v[206:209], v197 offset:37888
	ds_read_b128 v[210:213], v197 offset:38912
	ds_read_b128 v[214:217], v197 offset:39936
	global_load_lds_dwordx4 v[230:231], off
	v_lshl_add_u64 v[230:231], s[6:7], 0, v[164:165]
	s_mov_b32 m0, s40
	s_nop 0
	global_load_lds_dwordx4 v[230:231], off
	s_waitcnt vmcnt(8)
	s_waitcnt lgkmcnt(0)
	s_barrier
	s_setprio 1
	s_waitcnt lgkmcnt(0)
	v_mfma_f32_16x16x32_bf16 v[124:127], v[128:131], v[178:181], v[124:127]
	v_mfma_f32_16x16x32_bf16 v[120:123], v[136:139], v[178:181], v[120:123]
	v_mfma_f32_16x16x32_bf16 v[108:111], v[128:131], v[186:189], v[108:111]
	v_mfma_f32_16x16x32_bf16 v[104:107], v[136:139], v[186:189], v[104:107]
	v_mfma_f32_16x16x32_bf16 v[92:95], v[128:131], v[202:205], v[92:95]
	v_mfma_f32_16x16x32_bf16 v[88:91], v[136:139], v[202:205], v[88:91]
	v_mfma_f32_16x16x32_bf16 v[76:79], v[128:131], v[210:213], v[76:79]
	v_mfma_f32_16x16x32_bf16 v[72:75], v[136:139], v[210:213], v[72:75]
	v_mfma_f32_16x16x32_bf16 v[124:127], v[132:135], v[182:185], v[124:127]
	v_mfma_f32_16x16x32_bf16 v[120:123], v[140:143], v[182:185], v[120:123]
	v_mfma_f32_16x16x32_bf16 v[108:111], v[132:135], v[190:193], v[108:111]
	v_mfma_f32_16x16x32_bf16 v[104:107], v[140:143], v[190:193], v[104:107]
	v_mfma_f32_16x16x32_bf16 v[92:95], v[132:135], v[206:209], v[92:95]
	v_mfma_f32_16x16x32_bf16 v[88:91], v[140:143], v[206:209], v[88:91]
	v_mfma_f32_16x16x32_bf16 v[76:79], v[132:135], v[214:217], v[76:79]
	v_mfma_f32_16x16x32_bf16 v[72:75], v[140:143], v[214:217], v[72:75]
	s_setprio 0
	s_setprio 1
	v_mfma_f32_16x16x32_bf16 v[116:119], v[144:147], v[178:181], v[116:119]
	v_mfma_f32_16x16x32_bf16 v[112:115], v[152:155], v[178:181], v[112:115]
	v_mfma_f32_16x16x32_bf16 v[100:103], v[144:147], v[186:189], v[100:103]
	v_mfma_f32_16x16x32_bf16 v[96:99], v[152:155], v[186:189], v[96:99]
	v_mfma_f32_16x16x32_bf16 v[84:87], v[144:147], v[202:205], v[84:87]
	v_mfma_f32_16x16x32_bf16 v[80:83], v[152:155], v[202:205], v[80:83]
	v_mfma_f32_16x16x32_bf16 v[68:71], v[144:147], v[210:213], v[68:71]
	v_mfma_f32_16x16x32_bf16 v[64:67], v[152:155], v[210:213], v[64:67]
	v_mfma_f32_16x16x32_bf16 v[116:119], v[148:151], v[182:185], v[116:119]
	v_mfma_f32_16x16x32_bf16 v[112:115], v[156:159], v[182:185], v[112:115]
	v_mfma_f32_16x16x32_bf16 v[100:103], v[148:151], v[190:193], v[100:103]
	v_mfma_f32_16x16x32_bf16 v[96:99], v[156:159], v[190:193], v[96:99]
	v_mfma_f32_16x16x32_bf16 v[84:87], v[148:151], v[206:209], v[84:87]
	v_mfma_f32_16x16x32_bf16 v[80:83], v[156:159], v[206:209], v[80:83]
	v_mfma_f32_16x16x32_bf16 v[68:71], v[148:151], v[214:217], v[68:71]
	v_mfma_f32_16x16x32_bf16 v[64:67], v[156:159], v[214:217], v[64:67]
	s_setprio 0
	s_barrier
; #define PG8_STAGE(bufoff, gbase, voff) do { _Pragma("unroll") for (int _i = 0; _i < 2; ++_i) \
;         __builtin_amdgcn_global_load_lds((const unsigned*)((const char*)(gbase) + (voff)[_i]), (PG8_LAS unsigned*)(lds + (bufoff) + ldsw + _i * 8192), 16, 0, 0); } while (0)
; #define PG8_LDA(dst, b, h) do { _Pragma("unroll") for (int m = 0; m < 4; ++m) _Pragma("unroll") for (int k = 0; k < 2; ++k) dst[m][k] = *(const PG8_LAS bf16x8*)(lds + PG8_SA(b, h) + aoff + m * 2048 + k * 1024); } while (0)
; #define PG8_MMA(ai, bj, At, Bt) do { __builtin_amdgcn_s_setprio(1); _Pragma("unroll") for (int m = 0; m < 4; ++m) _Pragma("unroll") for (int n = 0; n < 2; ++n) _Pragma("unroll") for (int k = 0; k < 2; ++k) \
;         acc[ai][bj][m][n] = __builtin_amdgcn_mfma_f32_16x16x32_bf16(Bt[n][k], At[m][k], acc[ai][bj][m][n], 0, 0, 0); __builtin_amdgcn_s_setprio(0); } while (0)
; #define PG8_WAIT_V(n) asm volatile("s_waitcnt vmcnt(" #n ")" ::: "memory")
; #define PG8_WAIT_L(n) asm volatile("s_waitcnt lgkmcnt(" #n ")" ::: "memory")
; #define PG8_BAR __builtin_amdgcn_s_barrier()
; #define PG8_SCHED __builtin_amdgcn_sched_barrier(0)
; template <class Epi, class Sched, bool ALIGN_EPI = false, bool SP2 = false>
; __device__ __forceinline__ void gemm_phase(PG8_LAS unsigned char* lds, const Gemm g, const Sched& S, const Epi& E) {
;     ...
;         for (int t = 0; t < nt; t += 2) {
;             if constexpr (Epi::HAS_MID) { if (t == Epi::MID_T) E.mid(acc, cur, wr, wc, fr, fq); }
;             const bool last = (t == nt - 2);
;             const char* a1 = cA + (size_t)(t + 1) * kstep;
;             const char* a2 = last ? nA : cA + (size_t)(t + 2) * kstep; const char* b2 = last ? nB : cB + (size_t)(t + 2) * kstep;
;     ...
;             PG8_LDA(At, 1, 1); PG8_STAGE(PG8_SB(1, 0), b3, voffB); PG8_STAGE(PG8_SB(1, 1), b3 + hstep, voffB); PG8_STAGE(PG8_SA(1, 0), a3, voffA);
;             PG8_WAIT_V(8); PG8_WAIT_L(0); PG8_BAR; PG8_MMA(1, 0, At, B0); PG8_MMA(1, 1, At, B1); PG8_BAR; PG8_SCHED;
	s_add_i32 s6, s57, s36
	v_lshl_add_u64 v[218:219], v[218:219], 0, s[18:19]
	s_mov_b32 m0, s6
	ds_read_b128 v[178:181], v197 offset:49152
	ds_read_b128 v[182:185], v197 offset:50176
	ds_read_b128 v[186:189], v197 offset:51200
	ds_read_b128 v[190:193], v197 offset:52224
	ds_read_b128 v[202:205], v197 offset:53248
	ds_read_b128 v[206:209], v197 offset:54272
	ds_read_b128 v[210:213], v197 offset:55296
	ds_read_b128 v[214:217], v197 offset:56320
	global_load_lds_dwordx4 v[218:219], off
	v_lshl_add_u64 v[218:219], v[220:221], 0, s[18:19]
	s_add_i32 m0, s6, 0x2000
	s_add_i32 s6, s58, s36
	global_load_lds_dwordx4 v[218:219], off
	v_lshl_add_u64 v[218:219], v[222:223], 0, s[18:19]
	s_mov_b32 m0, s6
	s_nop 0
	global_load_lds_dwordx4 v[218:219], off
	v_lshl_add_u64 v[218:219], v[224:225], 0, s[18:19]
	s_add_i32 m0, s6, 0x2000
	s_nop 0
	global_load_lds_dwordx4 v[218:219], off
	v_lshl_add_u64 v[218:219], v[226:227], 0, s[18:19]
	s_mov_b32 m0, s42
	s_nop 0
	global_load_lds_dwordx4 v[218:219], off
	v_lshl_add_u64 v[218:219], v[228:229], 0, s[18:19]
	s_mov_b32 m0, s43
	s_nop 0
	global_load_lds_dwordx4 v[218:219], off
	s_waitcnt vmcnt(8)
	s_waitcnt lgkmcnt(0)
	s_barrier
	s_setprio 1
	s_waitcnt lgkmcnt(0)
	v_mfma_f32_16x16x32_bf16 v[60:63], v[128:131], v[178:181], v[60:63]
	v_mfma_f32_16x16x32_bf16 v[56:59], v[136:139], v[178:181], v[56:59]
	v_mfma_f32_16x16x32_bf16 v[44:47], v[128:131], v[186:189], v[44:47]
	v_mfma_f32_16x16x32_bf16 v[40:43], v[136:139], v[186:189], v[40:43]
	v_mfma_f32_16x16x32_bf16 v[28:31], v[128:131], v[202:205], v[28:31]
	v_mfma_f32_16x16x32_bf16 v[24:27], v[136:139], v[202:205], v[24:27]
	v_mfma_f32_16x16x32_bf16 v[12:15], v[128:131], v[210:213], v[12:15]
	v_mfma_f32_16x16x32_bf16 v[8:11], v[136:139], v[210:213], v[8:11]
	v_mfma_f32_16x16x32_bf16 v[60:63], v[132:135], v[182:185], v[60:63]
	v_mfma_f32_16x16x32_bf16 v[56:59], v[140:143], v[182:185], v[56:59]
	v_mfma_f32_16x16x32_bf16 v[44:47], v[132:135], v[190:193], v[44:47]
	v_mfma_f32_16x16x32_bf16 v[40:43], v[140:143], v[190:193], v[40:43]
	v_mfma_f32_16x16x32_bf16 v[28:31], v[132:135], v[206:209], v[28:31]
	v_mfma_f32_16x16x32_bf16 v[24:27], v[140:143], v[206:209], v[24:27]
	v_mfma_f32_16x16x32_bf16 v[12:15], v[132:135], v[214:217], v[12:15]
	v_mfma_f32_16x16x32_bf16 v[8:11], v[140:143], v[214:217], v[8:11]
	s_setprio 0
	s_setprio 1
	v_mfma_f32_16x16x32_bf16 v[52:55], v[144:147], v[178:181], v[52:55]
	v_mfma_f32_16x16x32_bf16 v[48:51], v[152:155], v[178:181], v[48:51]
	v_mfma_f32_16x16x32_bf16 v[36:39], v[144:147], v[186:189], v[36:39]
	v_mfma_f32_16x16x32_bf16 v[32:35], v[152:155], v[186:189], v[32:35]
	v_mfma_f32_16x16x32_bf16 v[20:23], v[144:147], v[202:205], v[20:23]
	v_mfma_f32_16x16x32_bf16 v[16:19], v[152:155], v[202:205], v[16:19]
	v_mfma_f32_16x16x32_bf16 v[4:7], v[144:147], v[210:213], v[4:7]
	v_mfma_f32_16x16x32_bf16 v[0:3], v[152:155], v[210:213], v[0:3]
	v_mfma_f32_16x16x32_bf16 v[52:55], v[148:151], v[182:185], v[52:55]
	v_mfma_f32_16x16x32_bf16 v[48:51], v[156:159], v[182:185], v[48:51]
	v_mfma_f32_16x16x32_bf16 v[36:39], v[148:151], v[190:193], v[36:39]
	v_mfma_f32_16x16x32_bf16 v[32:35], v[156:159], v[190:193], v[32:35]
	v_mfma_f32_16x16x32_bf16 v[20:23], v[148:151], v[206:209], v[20:23]
	v_mfma_f32_16x16x32_bf16 v[16:19], v[156:159], v[206:209], v[16:19]
	v_mfma_f32_16x16x32_bf16 v[4:7], v[148:151], v[214:217], v[4:7]
	v_mfma_f32_16x16x32_bf16 v[0:3], v[156:159], v[214:217], v[0:3]
	s_setprio 0
	s_barrier
	s_add_u32 s4, s4, 0x100
	s_addc_u32 s5, s5, 0
	s_add_u32 s11, s11, 0x100
	s_addc_u32 s29, s29, 0
	s_cmp_ge_i32 s56, s44
	s_mov_b32 s6, s56
	s_cbranch_scc1 .LBB0_1011

; #define PG8_STAGE(bufoff, gbase, voff) do { _Pragma("unroll") for (int _i = 0; _i < 2; ++_i) \
;         __builtin_amdgcn_global_load_lds((const unsigned*)((const char*)(gbase) + (voff)[_i]), (PG8_LAS unsigned*)(lds + (bufoff) + ldsw + _i * 8192), 16, 0, 0); } while (0)
; #define PG8_LDA(dst, b, h) do { _Pragma("unroll") for (int m = 0; m < 4; ++m) _Pragma("unroll") for (int k = 0; k < 2; ++k) dst[m][k] = *(const PG8_LAS bf16x8*)(lds + PG8_SA(b, h) + aoff + m * 2048 + k * 1024); } while (0)
; #define PG8_LDB(dst, b, h) do { _Pragma("unroll") for (int n = 0; n < 2; ++n) _Pragma("unroll") for (int k = 0; k < 2; ++k) dst[n][k] = *(const PG8_LAS bf16x8*)(lds + PG8_SB(b, h) + boff + n * 2048 + k * 1024); } while (0)
; #define PG8_MMA(ai, bj, At, Bt) do { __builtin_amdgcn_s_setprio(1); _Pragma("unroll") for (int m = 0; m < 4; ++m) _Pragma("unroll") for (int n = 0; n < 2; ++n) _Pragma("unroll") for (int k = 0; k < 2; ++k) \
;         acc[ai][bj][m][n] = __builtin_amdgcn_mfma_f32_16x16x32_bf16(Bt[n][k], At[m][k], acc[ai][bj][m][n], 0, 0, 0); __builtin_amdgcn_s_setprio(0); } while (0)
; #define PG8_WAIT_V(n) asm volatile("s_waitcnt vmcnt(" #n ")" ::: "memory")
; #define PG8_WAIT_L(n) asm volatile("s_waitcnt lgkmcnt(" #n ")" ::: "memory")
; #define PG8_BAR __builtin_amdgcn_s_barrier()
; #define PG8_SCHED __builtin_amdgcn_sched_barrier(0)
; template <class Epi, class Sched, bool ALIGN_EPI = false, bool SP2 = false>
; __device__ __forceinline__ void gemm_phase(PG8_LAS unsigned char* lds, const Gemm g, const Sched& S, const Epi& E) {
;     ...
;             PG8_LDB(B0, 0, 0); PG8_LDB(B1, 0, 1); PG8_SCHED; PG8_LDA(At, 0, 0); PG8_STAGE(PG8_SA(1, 1), a1 + hstep, voffA);
;             PG8_WAIT_V(8); PG8_WAIT_L(0); PG8_BAR; PG8_MMA(0, 0, At, B0); PG8_MMA(0, 1, At, B1); PG8_BAR; PG8_SCHED;
;             PG8_LDA(At, 0, 1); PG8_STAGE(PG8_SB(0, 0), b2, voffB); PG8_STAGE(PG8_SB(0, 1), b2 + hstep, voffB); PG8_STAGE(PG8_SA(0, 0), a2, voffA);
;             PG8_WAIT_V(8); PG8_WAIT_L(0); PG8_BAR; PG8_MMA(1, 0, At, B0); PG8_MMA(1, 1, At, B1); PG8_BAR; PG8_SCHED;
;     ...
;         for (int a = 0; a < 2; ++a)
; #pragma unroll
;             for (int b = 0; b < 2; ++b)
; #pragma unroll
;                 for (int m = 0; m < 4; ++m)
; #pragma unroll
;                     for (int n = 0; n < 2; ++n) acc[a][b][m][n] = (f32x4){0.f, 0.f, 0.f, 0.f};
.LBB0_1395:
	s_andn2_b64 vcc, exec, s[14:15]
	s_cbranch_vccnz .LBB0_1398
	s_add_u32 s20, s20, 0x80
	s_addc_u32 s21, s21, 0
	s_add_u32 s50, s22, 0x100
	s_addc_u32 s51, s23, 0
	s_mov_b32 s22, 0
	ds_read_b128 v[150:153], v147
	ds_read_b128 v[154:157], v147 offset:1024
	ds_read_b128 v[158:161], v147 offset:2048
	ds_read_b128 v[162:165], v147 offset:3072
	ds_read_b128 v[166:169], v148
	ds_read_b128 v[170:173], v148 offset:1024
	ds_read_b128 v[174:177], v148 offset:2048
	ds_read_b128 v[178:181], v148 offset:3072
	s_add_i32 s52, s22, 2
	s_add_u32 s53, s20, 0x80
	s_addc_u32 s23, s21, 0
	s_cmp_eq_u32 s40, s22
	s_cselect_b32 s22, s0, s53
	s_cselect_b32 s23, s1, s23
	s_cselect_b32 s55, s19, s51
	s_cselect_b32 s54, s18, s50
	v_lshl_add_u64 v[198:199], s[20:21], 0, v[136:137]
	s_add_i32 m0, s30, 0xc000
	ds_read_b128 v[182:185], v149
	ds_read_b128 v[186:189], v149 offset:1024
	ds_read_b128 v[190:193], v149 offset:2048
	ds_read_b128 v[194:197], v149 offset:3072
	ds_read_b128 v[202:205], v149 offset:4096
	ds_read_b128 v[206:209], v149 offset:5120
	ds_read_b128 v[210:213], v149 offset:6144
	ds_read_b128 v[214:217], v149 offset:7168
	global_load_lds_dwordx4 v[198:199], off
	v_lshl_add_u64 v[198:199], s[20:21], 0, v[138:139]
	s_add_i32 m0, s30, 0xe000
	s_nop 0
	global_load_lds_dwordx4 v[198:199], off
	s_waitcnt vmcnt(8)
	s_waitcnt lgkmcnt(0)
	s_barrier
	s_setprio 1
	s_waitcnt lgkmcnt(0)
	v_mfma_f32_16x16x32_bf16 v[120:123], v[150:153], v[182:185], 0
	v_mfma_f32_16x16x32_bf16 v[124:127], v[158:161], v[182:185], 0
	v_mfma_f32_16x16x32_bf16 v[108:111], v[150:153], v[190:193], 0
	v_mfma_f32_16x16x32_bf16 v[104:107], v[158:161], v[190:193], 0
	v_mfma_f32_16x16x32_bf16 v[92:95], v[150:153], v[202:205], 0
	v_mfma_f32_16x16x32_bf16 v[88:91], v[158:161], v[202:205], 0
	v_mfma_f32_16x16x32_bf16 v[76:79], v[150:153], v[210:213], 0
	v_mfma_f32_16x16x32_bf16 v[72:75], v[158:161], v[210:213], 0
	v_mfma_f32_16x16x32_bf16 v[120:123], v[154:157], v[186:189], v[120:123]
	v_mfma_f32_16x16x32_bf16 v[124:127], v[162:165], v[186:189], v[124:127]
	v_mfma_f32_16x16x32_bf16 v[108:111], v[154:157], v[194:197], v[108:111]
	v_mfma_f32_16x16x32_bf16 v[104:107], v[162:165], v[194:197], v[104:107]
	v_mfma_f32_16x16x32_bf16 v[92:95], v[154:157], v[206:209], v[92:95]
	v_mfma_f32_16x16x32_bf16 v[88:91], v[162:165], v[206:209], v[88:91]
	v_mfma_f32_16x16x32_bf16 v[76:79], v[154:157], v[214:217], v[76:79]
	v_mfma_f32_16x16x32_bf16 v[72:75], v[162:165], v[214:217], v[72:75]
	s_setprio 0
	s_setprio 1
	v_mfma_f32_16x16x32_bf16 v[116:119], v[166:169], v[182:185], 0
	v_mfma_f32_16x16x32_bf16 v[112:115], v[174:177], v[182:185], 0
	v_mfma_f32_16x16x32_bf16 v[100:103], v[166:169], v[190:193], 0
	v_mfma_f32_16x16x32_bf16 v[96:99], v[174:177], v[190:193], 0
	v_mfma_f32_16x16x32_bf16 v[84:87], v[166:169], v[202:205], 0
	v_mfma_f32_16x16x32_bf16 v[80:83], v[174:177], v[202:205], 0
	v_mfma_f32_16x16x32_bf16 v[68:71], v[166:169], v[210:213], 0
	v_mfma_f32_16x16x32_bf16 v[64:67], v[174:177], v[210:213], 0
	v_mfma_f32_16x16x32_bf16 v[116:119], v[170:173], v[186:189], v[116:119]
	v_mfma_f32_16x16x32_bf16 v[112:115], v[178:181], v[186:189], v[112:115]
	v_mfma_f32_16x16x32_bf16 v[100:103], v[170:173], v[194:197], v[100:103]
	v_mfma_f32_16x16x32_bf16 v[96:99], v[178:181], v[194:197], v[96:99]
	v_mfma_f32_16x16x32_bf16 v[84:87], v[170:173], v[206:209], v[84:87]
	v_mfma_f32_16x16x32_bf16 v[80:83], v[178:181], v[206:209], v[80:83]
	v_mfma_f32_16x16x32_bf16 v[68:71], v[170:173], v[214:217], v[68:71]
	v_mfma_f32_16x16x32_bf16 v[64:67], v[178:181], v[214:217], v[64:67]
	s_setprio 0
	s_barrier
	s_add_i32 s53, s44, s29
	v_lshl_add_u64 v[198:199], s[54:55], 0, v[130:131]
	s_mov_b32 m0, s53
	ds_read_b128 v[182:185], v149 offset:16384
	ds_read_b128 v[186:189], v149 offset:17408
	ds_read_b128 v[190:193], v149 offset:18432
	ds_read_b128 v[194:197], v149 offset:19456
	ds_read_b128 v[202:205], v149 offset:20480
	ds_read_b128 v[206:209], v149 offset:21504
	ds_read_b128 v[210:213], v149 offset:22528
	ds_read_b128 v[214:217], v149 offset:23552
	global_load_lds_dwordx4 v[198:199], off
	s_add_i32 m0, s53, 0x2000
	v_lshl_add_u64 v[218:219], s[54:55], 0, v[134:135]
	s_add_u32 s54, s54, s6
	s_addc_u32 s55, s55, s7
	s_add_i32 s53, s45, s29
	global_load_lds_dwordx4 v[218:219], off
	v_lshl_add_u64 v[220:221], s[54:55], 0, v[130:131]
	s_mov_b32 m0, s53
	v_lshl_add_u64 v[222:223], s[54:55], 0, v[134:135]
	global_load_lds_dwordx4 v[220:221], off
	s_add_i32 m0, s53, 0x2000
	v_lshl_add_u64 v[224:225], s[22:23], 0, v[128:129]
	global_load_lds_dwordx4 v[222:223], off
	s_mov_b32 m0, s30
	v_lshl_add_u64 v[226:227], s[22:23], 0, v[132:133]
	global_load_lds_dwordx4 v[224:225], off
	s_mov_b32 m0, s31
	s_nop 0
	global_load_lds_dwordx4 v[226:227], off
	s_waitcnt vmcnt(8)
	s_waitcnt lgkmcnt(0)
	s_barrier
; #define PG8_STAGE(bufoff, gbase, voff) do { _Pragma("unroll") for (int _i = 0; _i < 2; ++_i) \
;         __builtin_amdgcn_global_load_lds((const unsigned*)((const char*)(gbase) + (voff)[_i]), (PG8_LAS unsigned*)(lds + (bufoff) + ldsw + _i * 8192), 16, 0, 0); } while (0)
; #define PG8_LDA(dst, b, h) do { _Pragma("unroll") for (int m = 0; m < 4; ++m) _Pragma("unroll") for (int k = 0; k < 2; ++k) dst[m][k] = *(const PG8_LAS bf16x8*)(lds + PG8_SA(b, h) + aoff + m * 2048 + k * 1024); } while (0)
; #define PG8_LDB(dst, b, h) do { _Pragma("unroll") for (int n = 0; n < 2; ++n) _Pragma("unroll") for (int k = 0; k < 2; ++k) dst[n][k] = *(const PG8_LAS bf16x8*)(lds + PG8_SB(b, h) + boff + n * 2048 + k * 1024); } while (0)
; #define PG8_MMA(ai, bj, At, Bt) do { __builtin_amdgcn_s_setprio(1); _Pragma("unroll") for (int m = 0; m < 4; ++m) _Pragma("unroll") for (int n = 0; n < 2; ++n) _Pragma("unroll") for (int k = 0; k < 2; ++k) \
;         acc[ai][bj][m][n] = __builtin_amdgcn_mfma_f32_16x16x32_bf16(Bt[n][k], At[m][k], acc[ai][bj][m][n], 0, 0, 0); __builtin_amdgcn_s_setprio(0); } while (0)
; #define PG8_WAIT_V(n) asm volatile("s_waitcnt vmcnt(" #n ")" ::: "memory")
; #define PG8_WAIT_L(n) asm volatile("s_waitcnt lgkmcnt(" #n ")" ::: "memory")
; #define PG8_BAR __builtin_amdgcn_s_barrier()
; #define PG8_SCHED __builtin_amdgcn_sched_barrier(0)
; template <class Epi, class Sched, bool ALIGN_EPI = false, bool SP2 = false>
; __device__ __forceinline__ void gemm_phase(PG8_LAS unsigned char* lds, const Gemm g, const Sched& S, const Epi& E) {
;     ...
;             PG8_WAIT_V(8); PG8_WAIT_L(0); PG8_BAR; PG8_MMA(1, 0, At, B0); PG8_MMA(1, 1, At, B1); PG8_BAR; PG8_SCHED;
;             PG8_LDB(B0, 1, 0); PG8_LDB(B1, 1, 1); PG8_SCHED; PG8_LDA(At, 1, 0); PG8_STAGE(PG8_SA(0, 1), a2 + hstep, voffA);
;             PG8_WAIT_V(8); PG8_WAIT_L(0); PG8_BAR; PG8_MMA(0, 0, At, B0); PG8_MMA(0, 1, At, B1); PG8_BAR; PG8_SCHED;
	s_setprio 1
	s_waitcnt lgkmcnt(0)
	v_mfma_f32_16x16x32_bf16 v[60:63], v[150:153], v[182:185], 0
	v_mfma_f32_16x16x32_bf16 v[56:59], v[158:161], v[182:185], 0
	v_mfma_f32_16x16x32_bf16 v[44:47], v[150:153], v[190:193], 0
	v_mfma_f32_16x16x32_bf16 v[40:43], v[158:161], v[190:193], 0
	v_mfma_f32_16x16x32_bf16 v[28:31], v[150:153], v[202:205], 0
	v_mfma_f32_16x16x32_bf16 v[24:27], v[158:161], v[202:205], 0
	v_mfma_f32_16x16x32_bf16 v[12:15], v[150:153], v[210:213], 0
	v_mfma_f32_16x16x32_bf16 v[8:11], v[158:161], v[210:213], 0
	v_mfma_f32_16x16x32_bf16 v[60:63], v[154:157], v[186:189], v[60:63]
	v_mfma_f32_16x16x32_bf16 v[56:59], v[162:165], v[186:189], v[56:59]
	v_mfma_f32_16x16x32_bf16 v[44:47], v[154:157], v[194:197], v[44:47]
	v_mfma_f32_16x16x32_bf16 v[40:43], v[162:165], v[194:197], v[40:43]
	v_mfma_f32_16x16x32_bf16 v[28:31], v[154:157], v[206:209], v[28:31]
	v_mfma_f32_16x16x32_bf16 v[24:27], v[162:165], v[206:209], v[24:27]
	v_mfma_f32_16x16x32_bf16 v[12:15], v[154:157], v[214:217], v[12:15]
	v_mfma_f32_16x16x32_bf16 v[8:11], v[162:165], v[214:217], v[8:11]
	s_setprio 0
	s_setprio 1
	v_mfma_f32_16x16x32_bf16 v[52:55], v[166:169], v[182:185], 0
	v_mfma_f32_16x16x32_bf16 v[48:51], v[174:177], v[182:185], 0
	v_mfma_f32_16x16x32_bf16 v[36:39], v[166:169], v[190:193], 0
	v_mfma_f32_16x16x32_bf16 v[32:35], v[174:177], v[190:193], 0
	v_mfma_f32_16x16x32_bf16 v[20:23], v[166:169], v[202:205], 0
	v_mfma_f32_16x16x32_bf16 v[16:19], v[174:177], v[202:205], 0
	v_mfma_f32_16x16x32_bf16 v[4:7], v[166:169], v[210:213], 0
	v_mfma_f32_16x16x32_bf16 v[0:3], v[174:177], v[210:213], 0
	v_mfma_f32_16x16x32_bf16 v[52:55], v[170:173], v[186:189], v[52:55]
	v_mfma_f32_16x16x32_bf16 v[48:51], v[178:181], v[186:189], v[48:51]
	v_mfma_f32_16x16x32_bf16 v[36:39], v[170:173], v[194:197], v[36:39]
	v_mfma_f32_16x16x32_bf16 v[32:35], v[178:181], v[194:197], v[32:35]
	v_mfma_f32_16x16x32_bf16 v[20:23], v[170:173], v[206:209], v[20:23]
	v_mfma_f32_16x16x32_bf16 v[16:19], v[178:181], v[206:209], v[16:19]
	v_mfma_f32_16x16x32_bf16 v[4:7], v[170:173], v[214:217], v[4:7]
	v_mfma_f32_16x16x32_bf16 v[0:3], v[178:181], v[214:217], v[0:3]
	s_setprio 0
	s_barrier
	s_add_i32 s53, 0, 0x18000
	s_add_i32 s54, 0, 0x1c000
	v_add_u32_e32 v162, s53, v146
	v_add_u32_e32 v178, s54, v146
	ds_read_b128 v[150:153], v162
	ds_read_b128 v[154:157], v162 offset:1024
	ds_read_b128 v[158:161], v162 offset:2048
	ds_read_b128 v[162:165], v162 offset:3072
	ds_read_b128 v[166:169], v178
	ds_read_b128 v[170:173], v178 offset:1024
	ds_read_b128 v[174:177], v178 offset:2048
	ds_read_b128 v[178:181], v178 offset:3072
	s_add_u32 s22, s22, s6
	s_addc_u32 s23, s23, s7
	s_mov_b32 m0, s33
	v_lshl_add_u64 v[228:229], s[22:23], 0, v[128:129]
	ds_read_b128 v[182:185], v149 offset:32768
	ds_read_b128 v[186:189], v149 offset:33792
	ds_read_b128 v[190:193], v149 offset:34816
	ds_read_b128 v[194:197], v149 offset:35840
	ds_read_b128 v[202:205], v149 offset:36864
	ds_read_b128 v[206:209], v149 offset:37888
	ds_read_b128 v[210:213], v149 offset:38912
	ds_read_b128 v[214:217], v149 offset:39936
	global_load_lds_dwordx4 v[228:229], off
	v_lshl_add_u64 v[228:229], s[22:23], 0, v[132:133]
	s_mov_b32 m0, s34
	s_nop 0
	global_load_lds_dwordx4 v[228:229], off
	s_waitcnt vmcnt(8)
	s_waitcnt lgkmcnt(0)
	s_barrier
	s_setprio 1
	s_waitcnt lgkmcnt(0)
	v_mfma_f32_16x16x32_bf16 v[120:123], v[150:153], v[182:185], v[120:123]
	v_mfma_f32_16x16x32_bf16 v[124:127], v[158:161], v[182:185], v[124:127]
	v_mfma_f32_16x16x32_bf16 v[108:111], v[150:153], v[190:193], v[108:111]
	v_mfma_f32_16x16x32_bf16 v[104:107], v[158:161], v[190:193], v[104:107]
	v_mfma_f32_16x16x32_bf16 v[92:95], v[150:153], v[202:205], v[92:95]
	v_mfma_f32_16x16x32_bf16 v[88:91], v[158:161], v[202:205], v[88:91]
	v_mfma_f32_16x16x32_bf16 v[76:79], v[150:153], v[210:213], v[76:79]
	v_mfma_f32_16x16x32_bf16 v[72:75], v[158:161], v[210:213], v[72:75]
	v_mfma_f32_16x16x32_bf16 v[120:123], v[154:157], v[186:189], v[120:123]
	v_mfma_f32_16x16x32_bf16 v[124:127], v[162:165], v[186:189], v[124:127]
	v_mfma_f32_16x16x32_bf16 v[108:111], v[154:157], v[194:197], v[108:111]
	v_mfma_f32_16x16x32_bf16 v[104:107], v[162:165], v[194:197], v[104:107]
	v_mfma_f32_16x16x32_bf16 v[92:95], v[154:157], v[206:209], v[92:95]
	v_mfma_f32_16x16x32_bf16 v[88:91], v[162:165], v[206:209], v[88:91]
	v_mfma_f32_16x16x32_bf16 v[76:79], v[154:157], v[214:217], v[76:79]
	v_mfma_f32_16x16x32_bf16 v[72:75], v[162:165], v[214:217], v[72:75]
	s_setprio 0
	s_setprio 1
	v_mfma_f32_16x16x32_bf16 v[116:119], v[166:169], v[182:185], v[116:119]
	v_mfma_f32_16x16x32_bf16 v[112:115], v[174:177], v[182:185], v[112:115]
	v_mfma_f32_16x16x32_bf16 v[100:103], v[166:169], v[190:193], v[100:103]
	v_mfma_f32_16x16x32_bf16 v[96:99], v[174:177], v[190:193], v[96:99]
	v_mfma_f32_16x16x32_bf16 v[84:87], v[166:169], v[202:205], v[84:87]
	v_mfma_f32_16x16x32_bf16 v[80:83], v[174:177], v[202:205], v[80:83]
	v_mfma_f32_16x16x32_bf16 v[68:71], v[166:169], v[210:213], v[68:71]
	v_mfma_f32_16x16x32_bf16 v[64:67], v[174:177], v[210:213], v[64:67]
	v_mfma_f32_16x16x32_bf16 v[116:119], v[170:173], v[186:189], v[116:119]
	v_mfma_f32_16x16x32_bf16 v[112:115], v[178:181], v[186:189], v[112:115]
	v_mfma_f32_16x16x32_bf16 v[100:103], v[170:173], v[194:197], v[100:103]
	v_mfma_f32_16x16x32_bf16 v[96:99], v[178:181], v[194:197], v[96:99]
	v_mfma_f32_16x16x32_bf16 v[84:87], v[170:173], v[206:209], v[84:87]
	v_mfma_f32_16x16x32_bf16 v[80:83], v[178:181], v[206:209], v[80:83]
	v_mfma_f32_16x16x32_bf16 v[68:71], v[170:173], v[214:217], v[68:71]
	v_mfma_f32_16x16x32_bf16 v[64:67], v[178:181], v[214:217], v[64:67]
	s_setprio 0
	s_barrier
; #define PG8_STAGE(bufoff, gbase, voff) do { _Pragma("unroll") for (int _i = 0; _i < 2; ++_i) \
;         __builtin_amdgcn_global_load_lds((const unsigned*)((const char*)(gbase) + (voff)[_i]), (PG8_LAS unsigned*)(lds + (bufoff) + ldsw + _i * 8192), 16, 0, 0); } while (0)
; #define PG8_LDA(dst, b, h) do { _Pragma("unroll") for (int m = 0; m < 4; ++m) _Pragma("unroll") for (int k = 0; k < 2; ++k) dst[m][k] = *(const PG8_LAS bf16x8*)(lds + PG8_SA(b, h) + aoff + m * 2048 + k * 1024); } while (0)
; #define PG8_MMA(ai, bj, At, Bt) do { __builtin_amdgcn_s_setprio(1); _Pragma("unroll") for (int m = 0; m < 4; ++m) _Pragma("unroll") for (int n = 0; n < 2; ++n) _Pragma("unroll") for (int k = 0; k < 2; ++k) \
;         acc[ai][bj][m][n] = __builtin_amdgcn_mfma_f32_16x16x32_bf16(Bt[n][k], At[m][k], acc[ai][bj][m][n], 0, 0, 0); __builtin_amdgcn_s_setprio(0); } while (0)
; #define PG8_WAIT_V(n) asm volatile("s_waitcnt vmcnt(" #n ")" ::: "memory")
; #define PG8_WAIT_L(n) asm volatile("s_waitcnt lgkmcnt(" #n ")" ::: "memory")
; #define PG8_BAR __builtin_amdgcn_s_barrier()
; #define PG8_SCHED __builtin_amdgcn_sched_barrier(0)
; template <class Epi, class Sched, bool ALIGN_EPI = false, bool SP2 = false>
; __device__ __forceinline__ void gemm_phase(PG8_LAS unsigned char* lds, const Gemm g, const Sched& S, const Epi& E) {
;     ...
;         for (int t = 0; t < nt; t += 2) {
;             if constexpr (Epi::HAS_MID) { if (t == Epi::MID_T) E.mid(acc, cur, wr, wc, fr, fq); }
;             const bool last = (t == nt - 2);
;             const char* a1 = cA + (size_t)(t + 1) * kstep;
;             const char* a2 = last ? nA : cA + (size_t)(t + 2) * kstep; const char* b2 = last ? nB : cB + (size_t)(t + 2) * kstep;
;     ...
;             PG8_LDA(At, 1, 1); PG8_STAGE(PG8_SB(1, 0), b3, voffB); PG8_STAGE(PG8_SB(1, 1), b3 + hstep, voffB); PG8_STAGE(PG8_SA(1, 0), a3, voffA);
;             PG8_WAIT_V(8); PG8_WAIT_L(0); PG8_BAR; PG8_MMA(1, 0, At, B0); PG8_MMA(1, 1, At, B1); PG8_BAR; PG8_SCHED;
	s_add_i32 s22, s53, s29
	v_lshl_add_u64 v[198:199], v[198:199], 0, s[12:13]
	s_mov_b32 m0, s22
	ds_read_b128 v[182:185], v149 offset:49152
	ds_read_b128 v[186:189], v149 offset:50176
	ds_read_b128 v[190:193], v149 offset:51200
	ds_read_b128 v[194:197], v149 offset:52224
	ds_read_b128 v[202:205], v149 offset:53248
	ds_read_b128 v[206:209], v149 offset:54272
	ds_read_b128 v[210:213], v149 offset:55296
	ds_read_b128 v[214:217], v149 offset:56320
	global_load_lds_dwordx4 v[198:199], off
	v_lshl_add_u64 v[198:199], v[218:219], 0, s[12:13]
	s_add_i32 m0, s22, 0x2000
	s_add_i32 s22, s54, s29
	global_load_lds_dwordx4 v[198:199], off
	v_lshl_add_u64 v[198:199], v[220:221], 0, s[12:13]
	s_mov_b32 m0, s22
	s_nop 0
	global_load_lds_dwordx4 v[198:199], off
	v_lshl_add_u64 v[198:199], v[222:223], 0, s[12:13]
	s_add_i32 m0, s22, 0x2000
	s_nop 0
	global_load_lds_dwordx4 v[198:199], off
	v_lshl_add_u64 v[198:199], v[224:225], 0, s[12:13]
	s_mov_b32 m0, s36
	s_nop 0
	global_load_lds_dwordx4 v[198:199], off
	v_lshl_add_u64 v[198:199], v[226:227], 0, s[12:13]
	s_mov_b32 m0, s37
	s_nop 0
	global_load_lds_dwordx4 v[198:199], off
	s_waitcnt vmcnt(8)
	s_waitcnt lgkmcnt(0)
	s_barrier
	s_setprio 1
	s_waitcnt lgkmcnt(0)
	v_mfma_f32_16x16x32_bf16 v[60:63], v[150:153], v[182:185], v[60:63]
	v_mfma_f32_16x16x32_bf16 v[56:59], v[158:161], v[182:185], v[56:59]
	v_mfma_f32_16x16x32_bf16 v[44:47], v[150:153], v[190:193], v[44:47]
	v_mfma_f32_16x16x32_bf16 v[40:43], v[158:161], v[190:193], v[40:43]
	v_mfma_f32_16x16x32_bf16 v[28:31], v[150:153], v[202:205], v[28:31]
	v_mfma_f32_16x16x32_bf16 v[24:27], v[158:161], v[202:205], v[24:27]
	v_mfma_f32_16x16x32_bf16 v[12:15], v[150:153], v[210:213], v[12:15]
	v_mfma_f32_16x16x32_bf16 v[8:11], v[158:161], v[210:213], v[8:11]
	v_mfma_f32_16x16x32_bf16 v[60:63], v[154:157], v[186:189], v[60:63]
	v_mfma_f32_16x16x32_bf16 v[56:59], v[162:165], v[186:189], v[56:59]
	v_mfma_f32_16x16x32_bf16 v[44:47], v[154:157], v[194:197], v[44:47]
	v_mfma_f32_16x16x32_bf16 v[40:43], v[162:165], v[194:197], v[40:43]
	v_mfma_f32_16x16x32_bf16 v[28:31], v[154:157], v[206:209], v[28:31]
	v_mfma_f32_16x16x32_bf16 v[24:27], v[162:165], v[206:209], v[24:27]
	v_mfma_f32_16x16x32_bf16 v[12:15], v[154:157], v[214:217], v[12:15]
	v_mfma_f32_16x16x32_bf16 v[8:11], v[162:165], v[214:217], v[8:11]
	s_setprio 0
	s_setprio 1
	v_mfma_f32_16x16x32_bf16 v[52:55], v[166:169], v[182:185], v[52:55]
	v_mfma_f32_16x16x32_bf16 v[48:51], v[174:177], v[182:185], v[48:51]
	v_mfma_f32_16x16x32_bf16 v[36:39], v[166:169], v[190:193], v[36:39]
	v_mfma_f32_16x16x32_bf16 v[32:35], v[174:177], v[190:193], v[32:35]
	v_mfma_f32_16x16x32_bf16 v[20:23], v[166:169], v[202:205], v[20:23]
	v_mfma_f32_16x16x32_bf16 v[16:19], v[174:177], v[202:205], v[16:19]
	v_mfma_f32_16x16x32_bf16 v[4:7], v[166:169], v[210:213], v[4:7]
	v_mfma_f32_16x16x32_bf16 v[0:3], v[174:177], v[210:213], v[0:3]
	v_mfma_f32_16x16x32_bf16 v[52:55], v[170:173], v[186:189], v[52:55]
	v_mfma_f32_16x16x32_bf16 v[48:51], v[178:181], v[186:189], v[48:51]
	v_mfma_f32_16x16x32_bf16 v[36:39], v[170:173], v[194:197], v[36:39]
	v_mfma_f32_16x16x32_bf16 v[32:35], v[178:181], v[194:197], v[32:35]
	v_mfma_f32_16x16x32_bf16 v[20:23], v[170:173], v[206:209], v[20:23]
	v_mfma_f32_16x16x32_bf16 v[16:19], v[178:181], v[206:209], v[16:19]
	v_mfma_f32_16x16x32_bf16 v[4:7], v[170:173], v[214:217], v[4:7]
	v_mfma_f32_16x16x32_bf16 v[0:3], v[178:181], v[214:217], v[0:3]
	s_setprio 0
	s_barrier
	s_add_u32 s20, s20, 0x100
	s_addc_u32 s21, s21, 0
	s_add_u32 s50, s50, 0x100
	s_addc_u32 s51, s51, 0
	s_cmp_ge_i32 s52, s38
	s_mov_b32 s22, s52
	s_cbranch_scc1 .LBB0_1398
